# v42 plus the ph4 add+mul->fmamk peephole and v_pk_mov accumulator zeroing (all individually validated neutral edits)
# speedup vs baseline: 1.0092x; 1.0016x over previous
.LBB0_109:
	v_mov_b64_e32 v[0:1], 0x200
	s_ashr_i32 s5, s4, 31
	v_cmp_lt_i64_e32 vcc, s[6:7], v[0:1]
	s_lshl_b64 s[6:7], s[4:5], 21
	v_readlane_b32 s12, v253, 29
	v_readlane_b32 s13, v253, 30
	s_add_u32 s6, s12, s6
	s_addc_u32 s7, s13, s7
	s_and_b64 s[12:13], vcc, exec
	s_cselect_b32 s5, s7, s21
	s_cselect_b32 s50, s6, s20
	s_ashr_i32 s1, s0, 31
	s_lshl_b64 s[12:13], s[0:1], 21
	v_readlane_b32 s1, v252, 4
	s_add_u32 s58, s1, s12
	v_readlane_b32 s1, v252, 5
	s_addc_u32 s59, s1, s13
	s_and_b64 s[12:13], vcc, exec
	s_cselect_b32 s1, s59, s9
	s_cselect_b32 s12, s58, s8
	s_add_u32 s60, s20, 0x100080
	s_addc_u32 s61, s21, 0
	s_add_u32 s13, s8, 0x100
	v_mov_b32_e32 v0, 0
	s_addc_u32 s14, s9, 0
	s_mov_b32 s15, -2
	v_mov_b32_e32 v1, v0
	v_pk_mov_b32 v[2:3], v[0:1], v[0:1]
	v_pk_mov_b32 v[4:5], v[0:1], v[0:1]
	v_pk_mov_b32 v[6:7], v[0:1], v[0:1]
	v_pk_mov_b32 v[8:9], v[0:1], v[0:1]
	v_pk_mov_b32 v[10:11], v[0:1], v[0:1]
	v_pk_mov_b32 v[12:13], v[0:1], v[0:1]
	v_pk_mov_b32 v[14:15], v[0:1], v[0:1]
	v_pk_mov_b32 v[16:17], v[0:1], v[0:1]
	v_pk_mov_b32 v[18:19], v[0:1], v[0:1]
	v_pk_mov_b32 v[20:21], v[0:1], v[0:1]
	v_pk_mov_b32 v[22:23], v[0:1], v[0:1]
	v_pk_mov_b32 v[24:25], v[0:1], v[0:1]
	v_pk_mov_b32 v[26:27], v[0:1], v[0:1]
	v_pk_mov_b32 v[28:29], v[0:1], v[0:1]
	v_pk_mov_b32 v[30:31], v[0:1], v[0:1]
	v_pk_mov_b32 v[64:65], v[0:1], v[0:1]
	v_pk_mov_b32 v[66:67], v[0:1], v[0:1]
	v_pk_mov_b32 v[68:69], v[0:1], v[0:1]
	v_pk_mov_b32 v[70:71], v[0:1], v[0:1]
	v_pk_mov_b32 v[72:73], v[0:1], v[0:1]
	v_pk_mov_b32 v[74:75], v[0:1], v[0:1]
	v_pk_mov_b32 v[76:77], v[0:1], v[0:1]
	v_pk_mov_b32 v[78:79], v[0:1], v[0:1]
	v_pk_mov_b32 v[80:81], v[0:1], v[0:1]
	v_pk_mov_b32 v[82:83], v[0:1], v[0:1]
	v_pk_mov_b32 v[84:85], v[0:1], v[0:1]
	v_pk_mov_b32 v[86:87], v[0:1], v[0:1]
	v_pk_mov_b32 v[88:89], v[0:1], v[0:1]
	v_pk_mov_b32 v[90:91], v[0:1], v[0:1]
	v_pk_mov_b32 v[92:93], v[0:1], v[0:1]
	v_pk_mov_b32 v[94:95], v[0:1], v[0:1]
	v_pk_mov_b32 v[32:33], v[0:1], v[0:1]
	v_pk_mov_b32 v[34:35], v[0:1], v[0:1]
	v_pk_mov_b32 v[36:37], v[0:1], v[0:1]
	v_pk_mov_b32 v[38:39], v[0:1], v[0:1]
	v_pk_mov_b32 v[40:41], v[0:1], v[0:1]
	v_pk_mov_b32 v[42:43], v[0:1], v[0:1]
	v_pk_mov_b32 v[44:45], v[0:1], v[0:1]
	v_pk_mov_b32 v[46:47], v[0:1], v[0:1]
	v_pk_mov_b32 v[48:49], v[0:1], v[0:1]
	v_pk_mov_b32 v[50:51], v[0:1], v[0:1]
	v_pk_mov_b32 v[52:53], v[0:1], v[0:1]
	v_pk_mov_b32 v[54:55], v[0:1], v[0:1]
	v_pk_mov_b32 v[56:57], v[0:1], v[0:1]
	v_pk_mov_b32 v[58:59], v[0:1], v[0:1]
	v_pk_mov_b32 v[60:61], v[0:1], v[0:1]
	v_pk_mov_b32 v[62:63], v[0:1], v[0:1]
	v_pk_mov_b32 v[96:97], v[0:1], v[0:1]
	v_pk_mov_b32 v[98:99], v[0:1], v[0:1]
	v_pk_mov_b32 v[100:101], v[0:1], v[0:1]
	v_pk_mov_b32 v[102:103], v[0:1], v[0:1]
	v_pk_mov_b32 v[104:105], v[0:1], v[0:1]
	v_pk_mov_b32 v[106:107], v[0:1], v[0:1]
	v_pk_mov_b32 v[108:109], v[0:1], v[0:1]
	v_pk_mov_b32 v[110:111], v[0:1], v[0:1]
	v_pk_mov_b32 v[112:113], v[0:1], v[0:1]
	v_pk_mov_b32 v[114:115], v[0:1], v[0:1]
	v_pk_mov_b32 v[116:117], v[0:1], v[0:1]
	v_pk_mov_b32 v[118:119], v[0:1], v[0:1]
	v_pk_mov_b32 v[120:121], v[0:1], v[0:1]
	v_pk_mov_b32 v[122:123], v[0:1], v[0:1]
	v_pk_mov_b32 v[124:125], v[0:1], v[0:1]
	v_pk_mov_b32 v[126:127], v[0:1], v[0:1]
	.p2align 6

.LBB0_129:
	v_mov_b64_e32 v[0:1], 0x800
	s_ashr_i32 s5, s4, 31
	v_cmp_lt_i64_e32 vcc, s[6:7], v[0:1]
	s_lshl_b64 s[6:7], s[4:5], 19
	s_add_u32 s6, s28, s6
	s_addc_u32 s7, s29, s7
	s_and_b64 s[12:13], vcc, exec
	s_cselect_b32 s5, s7, s21
	s_cselect_b32 s10, s6, s20
	s_ashr_i32 s1, s0, 31
	s_lshl_b64 s[12:13], s[0:1], 19
	v_readlane_b32 s1, v252, 19
	s_add_u32 s58, s1, s12
	v_readlane_b32 s1, v252, 20
	s_addc_u32 s59, s1, s13
	s_and_b64 s[12:13], vcc, exec
	s_cselect_b32 s1, s59, s9
	s_cselect_b32 s12, s58, s8
	s_add_u32 s60, s20, 0x40080
	s_addc_u32 s61, s21, 0
	s_add_u32 s13, s8, 0x100
	v_mov_b32_e32 v0, 0
	s_addc_u32 s14, s9, 0
	s_mov_b32 s15, -2
	v_mov_b32_e32 v1, v0
	v_pk_mov_b32 v[2:3], v[0:1], v[0:1]
	v_pk_mov_b32 v[4:5], v[0:1], v[0:1]
	v_pk_mov_b32 v[6:7], v[0:1], v[0:1]
	v_pk_mov_b32 v[8:9], v[0:1], v[0:1]
	v_pk_mov_b32 v[10:11], v[0:1], v[0:1]
	v_pk_mov_b32 v[12:13], v[0:1], v[0:1]
	v_pk_mov_b32 v[14:15], v[0:1], v[0:1]
	v_pk_mov_b32 v[16:17], v[0:1], v[0:1]
	v_pk_mov_b32 v[18:19], v[0:1], v[0:1]
	v_pk_mov_b32 v[20:21], v[0:1], v[0:1]
	v_pk_mov_b32 v[22:23], v[0:1], v[0:1]
	v_pk_mov_b32 v[24:25], v[0:1], v[0:1]
	v_pk_mov_b32 v[26:27], v[0:1], v[0:1]
	v_pk_mov_b32 v[28:29], v[0:1], v[0:1]
	v_pk_mov_b32 v[30:31], v[0:1], v[0:1]
	v_pk_mov_b32 v[56:57], v[0:1], v[0:1]
	v_pk_mov_b32 v[58:59], v[0:1], v[0:1]
	v_pk_mov_b32 v[60:61], v[0:1], v[0:1]
	v_pk_mov_b32 v[62:63], v[0:1], v[0:1]
	v_pk_mov_b32 v[72:73], v[0:1], v[0:1]
	v_pk_mov_b32 v[74:75], v[0:1], v[0:1]
	v_pk_mov_b32 v[76:77], v[0:1], v[0:1]
	v_pk_mov_b32 v[78:79], v[0:1], v[0:1]
	v_pk_mov_b32 v[80:81], v[0:1], v[0:1]
	v_pk_mov_b32 v[82:83], v[0:1], v[0:1]
	v_pk_mov_b32 v[84:85], v[0:1], v[0:1]
	v_pk_mov_b32 v[86:87], v[0:1], v[0:1]
	v_pk_mov_b32 v[88:89], v[0:1], v[0:1]
	v_pk_mov_b32 v[90:91], v[0:1], v[0:1]
	v_pk_mov_b32 v[92:93], v[0:1], v[0:1]
	v_pk_mov_b32 v[94:95], v[0:1], v[0:1]
	v_pk_mov_b32 v[32:33], v[0:1], v[0:1]
	v_pk_mov_b32 v[34:35], v[0:1], v[0:1]
	v_pk_mov_b32 v[36:37], v[0:1], v[0:1]
	v_pk_mov_b32 v[38:39], v[0:1], v[0:1]
	v_pk_mov_b32 v[40:41], v[0:1], v[0:1]
	v_pk_mov_b32 v[42:43], v[0:1], v[0:1]
	v_pk_mov_b32 v[44:45], v[0:1], v[0:1]
	v_pk_mov_b32 v[46:47], v[0:1], v[0:1]
	v_pk_mov_b32 v[48:49], v[0:1], v[0:1]
	v_pk_mov_b32 v[50:51], v[0:1], v[0:1]
	v_pk_mov_b32 v[52:53], v[0:1], v[0:1]
	v_pk_mov_b32 v[54:55], v[0:1], v[0:1]
	v_pk_mov_b32 v[64:65], v[0:1], v[0:1]
	v_pk_mov_b32 v[66:67], v[0:1], v[0:1]
	v_pk_mov_b32 v[68:69], v[0:1], v[0:1]
	v_pk_mov_b32 v[70:71], v[0:1], v[0:1]
	v_pk_mov_b32 v[96:97], v[0:1], v[0:1]
	v_pk_mov_b32 v[98:99], v[0:1], v[0:1]
	v_pk_mov_b32 v[100:101], v[0:1], v[0:1]
	v_pk_mov_b32 v[102:103], v[0:1], v[0:1]
	v_pk_mov_b32 v[104:105], v[0:1], v[0:1]
	v_pk_mov_b32 v[106:107], v[0:1], v[0:1]
	v_pk_mov_b32 v[108:109], v[0:1], v[0:1]
	v_pk_mov_b32 v[110:111], v[0:1], v[0:1]
	v_pk_mov_b32 v[112:113], v[0:1], v[0:1]
	v_pk_mov_b32 v[114:115], v[0:1], v[0:1]
	v_pk_mov_b32 v[116:117], v[0:1], v[0:1]
	v_pk_mov_b32 v[118:119], v[0:1], v[0:1]
	v_pk_mov_b32 v[120:121], v[0:1], v[0:1]
	v_pk_mov_b32 v[122:123], v[0:1], v[0:1]
	v_pk_mov_b32 v[124:125], v[0:1], v[0:1]
	v_pk_mov_b32 v[126:127], v[0:1], v[0:1]
	.p2align 6

.LBB0_154:
	s_ashr_i32 s59, s58, 31
	s_lshl_b64 s[12:13], s[58:59], 19
	v_readlane_b32 s14, v253, 8
	v_mov_b64_e32 v[0:1], 0x200
	v_readlane_b32 s15, v253, 9
	s_add_u32 s64, s14, s12
	v_cmp_lt_i64_e32 vcc, s[20:21], v[0:1]
	s_addc_u32 s65, s15, s13
	s_and_b64 s[12:13], vcc, exec
	s_cselect_b32 s20, s65, s1
	s_cselect_b32 s21, s64, s0
	s_ashr_i32 s7, s6, 31
	s_lshl_b64 s[12:13], s[6:7], 19
	v_readlane_b32 s7, v253, 10
	s_add_u32 s66, s7, s12
	v_readlane_b32 s7, v253, 11
	s_addc_u32 s67, s7, s13
	s_and_b64 s[12:13], vcc, exec
	s_cselect_b32 s7, s67, s9
	s_cselect_b32 s12, s66, s8
	s_add_u32 s0, s0, 0x40080
	s_addc_u32 s1, s1, 0
	s_add_u32 s13, s8, 0x100
	v_mov_b32_e32 v0, 0
	s_addc_u32 s14, s9, 0
	s_mov_b32 s15, -2
	v_mov_b32_e32 v1, v0
	v_pk_mov_b32 v[2:3], v[0:1], v[0:1]
	v_pk_mov_b32 v[4:5], v[0:1], v[0:1]
	v_pk_mov_b32 v[6:7], v[0:1], v[0:1]
	v_pk_mov_b32 v[8:9], v[0:1], v[0:1]
	v_pk_mov_b32 v[10:11], v[0:1], v[0:1]
	v_pk_mov_b32 v[12:13], v[0:1], v[0:1]
	v_pk_mov_b32 v[14:15], v[0:1], v[0:1]
	v_pk_mov_b32 v[16:17], v[0:1], v[0:1]
	v_pk_mov_b32 v[18:19], v[0:1], v[0:1]
	v_pk_mov_b32 v[20:21], v[0:1], v[0:1]
	v_pk_mov_b32 v[22:23], v[0:1], v[0:1]
	v_pk_mov_b32 v[24:25], v[0:1], v[0:1]
	v_pk_mov_b32 v[26:27], v[0:1], v[0:1]
	v_pk_mov_b32 v[28:29], v[0:1], v[0:1]
	v_pk_mov_b32 v[30:31], v[0:1], v[0:1]
	v_pk_mov_b32 v[64:65], v[0:1], v[0:1]
	v_pk_mov_b32 v[66:67], v[0:1], v[0:1]
	v_pk_mov_b32 v[68:69], v[0:1], v[0:1]
	v_pk_mov_b32 v[70:71], v[0:1], v[0:1]
	v_pk_mov_b32 v[72:73], v[0:1], v[0:1]
	v_pk_mov_b32 v[74:75], v[0:1], v[0:1]
	v_pk_mov_b32 v[76:77], v[0:1], v[0:1]
	v_pk_mov_b32 v[78:79], v[0:1], v[0:1]
	v_pk_mov_b32 v[80:81], v[0:1], v[0:1]
	v_pk_mov_b32 v[82:83], v[0:1], v[0:1]
	v_pk_mov_b32 v[84:85], v[0:1], v[0:1]
	v_pk_mov_b32 v[86:87], v[0:1], v[0:1]
	v_pk_mov_b32 v[88:89], v[0:1], v[0:1]
	v_pk_mov_b32 v[90:91], v[0:1], v[0:1]
	v_pk_mov_b32 v[92:93], v[0:1], v[0:1]
	v_pk_mov_b32 v[94:95], v[0:1], v[0:1]
	v_pk_mov_b32 v[32:33], v[0:1], v[0:1]
	v_pk_mov_b32 v[34:35], v[0:1], v[0:1]
	v_pk_mov_b32 v[36:37], v[0:1], v[0:1]
	v_pk_mov_b32 v[38:39], v[0:1], v[0:1]
	v_pk_mov_b32 v[40:41], v[0:1], v[0:1]
	v_pk_mov_b32 v[42:43], v[0:1], v[0:1]
	v_pk_mov_b32 v[44:45], v[0:1], v[0:1]
	v_pk_mov_b32 v[46:47], v[0:1], v[0:1]
	v_pk_mov_b32 v[48:49], v[0:1], v[0:1]
	v_pk_mov_b32 v[50:51], v[0:1], v[0:1]
	v_pk_mov_b32 v[52:53], v[0:1], v[0:1]
	v_pk_mov_b32 v[54:55], v[0:1], v[0:1]
	v_pk_mov_b32 v[56:57], v[0:1], v[0:1]
	v_pk_mov_b32 v[58:59], v[0:1], v[0:1]
	v_pk_mov_b32 v[60:61], v[0:1], v[0:1]
	v_pk_mov_b32 v[62:63], v[0:1], v[0:1]
	v_pk_mov_b32 v[96:97], v[0:1], v[0:1]
	v_pk_mov_b32 v[98:99], v[0:1], v[0:1]
	v_pk_mov_b32 v[100:101], v[0:1], v[0:1]
	v_pk_mov_b32 v[102:103], v[0:1], v[0:1]
	v_pk_mov_b32 v[104:105], v[0:1], v[0:1]
	v_pk_mov_b32 v[106:107], v[0:1], v[0:1]
	v_pk_mov_b32 v[108:109], v[0:1], v[0:1]
	v_pk_mov_b32 v[110:111], v[0:1], v[0:1]
	v_pk_mov_b32 v[112:113], v[0:1], v[0:1]
	v_pk_mov_b32 v[114:115], v[0:1], v[0:1]
	v_pk_mov_b32 v[116:117], v[0:1], v[0:1]
	v_pk_mov_b32 v[118:119], v[0:1], v[0:1]
	v_pk_mov_b32 v[120:121], v[0:1], v[0:1]
	v_pk_mov_b32 v[122:123], v[0:1], v[0:1]
	v_pk_mov_b32 v[124:125], v[0:1], v[0:1]
	v_pk_mov_b32 v[126:127], v[0:1], v[0:1]
	.p2align 6

.LBB0_250:
	v_mov_b64_e32 v[0:1], 0x200
	s_ashr_i32 s5, s4, 31
	v_cmp_lt_i64_e32 vcc, s[6:7], v[0:1]
	s_lshl_b64 s[6:7], s[4:5], 17
	s_add_u32 s6, s16, s6
	s_addc_u32 s7, s17, s7
	s_and_b64 s[8:9], vcc, exec
	s_cselect_b32 s5, s7, s65
	s_cselect_b32 s50, s6, s64
	s_ashr_i32 s1, s0, 31
	s_lshl_b64 s[8:9], s[0:1], 17
	v_readlane_b32 s12, v252, 36
	v_readlane_b32 s13, v252, 37
	s_add_u32 s58, s12, s8
	s_addc_u32 s59, s13, s9
	s_and_b64 s[8:9], vcc, exec
	v_mov_b32_e32 v0, 0
	s_cselect_b32 s1, s59, s61
	s_cselect_b32 s12, s58, s60
	s_mov_b32 s8, 0
	s_mov_b64 s[66:67], -1
	s_mov_b64 s[62:63], 0
	v_mov_b32_e32 v1, v0
	v_pk_mov_b32 v[2:3], v[0:1], v[0:1]
	v_pk_mov_b32 v[4:5], v[0:1], v[0:1]
	v_pk_mov_b32 v[6:7], v[0:1], v[0:1]
	v_pk_mov_b32 v[8:9], v[0:1], v[0:1]
	v_pk_mov_b32 v[10:11], v[0:1], v[0:1]
	v_pk_mov_b32 v[12:13], v[0:1], v[0:1]
	v_pk_mov_b32 v[14:15], v[0:1], v[0:1]
	v_pk_mov_b32 v[16:17], v[0:1], v[0:1]
	v_pk_mov_b32 v[18:19], v[0:1], v[0:1]
	v_pk_mov_b32 v[20:21], v[0:1], v[0:1]
	v_pk_mov_b32 v[22:23], v[0:1], v[0:1]
	v_pk_mov_b32 v[24:25], v[0:1], v[0:1]
	v_pk_mov_b32 v[26:27], v[0:1], v[0:1]
	v_pk_mov_b32 v[28:29], v[0:1], v[0:1]
	v_pk_mov_b32 v[30:31], v[0:1], v[0:1]
	v_pk_mov_b32 v[56:57], v[0:1], v[0:1]
	v_pk_mov_b32 v[58:59], v[0:1], v[0:1]
	v_pk_mov_b32 v[60:61], v[0:1], v[0:1]
	v_pk_mov_b32 v[62:63], v[0:1], v[0:1]
	v_pk_mov_b32 v[72:73], v[0:1], v[0:1]
	v_pk_mov_b32 v[74:75], v[0:1], v[0:1]
	v_pk_mov_b32 v[76:77], v[0:1], v[0:1]
	v_pk_mov_b32 v[78:79], v[0:1], v[0:1]
	v_pk_mov_b32 v[80:81], v[0:1], v[0:1]
	v_pk_mov_b32 v[82:83], v[0:1], v[0:1]
	v_pk_mov_b32 v[84:85], v[0:1], v[0:1]
	v_pk_mov_b32 v[86:87], v[0:1], v[0:1]
	v_pk_mov_b32 v[88:89], v[0:1], v[0:1]
	v_pk_mov_b32 v[90:91], v[0:1], v[0:1]
	v_pk_mov_b32 v[92:93], v[0:1], v[0:1]
	v_pk_mov_b32 v[94:95], v[0:1], v[0:1]
	v_pk_mov_b32 v[32:33], v[0:1], v[0:1]
	v_pk_mov_b32 v[34:35], v[0:1], v[0:1]
	v_pk_mov_b32 v[36:37], v[0:1], v[0:1]
	v_pk_mov_b32 v[38:39], v[0:1], v[0:1]
	v_pk_mov_b32 v[40:41], v[0:1], v[0:1]
	v_pk_mov_b32 v[42:43], v[0:1], v[0:1]
	v_pk_mov_b32 v[44:45], v[0:1], v[0:1]
	v_pk_mov_b32 v[46:47], v[0:1], v[0:1]
	v_pk_mov_b32 v[48:49], v[0:1], v[0:1]
	v_pk_mov_b32 v[50:51], v[0:1], v[0:1]
	v_pk_mov_b32 v[52:53], v[0:1], v[0:1]
	v_pk_mov_b32 v[54:55], v[0:1], v[0:1]
	v_pk_mov_b32 v[64:65], v[0:1], v[0:1]
	v_pk_mov_b32 v[66:67], v[0:1], v[0:1]
	v_pk_mov_b32 v[68:69], v[0:1], v[0:1]
	v_pk_mov_b32 v[70:71], v[0:1], v[0:1]
	v_pk_mov_b32 v[96:97], v[0:1], v[0:1]
	v_pk_mov_b32 v[98:99], v[0:1], v[0:1]
	v_pk_mov_b32 v[100:101], v[0:1], v[0:1]
	v_pk_mov_b32 v[102:103], v[0:1], v[0:1]
	v_pk_mov_b32 v[104:105], v[0:1], v[0:1]
	v_pk_mov_b32 v[106:107], v[0:1], v[0:1]
	v_pk_mov_b32 v[108:109], v[0:1], v[0:1]
	v_pk_mov_b32 v[110:111], v[0:1], v[0:1]
	v_pk_mov_b32 v[112:113], v[0:1], v[0:1]
	v_pk_mov_b32 v[114:115], v[0:1], v[0:1]
	v_pk_mov_b32 v[116:117], v[0:1], v[0:1]
	v_pk_mov_b32 v[118:119], v[0:1], v[0:1]
	v_pk_mov_b32 v[120:121], v[0:1], v[0:1]
	v_pk_mov_b32 v[122:123], v[0:1], v[0:1]
	v_pk_mov_b32 v[124:125], v[0:1], v[0:1]
	v_pk_mov_b32 v[126:127], v[0:1], v[0:1]
	.p2align 6

.LBB0_283:
	s_ashr_i32 s7, s6, 31
	s_lshl_b64 s[12:13], s[6:7], 19
	v_mov_b64_e32 v[0:1], 0x600
	s_add_u32 s58, s28, s12
	v_cmp_lt_i64_e32 vcc, s[20:21], v[0:1]
	s_addc_u32 s59, s29, s13
	s_and_b64 s[12:13], vcc, exec
	s_cselect_b32 s7, s59, s1
	s_cselect_b32 s20, s58, s0
	s_ashr_i32 s5, s4, 31
	s_lshl_b64 s[12:13], s[4:5], 19
	v_readlane_b32 s5, v252, 51
	s_add_u32 s64, s5, s12
	v_readlane_b32 s5, v252, 52
	s_addc_u32 s65, s5, s13
	s_and_b64 s[12:13], vcc, exec
	s_cselect_b32 s5, s65, s9
	s_cselect_b32 s12, s64, s8
	s_add_u32 s0, s0, 0x40080
	s_addc_u32 s1, s1, 0
	s_add_u32 s13, s8, 0x100
	v_mov_b32_e32 v0, 0
	s_addc_u32 s14, s9, 0
	s_mov_b32 s15, -2
	v_mov_b32_e32 v1, v0
	v_pk_mov_b32 v[2:3], v[0:1], v[0:1]
	v_pk_mov_b32 v[4:5], v[0:1], v[0:1]
	v_pk_mov_b32 v[6:7], v[0:1], v[0:1]
	v_pk_mov_b32 v[8:9], v[0:1], v[0:1]
	v_pk_mov_b32 v[10:11], v[0:1], v[0:1]
	v_pk_mov_b32 v[12:13], v[0:1], v[0:1]
	v_pk_mov_b32 v[14:15], v[0:1], v[0:1]
	v_pk_mov_b32 v[16:17], v[0:1], v[0:1]
	v_pk_mov_b32 v[18:19], v[0:1], v[0:1]
	v_pk_mov_b32 v[20:21], v[0:1], v[0:1]
	v_pk_mov_b32 v[22:23], v[0:1], v[0:1]
	v_pk_mov_b32 v[24:25], v[0:1], v[0:1]
	v_pk_mov_b32 v[26:27], v[0:1], v[0:1]
	v_pk_mov_b32 v[28:29], v[0:1], v[0:1]
	v_pk_mov_b32 v[30:31], v[0:1], v[0:1]
	v_pk_mov_b32 v[52:53], v[0:1], v[0:1]
	v_pk_mov_b32 v[54:55], v[0:1], v[0:1]
	v_pk_mov_b32 v[60:61], v[0:1], v[0:1]
	v_pk_mov_b32 v[62:63], v[0:1], v[0:1]
	v_pk_mov_b32 v[72:73], v[0:1], v[0:1]
	v_pk_mov_b32 v[74:75], v[0:1], v[0:1]
	v_pk_mov_b32 v[76:77], v[0:1], v[0:1]
	v_pk_mov_b32 v[78:79], v[0:1], v[0:1]
	v_pk_mov_b32 v[80:81], v[0:1], v[0:1]
	v_pk_mov_b32 v[82:83], v[0:1], v[0:1]
	v_pk_mov_b32 v[84:85], v[0:1], v[0:1]
	v_pk_mov_b32 v[86:87], v[0:1], v[0:1]
	v_pk_mov_b32 v[88:89], v[0:1], v[0:1]
	v_pk_mov_b32 v[90:91], v[0:1], v[0:1]
	v_pk_mov_b32 v[92:93], v[0:1], v[0:1]
	v_pk_mov_b32 v[94:95], v[0:1], v[0:1]
	v_pk_mov_b32 v[32:33], v[0:1], v[0:1]
	v_pk_mov_b32 v[34:35], v[0:1], v[0:1]
	v_pk_mov_b32 v[36:37], v[0:1], v[0:1]
	v_pk_mov_b32 v[38:39], v[0:1], v[0:1]
	v_pk_mov_b32 v[40:41], v[0:1], v[0:1]
	v_pk_mov_b32 v[42:43], v[0:1], v[0:1]
	v_pk_mov_b32 v[44:45], v[0:1], v[0:1]
	v_pk_mov_b32 v[46:47], v[0:1], v[0:1]
	v_pk_mov_b32 v[48:49], v[0:1], v[0:1]
	v_pk_mov_b32 v[50:51], v[0:1], v[0:1]
	v_pk_mov_b32 v[56:57], v[0:1], v[0:1]
	v_pk_mov_b32 v[58:59], v[0:1], v[0:1]
	v_pk_mov_b32 v[64:65], v[0:1], v[0:1]
	v_pk_mov_b32 v[66:67], v[0:1], v[0:1]
	v_pk_mov_b32 v[68:69], v[0:1], v[0:1]
	v_pk_mov_b32 v[70:71], v[0:1], v[0:1]
	v_pk_mov_b32 v[96:97], v[0:1], v[0:1]
	v_pk_mov_b32 v[98:99], v[0:1], v[0:1]
	v_pk_mov_b32 v[100:101], v[0:1], v[0:1]
	v_pk_mov_b32 v[102:103], v[0:1], v[0:1]
	v_pk_mov_b32 v[104:105], v[0:1], v[0:1]
	v_pk_mov_b32 v[106:107], v[0:1], v[0:1]
	v_pk_mov_b32 v[108:109], v[0:1], v[0:1]
	v_pk_mov_b32 v[110:111], v[0:1], v[0:1]
	v_pk_mov_b32 v[112:113], v[0:1], v[0:1]
	v_pk_mov_b32 v[114:115], v[0:1], v[0:1]
	v_pk_mov_b32 v[116:117], v[0:1], v[0:1]
	v_pk_mov_b32 v[118:119], v[0:1], v[0:1]
	v_pk_mov_b32 v[120:121], v[0:1], v[0:1]
	v_pk_mov_b32 v[122:123], v[0:1], v[0:1]
	v_pk_mov_b32 v[124:125], v[0:1], v[0:1]
	v_pk_mov_b32 v[126:127], v[0:1], v[0:1]
	.p2align 6

.LBB0_316:
	s_ashr_i32 s7, s6, 31
	s_lshl_b64 s[12:13], s[6:7], 21
	v_readlane_b32 s14, v253, 29
	v_mov_b64_e32 v[0:1], 0x200
	v_readlane_b32 s15, v253, 30
	s_add_u32 s58, s14, s12
	v_cmp_lt_i64_e32 vcc, s[36:37], v[0:1]
	s_addc_u32 s59, s15, s13
	s_and_b64 s[12:13], vcc, exec
	s_cselect_b32 s7, s59, s21
	s_cselect_b32 s36, s58, s20
	s_ashr_i32 s1, s0, 31
	s_lshl_b64 s[12:13], s[0:1], 21
	s_add_u32 s64, s83, s12
	v_readlane_b32 s1, v253, 22
	s_addc_u32 s65, s1, s13
	s_and_b64 s[12:13], vcc, exec
	s_cselect_b32 s1, s65, s9
	s_cselect_b32 s12, s64, s8
	s_add_u32 s60, s20, 0x100080
	s_addc_u32 s61, s21, 0
	s_add_u32 s13, s8, 0x100
	v_mov_b32_e32 v0, 0
	s_addc_u32 s14, s9, 0
	s_mov_b32 s15, -2
	v_mov_b32_e32 v1, v0
	v_pk_mov_b32 v[2:3], v[0:1], v[0:1]
	v_pk_mov_b32 v[4:5], v[0:1], v[0:1]
	v_pk_mov_b32 v[6:7], v[0:1], v[0:1]
	v_pk_mov_b32 v[8:9], v[0:1], v[0:1]
	v_pk_mov_b32 v[10:11], v[0:1], v[0:1]
	v_pk_mov_b32 v[12:13], v[0:1], v[0:1]
	v_pk_mov_b32 v[14:15], v[0:1], v[0:1]
	v_pk_mov_b32 v[16:17], v[0:1], v[0:1]
	v_pk_mov_b32 v[18:19], v[0:1], v[0:1]
	v_pk_mov_b32 v[20:21], v[0:1], v[0:1]
	v_pk_mov_b32 v[22:23], v[0:1], v[0:1]
	v_pk_mov_b32 v[24:25], v[0:1], v[0:1]
	v_pk_mov_b32 v[26:27], v[0:1], v[0:1]
	v_pk_mov_b32 v[28:29], v[0:1], v[0:1]
	v_pk_mov_b32 v[30:31], v[0:1], v[0:1]
	v_pk_mov_b32 v[64:65], v[0:1], v[0:1]
	v_pk_mov_b32 v[66:67], v[0:1], v[0:1]
	v_pk_mov_b32 v[68:69], v[0:1], v[0:1]
	v_pk_mov_b32 v[70:71], v[0:1], v[0:1]
	v_pk_mov_b32 v[72:73], v[0:1], v[0:1]
	v_pk_mov_b32 v[74:75], v[0:1], v[0:1]
	v_pk_mov_b32 v[76:77], v[0:1], v[0:1]
	v_pk_mov_b32 v[78:79], v[0:1], v[0:1]
	v_pk_mov_b32 v[80:81], v[0:1], v[0:1]
	v_pk_mov_b32 v[82:83], v[0:1], v[0:1]
	v_pk_mov_b32 v[84:85], v[0:1], v[0:1]
	v_pk_mov_b32 v[86:87], v[0:1], v[0:1]
	v_pk_mov_b32 v[88:89], v[0:1], v[0:1]
	v_pk_mov_b32 v[90:91], v[0:1], v[0:1]
	v_pk_mov_b32 v[92:93], v[0:1], v[0:1]
	v_pk_mov_b32 v[94:95], v[0:1], v[0:1]
	v_pk_mov_b32 v[32:33], v[0:1], v[0:1]
	v_pk_mov_b32 v[34:35], v[0:1], v[0:1]
	v_pk_mov_b32 v[36:37], v[0:1], v[0:1]
	v_pk_mov_b32 v[38:39], v[0:1], v[0:1]
	v_pk_mov_b32 v[40:41], v[0:1], v[0:1]
	v_pk_mov_b32 v[42:43], v[0:1], v[0:1]
	v_pk_mov_b32 v[44:45], v[0:1], v[0:1]
	v_pk_mov_b32 v[46:47], v[0:1], v[0:1]
	v_pk_mov_b32 v[48:49], v[0:1], v[0:1]
	v_pk_mov_b32 v[50:51], v[0:1], v[0:1]
	v_pk_mov_b32 v[52:53], v[0:1], v[0:1]
	v_pk_mov_b32 v[54:55], v[0:1], v[0:1]
	v_pk_mov_b32 v[56:57], v[0:1], v[0:1]
	v_pk_mov_b32 v[58:59], v[0:1], v[0:1]
	v_pk_mov_b32 v[60:61], v[0:1], v[0:1]
	v_pk_mov_b32 v[62:63], v[0:1], v[0:1]
	v_pk_mov_b32 v[96:97], v[0:1], v[0:1]
	v_pk_mov_b32 v[98:99], v[0:1], v[0:1]
	v_pk_mov_b32 v[100:101], v[0:1], v[0:1]
	v_pk_mov_b32 v[102:103], v[0:1], v[0:1]
	v_pk_mov_b32 v[104:105], v[0:1], v[0:1]
	v_pk_mov_b32 v[106:107], v[0:1], v[0:1]
	v_pk_mov_b32 v[108:109], v[0:1], v[0:1]
	v_pk_mov_b32 v[110:111], v[0:1], v[0:1]
	v_pk_mov_b32 v[112:113], v[0:1], v[0:1]
	v_pk_mov_b32 v[114:115], v[0:1], v[0:1]
	v_pk_mov_b32 v[116:117], v[0:1], v[0:1]
	v_pk_mov_b32 v[118:119], v[0:1], v[0:1]
	v_mov_b32_e32 v128, v0
	v_mov_b32_e32 v129, v0
	v_mov_b32_e32 v130, v0
	v_mov_b32_e32 v131, v0
	v_mov_b32_e32 v132, v0
	v_mov_b32_e32 v133, v0
	v_mov_b32_e32 v134, v0
	v_mov_b32_e32 v135, v0
	.p2align 6

.LBB0_349:
	v_mov_b64_e32 v[0:1], 0x800
	s_ashr_i32 s5, s4, 31
	v_cmp_lt_i64_e32 vcc, s[6:7], v[0:1]
	s_lshl_b64 s[6:7], s[4:5], 19
	s_add_u32 s6, s28, s6
	s_addc_u32 s7, s29, s7
	s_and_b64 s[12:13], vcc, exec
	s_cselect_b32 s5, s7, s21
	s_cselect_b32 s10, s6, s20
	s_ashr_i32 s1, s0, 31
	s_lshl_b64 s[12:13], s[0:1], 19
	s_add_u32 s58, s87, s12
	v_readlane_b32 s1, v252, 63
	s_addc_u32 s59, s1, s13
	s_and_b64 s[12:13], vcc, exec
	s_cselect_b32 s1, s59, s9
	s_cselect_b32 s12, s58, s8
	s_add_u32 s60, s20, 0x40080
	s_addc_u32 s61, s21, 0
	s_add_u32 s13, s8, 0x100
	v_mov_b32_e32 v0, 0
	s_addc_u32 s14, s9, 0
	s_mov_b32 s15, -2
	v_mov_b32_e32 v1, v0
	v_pk_mov_b32 v[2:3], v[0:1], v[0:1]
	v_pk_mov_b32 v[4:5], v[0:1], v[0:1]
	v_pk_mov_b32 v[6:7], v[0:1], v[0:1]
	v_pk_mov_b32 v[8:9], v[0:1], v[0:1]
	v_pk_mov_b32 v[10:11], v[0:1], v[0:1]
	v_pk_mov_b32 v[12:13], v[0:1], v[0:1]
	v_pk_mov_b32 v[14:15], v[0:1], v[0:1]
	v_pk_mov_b32 v[16:17], v[0:1], v[0:1]
	v_pk_mov_b32 v[18:19], v[0:1], v[0:1]
	v_pk_mov_b32 v[20:21], v[0:1], v[0:1]
	v_pk_mov_b32 v[22:23], v[0:1], v[0:1]
	v_pk_mov_b32 v[24:25], v[0:1], v[0:1]
	v_pk_mov_b32 v[26:27], v[0:1], v[0:1]
	v_pk_mov_b32 v[28:29], v[0:1], v[0:1]
	v_pk_mov_b32 v[30:31], v[0:1], v[0:1]
	v_pk_mov_b32 v[56:57], v[0:1], v[0:1]
	v_pk_mov_b32 v[58:59], v[0:1], v[0:1]
	v_pk_mov_b32 v[60:61], v[0:1], v[0:1]
	v_pk_mov_b32 v[62:63], v[0:1], v[0:1]
	v_pk_mov_b32 v[72:73], v[0:1], v[0:1]
	v_pk_mov_b32 v[74:75], v[0:1], v[0:1]
	v_pk_mov_b32 v[76:77], v[0:1], v[0:1]
	v_pk_mov_b32 v[78:79], v[0:1], v[0:1]
	v_pk_mov_b32 v[80:81], v[0:1], v[0:1]
	v_pk_mov_b32 v[82:83], v[0:1], v[0:1]
	v_pk_mov_b32 v[84:85], v[0:1], v[0:1]
	v_pk_mov_b32 v[86:87], v[0:1], v[0:1]
	v_pk_mov_b32 v[88:89], v[0:1], v[0:1]
	v_pk_mov_b32 v[90:91], v[0:1], v[0:1]
	v_pk_mov_b32 v[92:93], v[0:1], v[0:1]
	v_pk_mov_b32 v[94:95], v[0:1], v[0:1]
	v_pk_mov_b32 v[32:33], v[0:1], v[0:1]
	v_pk_mov_b32 v[34:35], v[0:1], v[0:1]
	v_pk_mov_b32 v[36:37], v[0:1], v[0:1]
	v_pk_mov_b32 v[38:39], v[0:1], v[0:1]
	v_pk_mov_b32 v[40:41], v[0:1], v[0:1]
	v_pk_mov_b32 v[42:43], v[0:1], v[0:1]
	v_pk_mov_b32 v[44:45], v[0:1], v[0:1]
	v_pk_mov_b32 v[46:47], v[0:1], v[0:1]
	v_pk_mov_b32 v[48:49], v[0:1], v[0:1]
	v_pk_mov_b32 v[50:51], v[0:1], v[0:1]
	v_pk_mov_b32 v[52:53], v[0:1], v[0:1]
	v_pk_mov_b32 v[54:55], v[0:1], v[0:1]
	v_pk_mov_b32 v[64:65], v[0:1], v[0:1]
	v_pk_mov_b32 v[66:67], v[0:1], v[0:1]
	v_pk_mov_b32 v[68:69], v[0:1], v[0:1]
	v_pk_mov_b32 v[70:71], v[0:1], v[0:1]
	v_pk_mov_b32 v[96:97], v[0:1], v[0:1]
	v_pk_mov_b32 v[98:99], v[0:1], v[0:1]
	v_pk_mov_b32 v[100:101], v[0:1], v[0:1]
	v_pk_mov_b32 v[102:103], v[0:1], v[0:1]
	v_pk_mov_b32 v[104:105], v[0:1], v[0:1]
	v_pk_mov_b32 v[106:107], v[0:1], v[0:1]
	v_pk_mov_b32 v[108:109], v[0:1], v[0:1]
	v_pk_mov_b32 v[110:111], v[0:1], v[0:1]
	v_pk_mov_b32 v[112:113], v[0:1], v[0:1]
	v_pk_mov_b32 v[114:115], v[0:1], v[0:1]
	v_pk_mov_b32 v[116:117], v[0:1], v[0:1]
	v_pk_mov_b32 v[118:119], v[0:1], v[0:1]
	v_pk_mov_b32 v[120:121], v[0:1], v[0:1]
	v_pk_mov_b32 v[122:123], v[0:1], v[0:1]
	v_pk_mov_b32 v[124:125], v[0:1], v[0:1]
	v_pk_mov_b32 v[126:127], v[0:1], v[0:1]
	.p2align 6

.LBB0_376:
	s_ashr_i32 s59, s58, 31
	s_lshl_b64 s[12:13], s[58:59], 19
	v_readlane_b32 s14, v253, 29
	v_mov_b64_e32 v[0:1], 0x200
	v_readlane_b32 s15, v253, 30
	s_add_u32 s64, s14, s12
	v_cmp_lt_i64_e32 vcc, s[20:21], v[0:1]
	s_addc_u32 s65, s15, s13
	s_and_b64 s[12:13], vcc, exec
	s_cselect_b32 s20, s65, s7
	s_cselect_b32 s21, s64, s6
	s_ashr_i32 s1, s0, 31
	s_lshl_b64 s[12:13], s[0:1], 19
	s_add_u32 s66, s50, s12
	s_addc_u32 s67, s56, s13
	s_and_b64 s[12:13], vcc, exec
	s_cselect_b32 s1, s67, s9
	s_cselect_b32 s12, s66, s8
	s_add_u32 s6, s6, 0x40080
	s_addc_u32 s7, s7, 0
	s_add_u32 s13, s8, 0x100
	v_mov_b32_e32 v0, 0
	s_addc_u32 s14, s9, 0
	s_mov_b32 s15, -2
	v_mov_b32_e32 v1, v0
	v_pk_mov_b32 v[2:3], v[0:1], v[0:1]
	v_pk_mov_b32 v[4:5], v[0:1], v[0:1]
	v_pk_mov_b32 v[6:7], v[0:1], v[0:1]
	v_pk_mov_b32 v[8:9], v[0:1], v[0:1]
	v_pk_mov_b32 v[10:11], v[0:1], v[0:1]
	v_pk_mov_b32 v[12:13], v[0:1], v[0:1]
	v_pk_mov_b32 v[14:15], v[0:1], v[0:1]
	v_pk_mov_b32 v[16:17], v[0:1], v[0:1]
	v_pk_mov_b32 v[18:19], v[0:1], v[0:1]
	v_pk_mov_b32 v[20:21], v[0:1], v[0:1]
	v_pk_mov_b32 v[22:23], v[0:1], v[0:1]
	v_pk_mov_b32 v[24:25], v[0:1], v[0:1]
	v_pk_mov_b32 v[26:27], v[0:1], v[0:1]
	v_pk_mov_b32 v[28:29], v[0:1], v[0:1]
	v_pk_mov_b32 v[30:31], v[0:1], v[0:1]
	v_pk_mov_b32 v[64:65], v[0:1], v[0:1]
	v_pk_mov_b32 v[66:67], v[0:1], v[0:1]
	v_pk_mov_b32 v[68:69], v[0:1], v[0:1]
	v_pk_mov_b32 v[70:71], v[0:1], v[0:1]
	v_pk_mov_b32 v[72:73], v[0:1], v[0:1]
	v_pk_mov_b32 v[74:75], v[0:1], v[0:1]
	v_pk_mov_b32 v[76:77], v[0:1], v[0:1]
	v_pk_mov_b32 v[78:79], v[0:1], v[0:1]
	v_pk_mov_b32 v[80:81], v[0:1], v[0:1]
	v_pk_mov_b32 v[82:83], v[0:1], v[0:1]
	v_pk_mov_b32 v[84:85], v[0:1], v[0:1]
	v_pk_mov_b32 v[86:87], v[0:1], v[0:1]
	v_pk_mov_b32 v[88:89], v[0:1], v[0:1]
	v_pk_mov_b32 v[90:91], v[0:1], v[0:1]
	v_pk_mov_b32 v[92:93], v[0:1], v[0:1]
	v_pk_mov_b32 v[94:95], v[0:1], v[0:1]
	v_pk_mov_b32 v[32:33], v[0:1], v[0:1]
	v_pk_mov_b32 v[34:35], v[0:1], v[0:1]
	v_pk_mov_b32 v[36:37], v[0:1], v[0:1]
	v_pk_mov_b32 v[38:39], v[0:1], v[0:1]
	v_pk_mov_b32 v[40:41], v[0:1], v[0:1]
	v_pk_mov_b32 v[42:43], v[0:1], v[0:1]
	v_pk_mov_b32 v[44:45], v[0:1], v[0:1]
	v_pk_mov_b32 v[46:47], v[0:1], v[0:1]
	v_pk_mov_b32 v[48:49], v[0:1], v[0:1]
	v_pk_mov_b32 v[50:51], v[0:1], v[0:1]
	v_pk_mov_b32 v[52:53], v[0:1], v[0:1]
	v_pk_mov_b32 v[54:55], v[0:1], v[0:1]
	v_pk_mov_b32 v[56:57], v[0:1], v[0:1]
	v_pk_mov_b32 v[58:59], v[0:1], v[0:1]
	v_pk_mov_b32 v[60:61], v[0:1], v[0:1]
	v_pk_mov_b32 v[62:63], v[0:1], v[0:1]
	v_pk_mov_b32 v[96:97], v[0:1], v[0:1]
	v_pk_mov_b32 v[98:99], v[0:1], v[0:1]
	v_pk_mov_b32 v[100:101], v[0:1], v[0:1]
	v_pk_mov_b32 v[102:103], v[0:1], v[0:1]
	v_pk_mov_b32 v[112:113], v[0:1], v[0:1]
	v_pk_mov_b32 v[114:115], v[0:1], v[0:1]
	v_pk_mov_b32 v[116:117], v[0:1], v[0:1]
	v_pk_mov_b32 v[118:119], v[0:1], v[0:1]
	v_pk_mov_b32 v[120:121], v[0:1], v[0:1]
	v_pk_mov_b32 v[122:123], v[0:1], v[0:1]
	v_pk_mov_b32 v[124:125], v[0:1], v[0:1]
	v_pk_mov_b32 v[126:127], v[0:1], v[0:1]
	v_mov_b32_e32 v128, v0
	v_mov_b32_e32 v129, v0
	v_mov_b32_e32 v130, v0
	v_mov_b32_e32 v131, v0
	v_mov_b32_e32 v132, v0
	v_mov_b32_e32 v133, v0
	v_mov_b32_e32 v134, v0
	v_mov_b32_e32 v135, v0
	.p2align 6

.LBB0_446:
	s_or_b64 exec, exec, s[0:1]
	v_fmamk_f32 v3, v3, 0xbfb8aa3b, v67
	v_exp_f32_e32 v3, v3
	v_fmamk_f32 v2, v2, 0xbfb8aa3b, v66
	v_exp_f32_e32 v2, v2
	v_add_f32_e32 v3, 1.0, v3
	v_add_f32_e32 v2, 1.0, v2
	v_max_f32_e32 v11, v11, v11
	v_fmamk_f32 v1, v1, 0xbfb8aa3b, v65
	v_max_f32_e32 v11, 0, v11
	v_exp_f32_e32 v1, v1
	v_cmp_gt_f32_e32 vcc, s53, v11
	v_rcp_f32_e32 v2, v2
	v_add_f32_e32 v1, 1.0, v1
	v_cndmask_b32_e64 v13, 0, 32, vcc
	v_ldexp_f32 v11, v11, v13
	v_sqrt_f32_e32 v11, v11
	v_cndmask_b32_e64 v13, 0, -16, vcc
	v_ldexp_f32 v11, v11, v13
	v_rcp_f32_e32 v3, v3
	v_lshlrev_b32_e32 v12, 16, v17
	v_mul_f32_e32 v2, v2, v11
	v_mul_f32_e32 v2, v2, v12
	v_lshlrev_b32_e32 v11, 16, v16
	v_and_b32_e32 v12, 0xffff0000, v16
	v_and_b32_e32 v13, 0xffff0000, v17
	v_max_f32_e32 v10, v10, v10
	v_max_f32_e32 v10, 0, v10
	v_cmp_gt_f32_e32 vcc, s53, v10
	v_rcp_f32_e32 v1, v1
	s_nop 0
	v_cndmask_b32_e64 v14, 0, 32, vcc
	v_ldexp_f32 v10, v10, v14
	v_sqrt_f32_e32 v10, v10
	v_fmamk_f32 v0, v0, 0xbfb8aa3b, v64
	v_exp_f32_e32 v0, v0
	v_cndmask_b32_e64 v14, 0, -16, vcc
	v_ldexp_f32 v10, v10, v14
	v_mul_f32_e32 v1, v1, v10
	v_add_f32_e32 v0, 1.0, v0
	v_mul_f32_e32 v10, v1, v12
	s_nop 0
	v_rcp_f32_e32 v0, v0
	v_max_f32_e32 v1, v8, v8
	v_max_f32_e32 v1, 0, v1
	v_cmp_gt_f32_e32 vcc, s53, v1
	s_nop 1
	v_cndmask_b32_e64 v8, 0, 32, vcc
	v_ldexp_f32 v1, v1, v8
	v_sqrt_f32_e32 v1, v1
	v_cndmask_b32_e64 v8, 0, -16, vcc
	v_ldexp_f32 v1, v1, v8
	v_mul_f32_e32 v0, v0, v1
	v_mul_f32_e32 v8, v0, v11
	v_max_f32_e32 v0, v9, v9
	v_max_f32_e32 v0, 0, v0
	v_cmp_gt_f32_e32 vcc, s53, v0
	s_nop 1
	v_cndmask_b32_e64 v1, 0, 32, vcc
	v_ldexp_f32 v0, v0, v1
	v_sqrt_f32_e32 v0, v0
	v_cndmask_b32_e64 v1, 0, -16, vcc
	v_ldexp_f32 v0, v0, v1
	v_mul_f32_e32 v0, v3, v0
	v_mul_f32_e32 v3, v0, v13
	v_cvt_pk_bf16_f32 v0, v4, v5
	v_cvt_pk_bf16_f32 v1, v6, v7
	global_store_dwordx2 v[76:77], v[0:1], off offset:128
	v_cvt_pk_bf16_f32 v0, v8, v10
	v_cvt_pk_bf16_f32 v1, v2, v3
	global_store_dwordx2 v[78:79], v[0:1], off offset:128

.LBB0_452:
	s_ashr_i32 s7, s6, 31
	s_lshl_b64 s[8:9], s[6:7], 17
	v_readlane_b32 s5, v251, 22
	s_add_u32 s66, s5, s8
	v_readlane_b32 s5, v251, 23
	s_addc_u32 s67, s5, s9
	s_and_b64 s[0:1], s[0:1], exec
	v_mov_b32_e32 v0, 0
	s_cselect_b32 s5, s67, s59
	s_cselect_b32 s7, s66, s58
	s_mov_b64 s[92:93], 0
	s_mov_b64 s[0:1], -1
	s_mov_b64 s[62:63], 0
	v_mov_b32_e32 v1, v0
	v_pk_mov_b32 v[2:3], v[0:1], v[0:1]
	v_pk_mov_b32 v[4:5], v[0:1], v[0:1]
	v_pk_mov_b32 v[6:7], v[0:1], v[0:1]
	v_pk_mov_b32 v[8:9], v[0:1], v[0:1]
	v_pk_mov_b32 v[10:11], v[0:1], v[0:1]
	v_pk_mov_b32 v[12:13], v[0:1], v[0:1]
	v_pk_mov_b32 v[14:15], v[0:1], v[0:1]
	v_pk_mov_b32 v[16:17], v[0:1], v[0:1]
	v_pk_mov_b32 v[18:19], v[0:1], v[0:1]
	v_pk_mov_b32 v[20:21], v[0:1], v[0:1]
	v_pk_mov_b32 v[22:23], v[0:1], v[0:1]
	v_pk_mov_b32 v[24:25], v[0:1], v[0:1]
	v_pk_mov_b32 v[26:27], v[0:1], v[0:1]
	v_pk_mov_b32 v[28:29], v[0:1], v[0:1]
	v_pk_mov_b32 v[30:31], v[0:1], v[0:1]
	v_pk_mov_b32 v[64:65], v[0:1], v[0:1]
	v_pk_mov_b32 v[66:67], v[0:1], v[0:1]
	v_pk_mov_b32 v[68:69], v[0:1], v[0:1]
	v_pk_mov_b32 v[70:71], v[0:1], v[0:1]
	v_pk_mov_b32 v[72:73], v[0:1], v[0:1]
	v_pk_mov_b32 v[74:75], v[0:1], v[0:1]
	v_pk_mov_b32 v[80:81], v[0:1], v[0:1]
	v_pk_mov_b32 v[82:83], v[0:1], v[0:1]
	v_pk_mov_b32 v[92:93], v[0:1], v[0:1]
	v_pk_mov_b32 v[94:95], v[0:1], v[0:1]
	v_pk_mov_b32 v[96:97], v[0:1], v[0:1]
	v_pk_mov_b32 v[98:99], v[0:1], v[0:1]
	v_pk_mov_b32 v[100:101], v[0:1], v[0:1]
	v_pk_mov_b32 v[102:103], v[0:1], v[0:1]
	v_pk_mov_b32 v[104:105], v[0:1], v[0:1]
	v_pk_mov_b32 v[106:107], v[0:1], v[0:1]
	v_pk_mov_b32 v[32:33], v[0:1], v[0:1]
	v_pk_mov_b32 v[34:35], v[0:1], v[0:1]
	v_pk_mov_b32 v[36:37], v[0:1], v[0:1]
	v_pk_mov_b32 v[38:39], v[0:1], v[0:1]
	v_pk_mov_b32 v[40:41], v[0:1], v[0:1]
	v_pk_mov_b32 v[42:43], v[0:1], v[0:1]
	v_pk_mov_b32 v[44:45], v[0:1], v[0:1]
	v_pk_mov_b32 v[46:47], v[0:1], v[0:1]
	v_pk_mov_b32 v[48:49], v[0:1], v[0:1]
	v_pk_mov_b32 v[50:51], v[0:1], v[0:1]
	v_pk_mov_b32 v[52:53], v[0:1], v[0:1]
	v_pk_mov_b32 v[54:55], v[0:1], v[0:1]
	v_pk_mov_b32 v[56:57], v[0:1], v[0:1]
	v_pk_mov_b32 v[58:59], v[0:1], v[0:1]
	v_pk_mov_b32 v[60:61], v[0:1], v[0:1]
	v_pk_mov_b32 v[62:63], v[0:1], v[0:1]
	v_pk_mov_b32 v[108:109], v[0:1], v[0:1]
	v_pk_mov_b32 v[110:111], v[0:1], v[0:1]
	v_pk_mov_b32 v[112:113], v[0:1], v[0:1]
	v_pk_mov_b32 v[114:115], v[0:1], v[0:1]
	v_pk_mov_b32 v[116:117], v[0:1], v[0:1]
	v_pk_mov_b32 v[118:119], v[0:1], v[0:1]
	v_pk_mov_b32 v[120:121], v[0:1], v[0:1]
	v_pk_mov_b32 v[122:123], v[0:1], v[0:1]
	v_pk_mov_b32 v[124:125], v[0:1], v[0:1]
	v_pk_mov_b32 v[126:127], v[0:1], v[0:1]
	v_mov_b32_e32 v128, v0
	v_mov_b32_e32 v129, v0
	v_mov_b32_e32 v130, v0
	v_mov_b32_e32 v131, v0
	v_mov_b32_e32 v132, v0
	v_mov_b32_e32 v133, v0
	v_mov_b32_e32 v134, v0
	v_mov_b32_e32 v135, v0
	v_mov_b32_e32 v136, v0
	v_mov_b32_e32 v137, v0
	v_mov_b32_e32 v138, v0
	v_mov_b32_e32 v139, v0
	.p2align 6
.LBB0_453:
	s_add_u32 s12, s64, s92
	s_addc_u32 s13, s65, s93
	s_add_u32 s14, s12, 0x100
	s_addc_u32 s15, s13, 0
	s_and_b64 s[8:9], s[62:63], exec
	s_cselect_b32 s21, s61, s15
	s_cselect_b32 s20, s60, s14
	s_add_u32 s8, s58, s92
	s_addc_u32 s9, s59, s93
	s_add_u32 s14, s8, 0x100
	s_addc_u32 s15, s9, 0
	s_add_i32 s18, 0, 0x10000
	s_and_b64 s[8:9], s[62:63], exec
	s_cselect_b32 s9, s5, s15
	s_cselect_b32 s8, s7, s14
	s_add_u32 s36, s12, 0x40080
	s_addc_u32 s37, s13, 0
	s_add_i32 s24, s18, s39
	s_add_i32 m0, s40, 0xc000
	s_add_i32 s25, s40, 0xe000
	s_add_i32 s23, 0, 0x14000
	s_add_i32 s22, s24, 0x2000
	s_add_u32 vcc_lo, s8, 0x10000
	v_add_u32_e32 v140, s18, v238
	s_addc_u32 vcc_hi, s9, 0
	s_add_i32 s17, s23, s39
	ds_read_b128 v[76:79], v140
	ds_read_b128 v[84:87], v140 offset:1024
	ds_read_b128 v[88:91], v140 offset:2048
	ds_read_b128 v[140:143], v140 offset:3072
	s_add_i32 s16, s17, 0x2000
	s_add_i32 s15, 0, 0x18000
	s_add_u32 s92, s20, 0x40000
	s_addc_u32 s93, s21, 0
	s_add_i32 s14, s15, s39
	s_add_i32 s13, 0, 0x1c000
	s_add_i32 s12, s14, 0x2000
	s_add_u32 s62, s8, 0x10080
	s_addc_u32 s63, s9, 0
	s_add_i32 s19, s13, s39
	s_add_i32 s18, s19, 0x2000
	v_lshl_add_u64 v[158:159], s[36:37], 0, v[160:161]
	ds_read_b128 v[144:147], v240
	ds_read_b128 v[148:151], v240 offset:1024
	ds_read_b128 v[170:173], v240 offset:2048
	ds_read_b128 v[174:177], v240 offset:3072
	ds_read_b128 v[178:181], v240 offset:4096
	ds_read_b128 v[182:185], v240 offset:5120
	ds_read_b128 v[186:189], v240 offset:6144
	ds_read_b128 v[190:193], v240 offset:7168
	global_load_lds_dwordx4 v[158:159], off
	v_lshl_add_u64 v[158:159], s[36:37], 0, v[154:155]
	s_mov_b32 m0, s25
	s_nop 0
	global_load_lds_dwordx4 v[158:159], off
	s_waitcnt lgkmcnt(8)
	s_barrier
	s_waitcnt lgkmcnt(0)
	s_setprio 1
	s_waitcnt lgkmcnt(0)
	v_mfma_f32_16x16x32_bf16 v[136:139], v[76:79], v[144:147], v[136:139]
	v_mfma_f32_16x16x32_bf16 v[132:135], v[88:91], v[144:147], v[132:135]
	v_mfma_f32_16x16x32_bf16 v[128:131], v[76:79], v[170:173], v[128:131]
	v_mfma_f32_16x16x32_bf16 v[124:127], v[88:91], v[170:173], v[124:127]
	v_mfma_f32_16x16x32_bf16 v[120:123], v[76:79], v[178:181], v[120:123]
	v_mfma_f32_16x16x32_bf16 v[116:119], v[88:91], v[178:181], v[116:119]
	v_mfma_f32_16x16x32_bf16 v[112:115], v[76:79], v[186:189], v[112:115]
	v_mfma_f32_16x16x32_bf16 v[108:111], v[88:91], v[186:189], v[108:111]
	v_mfma_f32_16x16x32_bf16 v[136:139], v[84:87], v[148:151], v[136:139]
	v_mfma_f32_16x16x32_bf16 v[132:135], v[140:143], v[148:151], v[132:135]
	v_mfma_f32_16x16x32_bf16 v[128:131], v[84:87], v[174:177], v[128:131]
	v_mfma_f32_16x16x32_bf16 v[124:127], v[140:143], v[174:177], v[124:127]
	v_mfma_f32_16x16x32_bf16 v[120:123], v[84:87], v[182:185], v[120:123]
	v_mfma_f32_16x16x32_bf16 v[116:119], v[140:143], v[182:185], v[116:119]
	v_mfma_f32_16x16x32_bf16 v[112:115], v[84:87], v[190:193], v[112:115]
	v_mfma_f32_16x16x32_bf16 v[108:111], v[140:143], v[190:193], v[108:111]
	s_setprio 0
	s_barrier
	v_add_u32_e32 v158, s23, v238
	s_mov_b32 m0, s24
	ds_read_b128 v[194:197], v158
	ds_read_b128 v[198:201], v158 offset:1024
	ds_read_b128 v[202:205], v158 offset:2048
	ds_read_b128 v[206:209], v158 offset:3072
	v_lshl_add_u64 v[158:159], s[8:9], 0, v[152:153]
	global_load_lds_dwordx4 v[158:159], off
	v_lshl_add_u64 v[210:211], s[8:9], 0, v[156:157]
	s_mov_b32 m0, s22
	s_nop 0
	global_load_lds_dwordx4 v[210:211], off
	s_barrier
	s_waitcnt lgkmcnt(0)
	s_setprio 1
	s_waitcnt lgkmcnt(0)
	v_mfma_f32_16x16x32_bf16 v[60:63], v[194:197], v[144:147], v[60:63]
	v_mfma_f32_16x16x32_bf16 v[56:59], v[202:205], v[144:147], v[56:59]
	v_mfma_f32_16x16x32_bf16 v[52:55], v[194:197], v[170:173], v[52:55]
	v_mfma_f32_16x16x32_bf16 v[48:51], v[202:205], v[170:173], v[48:51]
	v_mfma_f32_16x16x32_bf16 v[44:47], v[194:197], v[178:181], v[44:47]
	v_mfma_f32_16x16x32_bf16 v[40:43], v[202:205], v[178:181], v[40:43]
	v_mfma_f32_16x16x32_bf16 v[36:39], v[194:197], v[186:189], v[36:39]
	v_mfma_f32_16x16x32_bf16 v[32:35], v[202:205], v[186:189], v[32:35]
	v_mfma_f32_16x16x32_bf16 v[60:63], v[198:201], v[148:151], v[60:63]
	v_mfma_f32_16x16x32_bf16 v[56:59], v[206:209], v[148:151], v[56:59]
	v_mfma_f32_16x16x32_bf16 v[52:55], v[198:201], v[174:177], v[52:55]
	v_mfma_f32_16x16x32_bf16 v[48:51], v[206:209], v[174:177], v[48:51]
	v_mfma_f32_16x16x32_bf16 v[44:47], v[198:201], v[182:185], v[44:47]
	v_mfma_f32_16x16x32_bf16 v[40:43], v[206:209], v[182:185], v[40:43]
	v_mfma_f32_16x16x32_bf16 v[36:39], v[198:201], v[190:193], v[36:39]
	v_mfma_f32_16x16x32_bf16 v[32:35], v[206:209], v[190:193], v[32:35]
	s_setprio 0
	s_mov_b32 m0, s40
	v_lshl_add_u64 v[212:213], s[20:21], 0, v[160:161]
	s_barrier
	ds_read_b128 v[144:147], v240 offset:16384
	ds_read_b128 v[148:151], v240 offset:17408
	ds_read_b128 v[170:173], v240 offset:18432
	ds_read_b128 v[174:177], v240 offset:19456
	ds_read_b128 v[178:181], v240 offset:20480
	ds_read_b128 v[182:185], v240 offset:21504
	ds_read_b128 v[186:189], v240 offset:22528
	ds_read_b128 v[190:193], v240 offset:23552
	global_load_lds_dwordx4 v[212:213], off
	v_lshl_add_u64 v[214:215], s[20:21], 0, v[154:155]
	s_mov_b32 m0, s41
	s_nop 0
	global_load_lds_dwordx4 v[214:215], off
	s_barrier
	s_waitcnt lgkmcnt(0)
	s_setprio 1
	s_waitcnt lgkmcnt(0)
	v_mfma_f32_16x16x32_bf16 v[104:107], v[76:79], v[144:147], v[104:107]
	v_mfma_f32_16x16x32_bf16 v[100:103], v[88:91], v[144:147], v[100:103]
	v_mfma_f32_16x16x32_bf16 v[96:99], v[76:79], v[170:173], v[96:99]
	v_mfma_f32_16x16x32_bf16 v[92:95], v[88:91], v[170:173], v[92:95]
	v_mfma_f32_16x16x32_bf16 v[80:83], v[76:79], v[178:181], v[80:83]
	v_mfma_f32_16x16x32_bf16 v[72:75], v[88:91], v[178:181], v[72:75]
	v_mfma_f32_16x16x32_bf16 v[68:71], v[76:79], v[186:189], v[68:71]
	v_mfma_f32_16x16x32_bf16 v[64:67], v[88:91], v[186:189], v[64:67]
	v_mfma_f32_16x16x32_bf16 v[104:107], v[84:87], v[148:151], v[104:107]
	v_mfma_f32_16x16x32_bf16 v[100:103], v[140:143], v[148:151], v[100:103]
	v_mfma_f32_16x16x32_bf16 v[96:99], v[84:87], v[174:177], v[96:99]
	v_mfma_f32_16x16x32_bf16 v[92:95], v[140:143], v[174:177], v[92:95]
	v_mfma_f32_16x16x32_bf16 v[80:83], v[84:87], v[182:185], v[80:83]
	v_mfma_f32_16x16x32_bf16 v[72:75], v[140:143], v[182:185], v[72:75]
	v_mfma_f32_16x16x32_bf16 v[68:71], v[84:87], v[190:193], v[68:71]
	v_mfma_f32_16x16x32_bf16 v[64:67], v[140:143], v[190:193], v[64:67]
	s_setprio 0
	s_barrier
	s_mov_b32 m0, s17
	v_lshl_add_u64 v[76:77], vcc, 0, v[152:153]
	global_load_lds_dwordx4 v[76:77], off
	v_lshl_add_u64 v[76:77], vcc, 0, v[156:157]
	s_mov_b32 m0, s16
	s_nop 0
	global_load_lds_dwordx4 v[76:77], off
	s_waitcnt vmcnt(6)
	s_barrier
	s_setprio 1
	v_mfma_f32_16x16x32_bf16 v[28:31], v[194:197], v[144:147], v[28:31]
	v_mfma_f32_16x16x32_bf16 v[24:27], v[202:205], v[144:147], v[24:27]
	v_mfma_f32_16x16x32_bf16 v[20:23], v[194:197], v[170:173], v[20:23]
	v_mfma_f32_16x16x32_bf16 v[16:19], v[202:205], v[170:173], v[16:19]
	v_mfma_f32_16x16x32_bf16 v[12:15], v[194:197], v[178:181], v[12:15]
	v_mfma_f32_16x16x32_bf16 v[8:11], v[202:205], v[178:181], v[8:11]
	v_mfma_f32_16x16x32_bf16 v[4:7], v[194:197], v[186:189], v[4:7]
	v_mfma_f32_16x16x32_bf16 v[0:3], v[202:205], v[186:189], v[0:3]
	v_mfma_f32_16x16x32_bf16 v[28:31], v[198:201], v[148:151], v[28:31]
	v_mfma_f32_16x16x32_bf16 v[24:27], v[206:209], v[148:151], v[24:27]
	v_mfma_f32_16x16x32_bf16 v[20:23], v[198:201], v[174:177], v[20:23]
	v_mfma_f32_16x16x32_bf16 v[16:19], v[206:209], v[174:177], v[16:19]
	v_mfma_f32_16x16x32_bf16 v[12:15], v[198:201], v[182:185], v[12:15]
	v_mfma_f32_16x16x32_bf16 v[8:11], v[206:209], v[182:185], v[8:11]
	v_mfma_f32_16x16x32_bf16 v[4:7], v[198:201], v[190:193], v[4:7]
	v_mfma_f32_16x16x32_bf16 v[0:3], v[206:209], v[190:193], v[0:3]
	s_setprio 0
	v_add_u32_e32 v140, s15, v238
	s_barrier
	ds_read_b128 v[76:79], v140
	ds_read_b128 v[84:87], v140 offset:1024
	ds_read_b128 v[88:91], v140 offset:2048
	ds_read_b128 v[140:143], v140 offset:3072
	s_mov_b32 m0, s42
	v_lshl_add_u64 v[194:195], s[92:93], 0, v[160:161]
	ds_read_b128 v[144:147], v240 offset:32768
	ds_read_b128 v[148:151], v240 offset:33792
	ds_read_b128 v[170:173], v240 offset:34816
	ds_read_b128 v[174:177], v240 offset:35840
	ds_read_b128 v[178:181], v240 offset:36864
	ds_read_b128 v[182:185], v240 offset:37888
	ds_read_b128 v[186:189], v240 offset:38912
	ds_read_b128 v[190:193], v240 offset:39936
	global_load_lds_dwordx4 v[194:195], off
	v_lshl_add_u64 v[194:195], s[92:93], 0, v[154:155]
	s_mov_b32 m0, s43
	s_nop 0
	global_load_lds_dwordx4 v[194:195], off
	s_waitcnt lgkmcnt(8)
	s_barrier
	s_waitcnt lgkmcnt(0)
	s_setprio 1
	s_waitcnt lgkmcnt(0)
	v_mfma_f32_16x16x32_bf16 v[136:139], v[76:79], v[144:147], v[136:139]
	v_mfma_f32_16x16x32_bf16 v[132:135], v[88:91], v[144:147], v[132:135]
	v_mfma_f32_16x16x32_bf16 v[128:131], v[76:79], v[170:173], v[128:131]
	v_mfma_f32_16x16x32_bf16 v[124:127], v[88:91], v[170:173], v[124:127]
	v_mfma_f32_16x16x32_bf16 v[120:123], v[76:79], v[178:181], v[120:123]
	v_mfma_f32_16x16x32_bf16 v[116:119], v[88:91], v[178:181], v[116:119]
	v_mfma_f32_16x16x32_bf16 v[112:115], v[76:79], v[186:189], v[112:115]
	v_mfma_f32_16x16x32_bf16 v[108:111], v[88:91], v[186:189], v[108:111]
	v_mfma_f32_16x16x32_bf16 v[136:139], v[84:87], v[148:151], v[136:139]
	v_mfma_f32_16x16x32_bf16 v[132:135], v[140:143], v[148:151], v[132:135]
	v_mfma_f32_16x16x32_bf16 v[128:131], v[84:87], v[174:177], v[128:131]
	v_mfma_f32_16x16x32_bf16 v[124:127], v[140:143], v[174:177], v[124:127]
	v_mfma_f32_16x16x32_bf16 v[120:123], v[84:87], v[182:185], v[120:123]
	v_mfma_f32_16x16x32_bf16 v[116:119], v[140:143], v[182:185], v[116:119]
	v_mfma_f32_16x16x32_bf16 v[112:115], v[84:87], v[190:193], v[112:115]
	v_mfma_f32_16x16x32_bf16 v[108:111], v[140:143], v[190:193], v[108:111]
	s_setprio 0
	s_barrier
	s_mov_b32 m0, s14
	v_add_u32_e32 v164, s13, v238
	v_lshl_add_u64 v[158:159], v[158:159], 0, s[74:75]
	ds_read_b128 v[194:197], v164
	ds_read_b128 v[198:201], v164 offset:1024
	ds_read_b128 v[202:205], v164 offset:2048
	ds_read_b128 v[206:209], v164 offset:3072
	global_load_lds_dwordx4 v[158:159], off
	v_lshl_add_u64 v[158:159], v[210:211], 0, s[74:75]
	s_mov_b32 m0, s12
	s_nop 0
	global_load_lds_dwordx4 v[158:159], off
	s_barrier
	s_waitcnt lgkmcnt(0)
	s_setprio 1
	s_waitcnt lgkmcnt(0)
	v_mfma_f32_16x16x32_bf16 v[60:63], v[194:197], v[144:147], v[60:63]
	v_mfma_f32_16x16x32_bf16 v[56:59], v[202:205], v[144:147], v[56:59]
	v_mfma_f32_16x16x32_bf16 v[52:55], v[194:197], v[170:173], v[52:55]
	v_mfma_f32_16x16x32_bf16 v[48:51], v[202:205], v[170:173], v[48:51]
	v_mfma_f32_16x16x32_bf16 v[44:47], v[194:197], v[178:181], v[44:47]
	v_mfma_f32_16x16x32_bf16 v[40:43], v[202:205], v[178:181], v[40:43]
	v_mfma_f32_16x16x32_bf16 v[36:39], v[194:197], v[186:189], v[36:39]
	v_mfma_f32_16x16x32_bf16 v[32:35], v[202:205], v[186:189], v[32:35]
	v_mfma_f32_16x16x32_bf16 v[60:63], v[198:201], v[148:151], v[60:63]
	v_mfma_f32_16x16x32_bf16 v[56:59], v[206:209], v[148:151], v[56:59]
	v_mfma_f32_16x16x32_bf16 v[52:55], v[198:201], v[174:177], v[52:55]
	v_mfma_f32_16x16x32_bf16 v[48:51], v[206:209], v[174:177], v[48:51]
	v_mfma_f32_16x16x32_bf16 v[44:47], v[198:201], v[182:185], v[44:47]
	v_mfma_f32_16x16x32_bf16 v[40:43], v[206:209], v[182:185], v[40:43]
	v_mfma_f32_16x16x32_bf16 v[36:39], v[198:201], v[190:193], v[36:39]
	v_mfma_f32_16x16x32_bf16 v[32:35], v[206:209], v[190:193], v[32:35]
	s_setprio 0
	s_mov_b32 m0, s38
	v_lshl_add_u64 v[158:159], v[212:213], 0, s[74:75]
	s_barrier
	ds_read_b128 v[144:147], v240 offset:49152
	ds_read_b128 v[148:151], v240 offset:50176
	ds_read_b128 v[170:173], v240 offset:51200
	ds_read_b128 v[174:177], v240 offset:52224
	ds_read_b128 v[178:181], v240 offset:53248
	ds_read_b128 v[182:185], v240 offset:54272
	ds_read_b128 v[186:189], v240 offset:55296
	ds_read_b128 v[190:193], v240 offset:56320
	global_load_lds_dwordx4 v[158:159], off
	v_lshl_add_u64 v[158:159], v[214:215], 0, s[74:75]
	s_mov_b32 m0, s81
	s_nop 0
	global_load_lds_dwordx4 v[158:159], off
	s_barrier
	s_waitcnt lgkmcnt(0)
	s_setprio 1
	s_waitcnt lgkmcnt(0)
	v_mfma_f32_16x16x32_bf16 v[104:107], v[76:79], v[144:147], v[104:107]
	v_mfma_f32_16x16x32_bf16 v[100:103], v[88:91], v[144:147], v[100:103]
	v_mfma_f32_16x16x32_bf16 v[96:99], v[76:79], v[170:173], v[96:99]
	v_mfma_f32_16x16x32_bf16 v[92:95], v[88:91], v[170:173], v[92:95]
	v_mfma_f32_16x16x32_bf16 v[80:83], v[76:79], v[178:181], v[80:83]
	v_mfma_f32_16x16x32_bf16 v[72:75], v[88:91], v[178:181], v[72:75]
	v_mfma_f32_16x16x32_bf16 v[68:71], v[76:79], v[186:189], v[68:71]
	v_mfma_f32_16x16x32_bf16 v[64:67], v[88:91], v[186:189], v[64:67]
	v_mfma_f32_16x16x32_bf16 v[104:107], v[84:87], v[148:151], v[104:107]
	v_mfma_f32_16x16x32_bf16 v[100:103], v[140:143], v[148:151], v[100:103]
	v_mfma_f32_16x16x32_bf16 v[96:99], v[84:87], v[174:177], v[96:99]
	v_mfma_f32_16x16x32_bf16 v[92:95], v[140:143], v[174:177], v[92:95]
	v_mfma_f32_16x16x32_bf16 v[80:83], v[84:87], v[182:185], v[80:83]
	v_mfma_f32_16x16x32_bf16 v[72:75], v[140:143], v[182:185], v[72:75]
	v_mfma_f32_16x16x32_bf16 v[68:71], v[84:87], v[190:193], v[68:71]
	v_mfma_f32_16x16x32_bf16 v[64:67], v[140:143], v[190:193], v[64:67]
	s_setprio 0
	s_barrier
	s_mov_b32 m0, s19
	v_lshl_add_u64 v[76:77], s[62:63], 0, v[152:153]
	global_load_lds_dwordx4 v[76:77], off
	v_lshl_add_u64 v[76:77], s[62:63], 0, v[156:157]
	s_mov_b32 m0, s18
	s_nop 0
	global_load_lds_dwordx4 v[76:77], off
	s_waitcnt vmcnt(6)
	s_barrier
	s_setprio 1
	v_mfma_f32_16x16x32_bf16 v[28:31], v[194:197], v[144:147], v[28:31]
	v_mfma_f32_16x16x32_bf16 v[24:27], v[202:205], v[144:147], v[24:27]
	v_mfma_f32_16x16x32_bf16 v[20:23], v[194:197], v[170:173], v[20:23]
	v_mfma_f32_16x16x32_bf16 v[16:19], v[202:205], v[170:173], v[16:19]
	v_mfma_f32_16x16x32_bf16 v[12:15], v[194:197], v[178:181], v[12:15]
	v_mfma_f32_16x16x32_bf16 v[8:11], v[202:205], v[178:181], v[8:11]
	v_mfma_f32_16x16x32_bf16 v[4:7], v[194:197], v[186:189], v[4:7]
	v_mfma_f32_16x16x32_bf16 v[0:3], v[202:205], v[186:189], v[0:3]
	v_mfma_f32_16x16x32_bf16 v[28:31], v[198:201], v[148:151], v[28:31]
	v_mfma_f32_16x16x32_bf16 v[24:27], v[206:209], v[148:151], v[24:27]
	v_mfma_f32_16x16x32_bf16 v[20:23], v[198:201], v[174:177], v[20:23]
	v_mfma_f32_16x16x32_bf16 v[16:19], v[206:209], v[174:177], v[16:19]
	v_mfma_f32_16x16x32_bf16 v[12:15], v[198:201], v[182:185], v[12:15]
	v_mfma_f32_16x16x32_bf16 v[8:11], v[206:209], v[182:185], v[8:11]
	v_mfma_f32_16x16x32_bf16 v[4:7], v[198:201], v[190:193], v[4:7]
	v_mfma_f32_16x16x32_bf16 v[0:3], v[206:209], v[190:193], v[0:3]
	s_setprio 0
	s_andn2_b64 vcc, exec, s[0:1]
	s_mov_b64 s[62:63], -1
	s_mov_b64 s[0:1], 0
	s_mov_b64 s[92:93], 0x100
	s_barrier
	s_cbranch_vccz .LBB0_453
	s_lshl_b32 s0, s97, 8
	s_bfe_u32 s7, s4, 0x10001
	s_add_i32 s1, s0, 0xffff8000
	s_cmpk_gt_i32 s97, 0x7f
	s_cselect_b32 s8, s1, s0
	s_lshl_b32 s0, s4, 6
	s_lshl_b32 s1, s4, 7
	s_and_b32 s0, s0, 0xffffff00
	s_and_b32 s1, s1, 0x80
	v_readlane_b32 s12, v251, 50
	s_or_b32 s5, s1, s0
	s_lshl_b32 s9, s7, 12
	v_readlane_b32 s24, v251, 62
	v_readlane_b32 s13, v251, 51
	v_readlane_b32 s14, v251, 52
	v_readlane_b32 s15, v251, 53
	v_readlane_b32 s16, v251, 54
	v_readlane_b32 s17, v251, 55
	v_readlane_b32 s18, v251, 56
	v_readlane_b32 s19, v251, 57
	v_readlane_b32 s20, v251, 58
	v_readlane_b32 s21, v251, 59
	v_readlane_b32 s22, v251, 60
	v_readlane_b32 s23, v251, 61
	v_readlane_b32 s25, v251, 63
	v_readlane_b32 s26, v252, 0
	v_readlane_b32 s27, v252, 1
	s_add_u32 s0, s24, s9
	v_or_b32_e32 v180, s5, v239
	s_addc_u32 s1, s25, 0
	v_readlane_b32 s12, v250, 62
	v_ashrrev_i32_e32 v181, 31, v180
	v_readlane_b32 s13, v250, 63
	s_add_u32 s4, s12, s9
	v_lshlrev_b64 v[84:85], 2, v[180:181]
	v_lshl_add_u64 v[172:173], s[0:1], 0, v[84:85]
	s_addc_u32 s5, s13, 0
	global_load_dwordx4 v[88:91], v[172:173], off
	v_lshl_add_u64 v[158:159], s[4:5], 0, v[84:85]
	global_load_dwordx4 v[76:79], v[158:159], off
	v_readlane_b32 s0, v251, 28
	v_readlane_b32 s1, v251, 29
	s_add_u32 s0, s0, s9
	s_addc_u32 s1, s1, 0
	v_lshl_add_u64 v[174:175], s[0:1], 0, v[84:85]
	global_load_dwordx4 v[84:87], v[174:175], off
	v_add_u32_e32 v182, s8, v162
	v_ashrrev_i32_e32 v183, 31, v182
	v_or_b32_e32 v184, 16, v182
	v_readlane_b32 s14, v251, 0
	v_lshlrev_b64 v[178:179], 11, v[182:183]
	v_ashrrev_i32_e32 v185, 31, v184
	v_lshlrev_b64 v[186:187], 10, v[182:183]
	v_readlane_b32 s62, v255, 4
	v_lshlrev_b64 v[176:177], 11, v[184:185]
	s_cmpk_lt_i32 s97, 0x80
	v_readlane_b32 s36, v249, 22
	s_mov_b32 s90, s62
	v_readlane_b32 s93, v250, 12
	v_readlane_b32 s92, v255, 6
	s_mov_b32 s14, 0x3e2aaaab
	v_readlane_b32 s15, v251, 1
	v_readlane_b32 s16, v251, 2
	v_readlane_b32 s17, v251, 3
	v_readlane_b32 s18, v251, 4
	v_readlane_b32 s19, v251, 5
	v_readlane_b32 s20, v251, 6
	v_readlane_b32 s21, v251, 7
	v_readlane_b32 s22, v251, 8
	v_readlane_b32 s23, v251, 9
	v_readlane_b32 s24, v251, 10
	v_readlane_b32 s25, v251, 11
	v_readlane_b32 s26, v251, 12
	v_readlane_b32 s27, v251, 13
	v_readlane_b32 s37, v249, 23
	v_readlane_b32 s63, v255, 5
	s_waitcnt vmcnt(0)
	v_mul_f32_e32 v88, 0xbfb8aa3b, v88
	v_mul_f32_e32 v89, 0xbfb8aa3b, v89
	v_mul_f32_e32 v90, 0xbfb8aa3b, v90
	v_mul_f32_e32 v91, 0xbfb8aa3b, v91
	v_mul_f32_e32 v76, 0xbfb8aa3b, v76
	v_mul_f32_e32 v77, 0xbfb8aa3b, v77
	v_mul_f32_e32 v78, 0xbfb8aa3b, v78
	v_mul_f32_e32 v79, 0xbfb8aa3b, v79
	v_mul_f32_e32 v84, 0xc1000000, v84
	v_mul_f32_e32 v85, 0xc1000000, v85
	v_mul_f32_e32 v86, 0xc1000000, v86
	v_mul_f32_e32 v87, 0xc1000000, v87
	v_fmamk_f32 v136, v136, 0xbfb8aa3b, v88
	v_exp_f32_e32 v136, v136
	v_fmamk_f32 v132, v132, 0xbfb8aa3b, v76
	v_exp_f32_e32 v132, v132
	v_add_f32_e32 v136, 1.0, v136
	v_add_f32_e32 v132, 1.0, v132
	s_mov_b64 vcc, s[0:1]
	v_rcp_f32_e32 v140, v136
	v_rcp_f32_e32 v136, v132
	v_mul_f32_e32 v132, v84, v140
	v_add_f32_e32 v183, v132, v132
	v_cmp_nlt_f32_e64 s[4:5], s51, v183
	s_mov_b64 s[0:1], -1
	s_cbranch_scc0 .LBB0_712
	v_lshl_add_u64 v[140:141], v[180:181], 1, s[28:29]
	v_lshl_add_u64 v[142:143], v[140:141], 0, v[178:179]
	v_lshl_add_u64 v[146:147], v[140:141], 0, v[176:177]
	global_load_dwordx2 v[144:145], v[142:143], off
	s_nop 0
	global_load_dwordx2 v[142:143], v[146:147], off
	s_and_saveexec_b64 s[0:1], s[4:5]
	s_xor_b64 s[0:1], exec, s[0:1]
	v_mul_f32_e32 v146, 0x3fb8aa3b, v183
	v_exp_f32_e32 v146, v146
	s_nop 0
	v_sub_f32_e32 v147, 1.0, v146
	s_andn2_saveexec_b64 s[0:1], s[0:1]
	v_fma_f32 v146, v183, s14, 0.5
	v_fma_f32 v146, v183, v146, 1.0
	v_mul_f32_e64 v147, v146, -v183
	s_or_b64 exec, exec, s[0:1]
	v_fmamk_f32 v146, v137, 0xbfb8aa3b, v89
	v_exp_f32_e32 v146, v146
	s_nop 0
	v_add_f32_e32 v146, 1.0, v146
	v_rcp_f32_e32 v146, v146
	s_nop 0
	v_mul_f32_e32 v146, v85, v146
	v_add_f32_e32 v148, v146, v146
	v_mul_f32_e32 v247, 0x3fb8aa3b, v148
	v_exp_f32_e32 v247, v247
	v_fma_f32 v149, v148, s14, 0.5
	v_fma_f32 v149, v148, v149, 1.0
	v_cmp_nlt_f32_e32 vcc, s51, v148
	v_mul_f32_e64 v149, v149, -v148
	v_sub_f32_e32 v247, 1.0, v247
	v_cndmask_b32_e32 v149, v149, v247, vcc
	v_fmamk_f32 v148, v138, 0xbfb8aa3b, v90
	v_exp_f32_e32 v148, v148
	s_nop 0
	v_add_f32_e32 v148, 1.0, v148
	v_rcp_f32_e32 v148, v148
	s_nop 0
	v_mul_f32_e32 v148, v86, v148
	v_add_f32_e32 v150, v148, v148
	v_mul_f32_e32 v247, 0x3fb8aa3b, v150
	v_exp_f32_e32 v247, v247
	v_fma_f32 v168, v150, s14, 0.5
	v_fma_f32 v168, v150, v168, 1.0
	v_cmp_nlt_f32_e32 vcc, s51, v150
	v_mul_f32_e64 v168, v168, -v150
	v_sub_f32_e32 v247, 1.0, v247
	v_cndmask_b32_e32 v168, v168, v247, vcc
	v_fmamk_f32 v150, v139, 0xbfb8aa3b, v91
	v_exp_f32_e32 v150, v150
	s_nop 0
	v_add_f32_e32 v150, 1.0, v150
	v_rcp_f32_e32 v150, v150
	s_nop 0
	v_mul_f32_e32 v150, v87, v150
	v_add_f32_e32 v170, v150, v150
	v_mul_f32_e32 v247, 0x3fb8aa3b, v170
	v_exp_f32_e32 v247, v247
	v_fma_f32 v151, v170, s14, 0.5
	v_fma_f32 v151, v170, v151, 1.0
	v_cmp_nlt_f32_e32 vcc, s51, v170
	v_mul_f32_e64 v151, v151, -v170
	v_sub_f32_e32 v247, 1.0, v247
	v_cndmask_b32_e32 v151, v151, v247, vcc
	v_fmamk_f32 v164, v134, 0xbfb8aa3b, v78
	v_exp_f32_e32 v164, v164
	v_max_f32_e32 v149, 0, v149
	v_add_f32_e32 v164, 1.0, v164
	v_max_f32_e32 v147, 0, v147
	v_readlane_b32 s8, v253, 8
	v_readlane_b32 s9, v253, 9
	v_max_f32_e32 v166, 0, v168
	v_rcp_f32_e32 v164, v164
	s_waitcnt vmcnt(0)
	v_lshlrev_b32_e32 v165, 16, v145
	v_sqrt_f32_e32 v166, v166
	v_cvt_pk_bf16_f32 v146, v132, v146
	v_mul_f32_e32 v164, v164, v166
	v_mul_f32_e32 v164, v164, v165
	v_fmamk_f32 v165, v135, 0xbfb8aa3b, v79
	v_exp_f32_e32 v165, v165
	s_nop 0
	v_add_f32_e32 v165, 1.0, v165
	v_rcp_f32_e32 v165, v165
	v_fmamk_f32 v166, v133, 0xbfb8aa3b, v77
	v_exp_f32_e32 v166, v166
	s_nop 0
	v_add_f32_e32 v166, 1.0, v166
	s_lshl_b32 s0, s7, 26
	s_add_u32 s58, s8, s0
	s_addc_u32 s59, s9, 0
	v_rcp_f32_e32 v166, v166
	v_and_b32_e32 v167, 0xffff0000, v144
	v_sqrt_f32_e32 v149, v149
	v_lshlrev_b32_e32 v144, 16, v144
	v_mul_f32_e32 v149, v166, v149
	v_sqrt_f32_e32 v147, v147
	s_add_u32 s0, s68, s0
	s_addc_u32 s1, s69, 0
	v_mul_f32_e32 v147, v136, v147
	v_mul_f32_e32 v166, v147, v144
	v_and_b32_e32 v144, 0xffff0000, v145
	v_max_f32_e32 v145, 0, v151
	v_mul_f32_e32 v149, v149, v167
	v_sqrt_f32_e32 v145, v145
	s_nop 0
	v_mul_f32_e32 v145, v165, v145
	v_mul_f32_e32 v151, v145, v144
	v_lshl_add_u64 v[144:145], v[186:187], 0, v[180:181]
	v_lshlrev_b64 v[144:145], 1, v[144:145]
	v_lshl_add_u64 v[190:191], s[58:59], 0, v[144:145]
	v_lshl_add_u64 v[194:195], s[0:1], 0, v[144:145]
	v_fmamk_f32 v144, v128, 0xbfb8aa3b, v88
	v_exp_f32_e32 v144, v144
	v_cvt_pk_bf16_f32 v147, v148, v150
	global_store_dwordx2 v[190:191], v[146:147], off
	v_cvt_pk_bf16_f32 v146, v166, v149
	v_add_f32_e32 v144, 1.0, v144
	v_cvt_pk_bf16_f32 v147, v164, v151
	global_store_dwordx2 v[194:195], v[146:147], off
	v_rcp_f32_e32 v144, v144
	s_nop 0
	v_mul_f32_e32 v144, v84, v144
	v_add_f32_e32 v145, v144, v144
	v_mul_f32_e32 v247, 0x3fb8aa3b, v145
	v_exp_f32_e32 v247, v247
	v_fma_f32 v146, v145, s14, 0.5
	v_fma_f32 v146, v145, v146, 1.0
	v_cmp_nlt_f32_e32 vcc, s51, v145
	v_mul_f32_e64 v146, v146, -v145
	v_sub_f32_e32 v247, 1.0, v247
	v_cndmask_b32_e32 v146, v146, v247, vcc
	v_fmamk_f32 v145, v129, 0xbfb8aa3b, v89
	v_exp_f32_e32 v145, v145
	s_nop 0
	v_add_f32_e32 v145, 1.0, v145
	v_rcp_f32_e32 v145, v145
	s_nop 0
	v_mul_f32_e32 v145, v85, v145
	v_add_f32_e32 v147, v145, v145
	v_mul_f32_e32 v247, 0x3fb8aa3b, v147
	v_exp_f32_e32 v247, v247
	v_fma_f32 v150, v147, s14, 0.5
	v_fma_f32 v150, v147, v150, 1.0
	v_cmp_nlt_f32_e32 vcc, s51, v147
	v_mul_f32_e64 v150, v150, -v147
	v_sub_f32_e32 v247, 1.0, v247
	v_cndmask_b32_e32 v150, v150, v247, vcc
	v_fmamk_f32 v147, v130, 0xbfb8aa3b, v90
	v_exp_f32_e32 v147, v147
	s_nop 0
	v_add_f32_e32 v147, 1.0, v147
	v_rcp_f32_e32 v147, v147
	s_nop 0
	v_mul_f32_e32 v147, v86, v147
	v_add_f32_e32 v148, v147, v147
	v_mul_f32_e32 v247, 0x3fb8aa3b, v148
	v_exp_f32_e32 v247, v247
	v_fma_f32 v151, v148, s14, 0.5
	v_fma_f32 v151, v148, v151, 1.0
	v_cmp_nlt_f32_e32 vcc, s51, v148
	v_mul_f32_e64 v151, v151, -v148
	v_sub_f32_e32 v247, 1.0, v247
	v_cndmask_b32_e32 v151, v151, v247, vcc
	v_fmamk_f32 v148, v131, 0xbfb8aa3b, v91
	v_exp_f32_e32 v148, v148
	s_nop 0
	v_add_f32_e32 v148, 1.0, v148
	v_rcp_f32_e32 v148, v148
	s_nop 0
	v_mul_f32_e32 v148, v87, v148
	v_add_f32_e32 v168, v148, v148
	v_mul_f32_e32 v247, 0x3fb8aa3b, v168
	v_exp_f32_e32 v247, v247
	v_fma_f32 v149, v168, s14, 0.5
	v_fma_f32 v149, v168, v149, 1.0
	v_cmp_nlt_f32_e32 vcc, s51, v168
	v_mul_f32_e64 v149, v149, -v168
	v_sub_f32_e32 v247, 1.0, v247
	v_cndmask_b32_e32 v149, v149, v247, vcc
	v_fmamk_f32 v164, v126, 0xbfb8aa3b, v78
	v_exp_f32_e32 v164, v164
	v_max_f32_e32 v151, 0, v151
	v_add_f32_e32 v164, 1.0, v164
	v_max_f32_e32 v150, 0, v150
	v_max_f32_e32 v146, 0, v146
	v_rcp_f32_e32 v164, v164
	v_lshlrev_b32_e32 v165, 16, v143
	v_sqrt_f32_e32 v151, v151
	v_cvt_pk_bf16_f32 v144, v144, v145
	v_cvt_pk_bf16_f32 v145, v147, v148
	v_mul_f32_e32 v151, v164, v151
	v_mul_f32_e32 v164, v151, v165
	v_fmamk_f32 v151, v127, 0xbfb8aa3b, v79
	v_exp_f32_e32 v151, v151
	s_nop 0
	v_add_f32_e32 v151, 1.0, v151
	v_rcp_f32_e32 v165, v151
	v_fmamk_f32 v151, v125, 0xbfb8aa3b, v77
	v_exp_f32_e32 v151, v151
	s_nop 0
	v_add_f32_e32 v151, 1.0, v151
	v_rcp_f32_e32 v151, v151
	v_and_b32_e32 v166, 0xffff0000, v142
	v_sqrt_f32_e32 v150, v150
	v_lshlrev_b32_e32 v142, 16, v142
	v_mul_f32_e32 v150, v151, v150
	v_mul_f32_e32 v166, v150, v166
	v_fmamk_f32 v150, v124, 0xbfb8aa3b, v76
	v_exp_f32_e32 v150, v150
	s_nop 0
	v_add_f32_e32 v150, 1.0, v150
	v_rcp_f32_e32 v150, v150
	v_sqrt_f32_e32 v146, v146
	s_nop 0
	v_mul_f32_e32 v146, v150, v146
	v_mul_f32_e32 v146, v146, v142
	v_and_b32_e32 v142, 0xffff0000, v143
	v_max_f32_e32 v143, 0, v149
	v_lshlrev_b64 v[150:151], 10, v[184:185]
	v_sqrt_f32_e32 v143, v143
	s_nop 0
	v_mul_f32_e32 v143, v165, v143
	v_mul_f32_e32 v149, v143, v142
	v_lshl_add_u64 v[142:143], v[150:151], 0, v[180:181]
	v_lshlrev_b64 v[142:143], 1, v[142:143]
	v_lshl_add_u64 v[188:189], s[58:59], 0, v[142:143]
	global_store_dwordx2 v[188:189], v[144:145], off
	v_cvt_pk_bf16_f32 v144, v146, v166
	v_or_b32_e32 v146, 32, v182
	v_ashrrev_i32_e32 v147, 31, v146
	v_lshl_add_u64 v[192:193], s[0:1], 0, v[142:143]
	v_lshlrev_b64 v[196:197], 11, v[146:147]
	v_cvt_pk_bf16_f32 v145, v164, v149
	global_store_dwordx2 v[192:193], v[144:145], off
	v_lshl_add_u64 v[142:143], v[140:141], 0, v[196:197]
	global_load_dwordx2 v[148:149], v[142:143], off
	v_or_b32_e32 v142, 48, v182
	v_ashrrev_i32_e32 v143, 31, v142
	v_lshlrev_b64 v[198:199], 11, v[142:143]
	v_lshl_add_u64 v[144:145], v[140:141], 0, v[198:199]
	global_load_dwordx2 v[144:145], v[144:145], off
	v_fmamk_f32 v150, v120, 0xbfb8aa3b, v88
	v_exp_f32_e32 v150, v150
	s_nop 0
	v_add_f32_e32 v150, 1.0, v150
	v_rcp_f32_e32 v150, v150
	s_nop 0
	v_mul_f32_e32 v150, v84, v150
	v_add_f32_e32 v151, v150, v150
	v_mul_f32_e32 v247, 0x3fb8aa3b, v151
	v_exp_f32_e32 v247, v247
	v_fma_f32 v168, v151, s14, 0.5
	v_fma_f32 v168, v151, v168, 1.0
	v_cmp_nlt_f32_e32 vcc, s51, v151
	v_mul_f32_e64 v168, v168, -v151
	v_sub_f32_e32 v247, 1.0, v247
	v_cndmask_b32_e32 v168, v168, v247, vcc
	v_fmamk_f32 v151, v121, 0xbfb8aa3b, v89
	v_exp_f32_e32 v151, v151
	s_nop 0
	v_add_f32_e32 v151, 1.0, v151
	v_rcp_f32_e32 v151, v151
	s_nop 0
	v_mul_f32_e32 v151, v85, v151
	v_add_f32_e32 v170, v151, v151
	v_mul_f32_e32 v247, 0x3fb8aa3b, v170
	v_exp_f32_e32 v247, v247
	v_fma_f32 v201, v170, s14, 0.5
	v_fma_f32 v201, v170, v201, 1.0
	v_cmp_nlt_f32_e32 vcc, s51, v170
	v_mul_f32_e64 v201, v201, -v170
	v_sub_f32_e32 v247, 1.0, v247
	v_cndmask_b32_e32 v201, v201, v247, vcc
	v_fmamk_f32 v164, v122, 0xbfb8aa3b, v90
	v_exp_f32_e32 v164, v164
	s_nop 0
	v_add_f32_e32 v164, 1.0, v164
	v_rcp_f32_e32 v164, v164
	s_nop 0
	v_mul_f32_e32 v170, v86, v164
	v_add_f32_e32 v171, v170, v170
	v_mul_f32_e32 v247, 0x3fb8aa3b, v171
	v_exp_f32_e32 v247, v247
	v_fma_f32 v202, v171, s14, 0.5
	v_fma_f32 v202, v171, v202, 1.0
	v_cmp_nlt_f32_e32 vcc, s51, v171
	v_mul_f32_e64 v202, v202, -v171
	v_sub_f32_e32 v247, 1.0, v247
	v_cndmask_b32_e32 v202, v202, v247, vcc
	v_fmamk_f32 v164, v123, 0xbfb8aa3b, v91
	v_exp_f32_e32 v164, v164
	s_nop 0
	v_add_f32_e32 v164, 1.0, v164
	v_rcp_f32_e32 v164, v164
	s_nop 0
	v_mul_f32_e32 v171, v87, v164
	v_add_f32_e32 v203, v171, v171
	v_mul_f32_e32 v247, 0x3fb8aa3b, v203
	v_exp_f32_e32 v247, v247
	v_fma_f32 v200, v203, s14, 0.5
	v_fma_f32 v200, v203, v200, 1.0
	v_cmp_nlt_f32_e32 vcc, s51, v203
	v_mul_f32_e64 v200, v200, -v203
	v_sub_f32_e32 v247, 1.0, v247
	v_cndmask_b32_e32 v200, v200, v247, vcc
	v_fmamk_f32 v164, v118, 0xbfb8aa3b, v78
	v_exp_f32_e32 v164, v164
	v_max_f32_e32 v201, 0, v201
	v_add_f32_e32 v164, 1.0, v164
	v_max_f32_e32 v168, 0, v168
	v_lshlrev_b64 v[146:147], 10, v[146:147]
	v_lshl_add_u64 v[146:147], v[146:147], 0, v[180:181]
	v_max_f32_e32 v166, 0, v202
	v_rcp_f32_e32 v164, v164
	s_waitcnt vmcnt(0)
	v_lshlrev_b32_e32 v165, 16, v149
	v_sqrt_f32_e32 v166, v166
	v_lshlrev_b64 v[146:147], 1, v[146:147]
	v_lshl_add_u64 v[206:207], s[0:1], 0, v[146:147]
	v_mul_f32_e32 v164, v164, v166
	v_mul_f32_e32 v164, v164, v165
	v_fmamk_f32 v165, v119, 0xbfb8aa3b, v79
	v_exp_f32_e32 v165, v165
	s_nop 0
	v_add_f32_e32 v165, 1.0, v165
	v_rcp_f32_e32 v165, v165
	v_fmamk_f32 v166, v117, 0xbfb8aa3b, v77
	v_exp_f32_e32 v166, v166
	s_nop 0
	v_add_f32_e32 v166, 1.0, v166
	v_rcp_f32_e32 v166, v166
	v_and_b32_e32 v167, 0xffff0000, v148
	v_sqrt_f32_e32 v201, v201
	v_lshlrev_b32_e32 v148, 16, v148
	v_mul_f32_e32 v166, v166, v201
	v_mul_f32_e32 v166, v166, v167
	v_fmamk_f32 v167, v116, 0xbfb8aa3b, v76
	v_exp_f32_e32 v167, v167
	s_nop 0
	v_add_f32_e32 v167, 1.0, v167
	v_rcp_f32_e32 v167, v167
	v_lshl_add_u64 v[202:203], s[58:59], 0, v[146:147]
	v_sqrt_f32_e32 v168, v168
	v_fmamk_f32 v146, v112, 0xbfb8aa3b, v88
	v_mul_f32_e32 v167, v167, v168
	v_mul_f32_e32 v167, v167, v148
	v_and_b32_e32 v148, 0xffff0000, v149
	v_max_f32_e32 v149, 0, v200
	v_exp_f32_e32 v146, v146
	v_sqrt_f32_e32 v149, v149
	v_add_f32_e32 v146, 1.0, v146
	v_mul_f32_e32 v149, v165, v149
	v_mul_f32_e32 v165, v149, v148
	v_cvt_pk_bf16_f32 v148, v150, v151
	v_cvt_pk_bf16_f32 v149, v170, v171
	global_store_dwordx2 v[202:203], v[148:149], off
	v_cvt_pk_bf16_f32 v148, v167, v166
	v_cvt_pk_bf16_f32 v149, v164, v165
	global_store_dwordx2 v[206:207], v[148:149], off
	v_rcp_f32_e32 v146, v146
	s_nop 0
	v_mul_f32_e32 v146, v84, v146
	v_add_f32_e32 v147, v146, v146
	v_mul_f32_e32 v247, 0x3fb8aa3b, v147
	v_exp_f32_e32 v247, v247
	v_fma_f32 v148, v147, s14, 0.5
	v_fma_f32 v148, v147, v148, 1.0
	v_cmp_nlt_f32_e32 vcc, s51, v147
	v_mul_f32_e64 v148, v148, -v147
	v_sub_f32_e32 v247, 1.0, v247
	v_cndmask_b32_e32 v148, v148, v247, vcc
	v_fmamk_f32 v147, v113, 0xbfb8aa3b, v89
	v_exp_f32_e32 v147, v147
	s_nop 0
	v_add_f32_e32 v147, 1.0, v147
	v_rcp_f32_e32 v147, v147
	s_nop 0
	v_mul_f32_e32 v147, v85, v147
	v_add_f32_e32 v149, v147, v147
	v_mul_f32_e32 v247, 0x3fb8aa3b, v149
	v_exp_f32_e32 v247, v247
	v_fma_f32 v168, v149, s14, 0.5
	v_fma_f32 v168, v149, v168, 1.0
	v_cmp_nlt_f32_e32 vcc, s51, v149
	v_mul_f32_e64 v168, v168, -v149
	v_sub_f32_e32 v247, 1.0, v247
	v_cndmask_b32_e32 v168, v168, v247, vcc
	v_fmamk_f32 v149, v114, 0xbfb8aa3b, v90
	v_exp_f32_e32 v149, v149
	s_nop 0
	v_add_f32_e32 v149, 1.0, v149
	v_rcp_f32_e32 v149, v149
	s_nop 0
	v_mul_f32_e32 v149, v86, v149
	v_add_f32_e32 v150, v149, v149
	v_mul_f32_e32 v247, 0x3fb8aa3b, v150
	v_exp_f32_e32 v247, v247
	v_fma_f32 v170, v150, s14, 0.5
	v_fma_f32 v170, v150, v170, 1.0
	v_cmp_nlt_f32_e32 vcc, s51, v150
	v_mul_f32_e64 v170, v170, -v150
	v_sub_f32_e32 v247, 1.0, v247
	v_cndmask_b32_e32 v170, v170, v247, vcc
	v_fmamk_f32 v150, v115, 0xbfb8aa3b, v91
	v_exp_f32_e32 v150, v150
	s_nop 0
	v_add_f32_e32 v150, 1.0, v150
	v_rcp_f32_e32 v150, v150
	s_nop 0
	v_mul_f32_e32 v150, v87, v150
	v_add_f32_e32 v171, v150, v150
	v_mul_f32_e32 v247, 0x3fb8aa3b, v171
	v_exp_f32_e32 v247, v247
	v_fma_f32 v151, v171, s14, 0.5
	v_fma_f32 v151, v171, v151, 1.0
	v_cmp_nlt_f32_e32 vcc, s51, v171
	v_mul_f32_e64 v151, v151, -v171
	v_sub_f32_e32 v247, 1.0, v247
	v_cndmask_b32_e32 v151, v151, v247, vcc
	v_fmamk_f32 v164, v110, 0xbfb8aa3b, v78
	v_exp_f32_e32 v164, v164
	v_max_f32_e32 v168, 0, v168
	v_add_f32_e32 v164, 1.0, v164
	v_max_f32_e32 v148, 0, v148
	v_lshlrev_b64 v[142:143], 10, v[142:143]
	v_lshl_add_u64 v[142:143], v[142:143], 0, v[180:181]
	v_max_f32_e32 v166, 0, v170
	v_rcp_f32_e32 v164, v164
	v_lshlrev_b32_e32 v165, 16, v145
	v_sqrt_f32_e32 v166, v166
	v_lshlrev_b64 v[142:143], 1, v[142:143]
	v_lshl_add_u64 v[204:205], s[0:1], 0, v[142:143]
	v_mul_f32_e32 v164, v164, v166
	v_mul_f32_e32 v164, v164, v165
	v_fmamk_f32 v165, v111, 0xbfb8aa3b, v79
	v_exp_f32_e32 v165, v165
	s_nop 0
	v_add_f32_e32 v165, 1.0, v165
	v_rcp_f32_e32 v165, v165
	v_fmamk_f32 v166, v109, 0xbfb8aa3b, v77
	v_exp_f32_e32 v166, v166
	s_nop 0
	v_add_f32_e32 v166, 1.0, v166
	v_rcp_f32_e32 v166, v166
	v_and_b32_e32 v167, 0xffff0000, v144
	v_sqrt_f32_e32 v168, v168
	v_lshlrev_b32_e32 v144, 16, v144
	v_mul_f32_e32 v166, v166, v168
	v_mul_f32_e32 v166, v166, v167
	v_fmamk_f32 v167, v108, 0xbfb8aa3b, v76
	v_exp_f32_e32 v167, v167
	s_nop 0
	v_add_f32_e32 v167, 1.0, v167
	v_rcp_f32_e32 v167, v167
	v_lshl_add_u64 v[200:201], s[58:59], 0, v[142:143]
	v_sqrt_f32_e32 v148, v148
	s_nop 0
	v_mul_f32_e32 v148, v167, v148
	v_mul_f32_e32 v148, v148, v144
	v_and_b32_e32 v144, 0xffff0000, v145
	v_max_f32_e32 v145, 0, v151
	v_sqrt_f32_e32 v145, v145
	s_nop 0
	v_mul_f32_e32 v145, v165, v145
	v_mul_f32_e32 v151, v145, v144
	v_cvt_pk_bf16_f32 v144, v146, v147
	v_add_u32_e32 v146, 0x80, v182
	v_ashrrev_i32_e32 v147, 31, v146
	v_cvt_pk_bf16_f32 v145, v149, v150
	v_lshlrev_b64 v[208:209], 11, v[146:147]
	global_store_dwordx2 v[200:201], v[144:145], off
	v_cvt_pk_bf16_f32 v144, v148, v166
	v_cvt_pk_bf16_f32 v145, v164, v151
	global_store_dwordx2 v[204:205], v[144:145], off
	v_lshl_add_u64 v[142:143], v[140:141], 0, v[208:209]
	global_load_dwordx2 v[148:149], v[142:143], off
	v_add_u32_e32 v142, 0x90, v182
	v_ashrrev_i32_e32 v143, 31, v142
	v_lshlrev_b64 v[210:211], 11, v[142:143]
	v_lshl_add_u64 v[144:145], v[140:141], 0, v[210:211]
	global_load_dwordx2 v[144:145], v[144:145], off
	v_fmamk_f32 v150, v104, 0xbfb8aa3b, v88
	v_exp_f32_e32 v150, v150
	s_nop 0
	v_add_f32_e32 v150, 1.0, v150
	v_rcp_f32_e32 v150, v150
	s_nop 0
	v_mul_f32_e32 v150, v84, v150
	v_add_f32_e32 v151, v150, v150
	v_mul_f32_e32 v247, 0x3fb8aa3b, v151
	v_exp_f32_e32 v247, v247
	v_fma_f32 v168, v151, s14, 0.5
	v_fma_f32 v168, v151, v168, 1.0
	v_cmp_nlt_f32_e32 vcc, s51, v151
	v_mul_f32_e64 v168, v168, -v151
	v_sub_f32_e32 v247, 1.0, v247
	v_cndmask_b32_e32 v168, v168, v247, vcc
	v_fmamk_f32 v151, v105, 0xbfb8aa3b, v89
	v_exp_f32_e32 v151, v151
	s_nop 0
	v_add_f32_e32 v151, 1.0, v151
	v_rcp_f32_e32 v151, v151
	s_nop 0
	v_mul_f32_e32 v151, v85, v151
	v_add_f32_e32 v170, v151, v151
	v_mul_f32_e32 v247, 0x3fb8aa3b, v170
	v_exp_f32_e32 v247, v247
	v_fma_f32 v213, v170, s14, 0.5
	v_fma_f32 v213, v170, v213, 1.0
	v_cmp_nlt_f32_e32 vcc, s51, v170
	v_mul_f32_e64 v213, v213, -v170
	v_sub_f32_e32 v247, 1.0, v247
	v_cndmask_b32_e32 v213, v213, v247, vcc
	v_fmamk_f32 v164, v106, 0xbfb8aa3b, v90
	v_exp_f32_e32 v164, v164
	s_nop 0
	v_add_f32_e32 v164, 1.0, v164
	v_rcp_f32_e32 v164, v164
	s_nop 0
	v_mul_f32_e32 v170, v86, v164
	v_add_f32_e32 v171, v170, v170
	v_mul_f32_e32 v247, 0x3fb8aa3b, v171
	v_exp_f32_e32 v247, v247
	v_fma_f32 v214, v171, s14, 0.5
	v_fma_f32 v214, v171, v214, 1.0
	v_cmp_nlt_f32_e32 vcc, s51, v171
	v_mul_f32_e64 v214, v214, -v171
	v_sub_f32_e32 v247, 1.0, v247
	v_cndmask_b32_e32 v214, v214, v247, vcc
	v_fmamk_f32 v164, v107, 0xbfb8aa3b, v91
	v_exp_f32_e32 v164, v164
	s_nop 0
	v_add_f32_e32 v164, 1.0, v164
	v_rcp_f32_e32 v164, v164
	s_nop 0
	v_mul_f32_e32 v171, v87, v164
	v_add_f32_e32 v215, v171, v171
	v_mul_f32_e32 v247, 0x3fb8aa3b, v215
	v_exp_f32_e32 v247, v247
	v_fma_f32 v212, v215, s14, 0.5
	v_fma_f32 v212, v215, v212, 1.0
	v_cmp_nlt_f32_e32 vcc, s51, v215
	v_mul_f32_e64 v212, v212, -v215
	v_sub_f32_e32 v247, 1.0, v247
	v_cndmask_b32_e32 v212, v212, v247, vcc
	v_fmamk_f32 v164, v102, 0xbfb8aa3b, v78
	v_exp_f32_e32 v164, v164
	v_max_f32_e32 v213, 0, v213
	v_add_f32_e32 v164, 1.0, v164
	v_max_f32_e32 v168, 0, v168
	v_lshlrev_b64 v[146:147], 10, v[146:147]
	v_lshl_add_u64 v[146:147], v[146:147], 0, v[180:181]
	v_max_f32_e32 v166, 0, v214
	v_rcp_f32_e32 v164, v164
	s_waitcnt vmcnt(0)
	v_lshlrev_b32_e32 v165, 16, v149
	v_sqrt_f32_e32 v166, v166
	v_lshlrev_b64 v[146:147], 1, v[146:147]
	v_lshl_add_u64 v[218:219], s[0:1], 0, v[146:147]
	v_mul_f32_e32 v164, v164, v166
	v_mul_f32_e32 v164, v164, v165
	v_fmamk_f32 v165, v103, 0xbfb8aa3b, v79
	v_exp_f32_e32 v165, v165
	s_nop 0
	v_add_f32_e32 v165, 1.0, v165
	v_rcp_f32_e32 v165, v165
	v_fmamk_f32 v166, v101, 0xbfb8aa3b, v77
	v_exp_f32_e32 v166, v166
	s_nop 0
	v_add_f32_e32 v166, 1.0, v166
	v_rcp_f32_e32 v166, v166
	v_and_b32_e32 v167, 0xffff0000, v148
	v_sqrt_f32_e32 v213, v213
	v_lshlrev_b32_e32 v148, 16, v148
	v_mul_f32_e32 v166, v166, v213
	v_mul_f32_e32 v166, v166, v167
	v_fmamk_f32 v167, v100, 0xbfb8aa3b, v76
	v_exp_f32_e32 v167, v167
	s_nop 0
	v_add_f32_e32 v167, 1.0, v167
	v_rcp_f32_e32 v167, v167
	v_lshl_add_u64 v[214:215], s[58:59], 0, v[146:147]
	v_sqrt_f32_e32 v168, v168
	v_fmamk_f32 v146, v96, 0xbfb8aa3b, v88
	v_mul_f32_e32 v167, v167, v168
	v_mul_f32_e32 v167, v167, v148
	v_and_b32_e32 v148, 0xffff0000, v149
	v_max_f32_e32 v149, 0, v212
	v_exp_f32_e32 v146, v146
	v_sqrt_f32_e32 v149, v149
	v_add_f32_e32 v146, 1.0, v146
	v_mul_f32_e32 v149, v165, v149
	v_mul_f32_e32 v165, v149, v148
	v_cvt_pk_bf16_f32 v148, v150, v151
	v_cvt_pk_bf16_f32 v149, v170, v171
	global_store_dwordx2 v[214:215], v[148:149], off
	v_cvt_pk_bf16_f32 v148, v167, v166
	v_cvt_pk_bf16_f32 v149, v164, v165
	global_store_dwordx2 v[218:219], v[148:149], off
	v_rcp_f32_e32 v146, v146
	s_nop 0
	v_mul_f32_e32 v146, v84, v146
	v_add_f32_e32 v147, v146, v146
	v_mul_f32_e32 v247, 0x3fb8aa3b, v147
	v_exp_f32_e32 v247, v247
	v_fma_f32 v148, v147, s14, 0.5
	v_fma_f32 v148, v147, v148, 1.0
	v_cmp_nlt_f32_e32 vcc, s51, v147
	v_mul_f32_e64 v148, v148, -v147
	v_sub_f32_e32 v247, 1.0, v247
	v_cndmask_b32_e32 v148, v148, v247, vcc
	v_fmamk_f32 v147, v97, 0xbfb8aa3b, v89
	v_exp_f32_e32 v147, v147
	s_nop 0
	v_add_f32_e32 v147, 1.0, v147
	v_rcp_f32_e32 v147, v147
	s_nop 0
	v_mul_f32_e32 v147, v85, v147
	v_add_f32_e32 v149, v147, v147
	v_mul_f32_e32 v247, 0x3fb8aa3b, v149
	v_exp_f32_e32 v247, v247
	v_fma_f32 v168, v149, s14, 0.5
	v_fma_f32 v168, v149, v168, 1.0
	v_cmp_nlt_f32_e32 vcc, s51, v149
	v_mul_f32_e64 v168, v168, -v149
	v_sub_f32_e32 v247, 1.0, v247
	v_cndmask_b32_e32 v168, v168, v247, vcc
	v_fmamk_f32 v149, v98, 0xbfb8aa3b, v90
	v_exp_f32_e32 v149, v149
	s_nop 0
	v_add_f32_e32 v149, 1.0, v149
	v_rcp_f32_e32 v149, v149
	s_nop 0
	v_mul_f32_e32 v149, v86, v149
	v_add_f32_e32 v150, v149, v149
	v_mul_f32_e32 v247, 0x3fb8aa3b, v150
	v_exp_f32_e32 v247, v247
	v_fma_f32 v170, v150, s14, 0.5
	v_fma_f32 v170, v150, v170, 1.0
	v_cmp_nlt_f32_e32 vcc, s51, v150
	v_mul_f32_e64 v170, v170, -v150
	v_sub_f32_e32 v247, 1.0, v247
	v_cndmask_b32_e32 v170, v170, v247, vcc
	v_fmamk_f32 v150, v99, 0xbfb8aa3b, v91
	v_exp_f32_e32 v150, v150
	s_nop 0
	v_add_f32_e32 v150, 1.0, v150
	v_rcp_f32_e32 v150, v150
	s_nop 0
	v_mul_f32_e32 v150, v87, v150
	v_add_f32_e32 v171, v150, v150
	v_mul_f32_e32 v247, 0x3fb8aa3b, v171
	v_exp_f32_e32 v247, v247
	v_fma_f32 v151, v171, s14, 0.5
	v_fma_f32 v151, v171, v151, 1.0
	v_cmp_nlt_f32_e32 vcc, s51, v171
	v_mul_f32_e64 v151, v151, -v171
	v_sub_f32_e32 v247, 1.0, v247
	v_cndmask_b32_e32 v151, v151, v247, vcc
	v_fmamk_f32 v164, v94, 0xbfb8aa3b, v78
	v_exp_f32_e32 v164, v164
	v_max_f32_e32 v168, 0, v168
	v_add_f32_e32 v164, 1.0, v164
	v_max_f32_e32 v148, 0, v148
	v_lshlrev_b64 v[142:143], 10, v[142:143]
	v_lshl_add_u64 v[142:143], v[142:143], 0, v[180:181]
	v_max_f32_e32 v166, 0, v170
	v_rcp_f32_e32 v164, v164
	v_lshlrev_b32_e32 v165, 16, v145
	v_sqrt_f32_e32 v166, v166
	v_lshlrev_b64 v[142:143], 1, v[142:143]
	v_lshl_add_u64 v[216:217], s[0:1], 0, v[142:143]
	v_mul_f32_e32 v164, v164, v166
	v_mul_f32_e32 v164, v164, v165
	v_fmamk_f32 v165, v95, 0xbfb8aa3b, v79
	v_exp_f32_e32 v165, v165
	s_nop 0
	v_add_f32_e32 v165, 1.0, v165
	v_rcp_f32_e32 v165, v165
	v_fmamk_f32 v166, v93, 0xbfb8aa3b, v77
	v_exp_f32_e32 v166, v166
	s_nop 0
	v_add_f32_e32 v166, 1.0, v166
	v_rcp_f32_e32 v166, v166
	v_and_b32_e32 v167, 0xffff0000, v144
	v_sqrt_f32_e32 v168, v168
	v_lshlrev_b32_e32 v144, 16, v144
	v_mul_f32_e32 v166, v166, v168
	v_mul_f32_e32 v166, v166, v167
	v_fmamk_f32 v167, v92, 0xbfb8aa3b, v76
	v_exp_f32_e32 v167, v167
	s_nop 0
	v_add_f32_e32 v167, 1.0, v167
	v_rcp_f32_e32 v167, v167
	v_lshl_add_u64 v[212:213], s[58:59], 0, v[142:143]
	v_sqrt_f32_e32 v148, v148
	s_nop 0
	v_mul_f32_e32 v148, v167, v148
	v_mul_f32_e32 v148, v148, v144
	v_and_b32_e32 v144, 0xffff0000, v145
	v_max_f32_e32 v145, 0, v151
	v_sqrt_f32_e32 v145, v145
	s_nop 0
	v_mul_f32_e32 v145, v165, v145
	v_mul_f32_e32 v151, v145, v144
	v_cvt_pk_bf16_f32 v144, v146, v147
	v_cvt_pk_bf16_f32 v145, v149, v150
	global_store_dwordx2 v[212:213], v[144:145], off
	v_cvt_pk_bf16_f32 v144, v148, v166
	v_cvt_pk_bf16_f32 v145, v164, v151
	global_store_dwordx2 v[216:217], v[144:145], off
	v_add_u32_e32 v144, 0xa0, v182
	v_ashrrev_i32_e32 v145, 31, v144
	v_lshlrev_b64 v[220:221], 11, v[144:145]
	v_lshl_add_u64 v[142:143], v[140:141], 0, v[220:221]
	global_load_dwordx2 v[146:147], v[142:143], off
	v_add_u32_e32 v142, 0xb0, v182
	v_ashrrev_i32_e32 v143, 31, v142
	v_lshlrev_b64 v[222:223], 11, v[142:143]
	v_lshl_add_u64 v[140:141], v[140:141], 0, v[222:223]
	global_load_dwordx2 v[140:141], v[140:141], off
	v_fmamk_f32 v148, v80, 0xbfb8aa3b, v88
	v_exp_f32_e32 v148, v148
	s_nop 0
	v_add_f32_e32 v148, 1.0, v148
	v_rcp_f32_e32 v148, v148
	s_nop 0
	v_mul_f32_e32 v148, v84, v148
	v_add_f32_e32 v149, v148, v148
	v_mul_f32_e32 v247, 0x3fb8aa3b, v149
	v_exp_f32_e32 v247, v247
	v_fma_f32 v150, v149, s14, 0.5
	v_fma_f32 v150, v149, v150, 1.0
	v_cmp_nlt_f32_e32 vcc, s51, v149
	v_mul_f32_e64 v150, v150, -v149
	v_sub_f32_e32 v247, 1.0, v247
	v_cndmask_b32_e32 v150, v150, v247, vcc
	v_fmamk_f32 v149, v81, 0xbfb8aa3b, v89
	v_exp_f32_e32 v149, v149
	s_nop 0
	v_add_f32_e32 v149, 1.0, v149
	v_rcp_f32_e32 v149, v149
	s_nop 0
	v_mul_f32_e32 v149, v85, v149
	v_add_f32_e32 v151, v149, v149
	v_mul_f32_e32 v247, 0x3fb8aa3b, v151
	v_exp_f32_e32 v247, v247
	v_fma_f32 v171, v151, s14, 0.5
	v_fma_f32 v171, v151, v171, 1.0
	v_cmp_nlt_f32_e32 vcc, s51, v151
	v_mul_f32_e64 v171, v171, -v151
	v_sub_f32_e32 v247, 1.0, v247
	v_cndmask_b32_e32 v171, v171, v247, vcc
	v_fmamk_f32 v151, v82, 0xbfb8aa3b, v90
	v_exp_f32_e32 v151, v151
	s_nop 0
	v_add_f32_e32 v151, 1.0, v151
	v_rcp_f32_e32 v151, v151
	s_nop 0
	v_mul_f32_e32 v151, v86, v151
	v_add_f32_e32 v168, v151, v151
	v_mul_f32_e32 v247, 0x3fb8aa3b, v168
	v_exp_f32_e32 v247, v247
	v_fma_f32 v224, v168, s14, 0.5
	v_fma_f32 v224, v168, v224, 1.0
	v_cmp_nlt_f32_e32 vcc, s51, v168
	v_mul_f32_e64 v224, v224, -v168
	v_sub_f32_e32 v247, 1.0, v247
	v_cndmask_b32_e32 v224, v224, v247, vcc
	v_fmamk_f32 v164, v83, 0xbfb8aa3b, v91
	v_exp_f32_e32 v164, v164
	s_nop 0
	v_add_f32_e32 v164, 1.0, v164
	v_rcp_f32_e32 v164, v164
	s_nop 0
	v_mul_f32_e32 v168, v87, v164
	v_add_f32_e32 v225, v168, v168
	v_mul_f32_e32 v247, 0x3fb8aa3b, v225
	v_exp_f32_e32 v247, v247
	v_fma_f32 v170, v225, s14, 0.5
	v_fma_f32 v170, v225, v170, 1.0
	v_cmp_nlt_f32_e32 vcc, s51, v225
	v_mul_f32_e64 v170, v170, -v225
	v_sub_f32_e32 v247, 1.0, v247
	v_cndmask_b32_e32 v170, v170, v247, vcc
	v_fmamk_f32 v164, v74, 0xbfb8aa3b, v78
	v_exp_f32_e32 v164, v164
	v_max_f32_e32 v171, 0, v171
	v_add_f32_e32 v164, 1.0, v164
	v_max_f32_e32 v150, 0, v150
	v_lshlrev_b64 v[144:145], 10, v[144:145]
	v_lshl_add_u64 v[144:145], v[144:145], 0, v[180:181]
	v_max_f32_e32 v166, 0, v224
	v_rcp_f32_e32 v164, v164
	s_waitcnt vmcnt(0)
	v_lshlrev_b32_e32 v165, 16, v147
	v_sqrt_f32_e32 v166, v166
	v_lshlrev_b64 v[144:145], 1, v[144:145]
	v_mul_f32_e32 v164, v164, v166
	v_mul_f32_e32 v164, v164, v165
	v_fmamk_f32 v165, v75, 0xbfb8aa3b, v79
	v_exp_f32_e32 v165, v165
	s_nop 0
	v_add_f32_e32 v165, 1.0, v165
	v_rcp_f32_e32 v165, v165
	v_fmamk_f32 v166, v73, 0xbfb8aa3b, v77
	v_exp_f32_e32 v166, v166
	s_nop 0
	v_add_f32_e32 v166, 1.0, v166
	v_rcp_f32_e32 v166, v166
	v_and_b32_e32 v167, 0xffff0000, v146
	v_sqrt_f32_e32 v171, v171
	v_lshlrev_b32_e32 v146, 16, v146
	v_mul_f32_e32 v166, v166, v171
	v_mul_f32_e32 v166, v166, v167
	v_fmamk_f32 v167, v72, 0xbfb8aa3b, v76
	v_exp_f32_e32 v167, v167
	s_nop 0
	v_add_f32_e32 v167, 1.0, v167
	v_rcp_f32_e32 v167, v167
	v_lshl_add_u64 v[224:225], s[58:59], 0, v[144:145]
	v_sqrt_f32_e32 v150, v150
	v_lshl_add_u64 v[226:227], s[0:1], 0, v[144:145]
	v_mul_f32_e32 v150, v167, v150
	v_mul_f32_e32 v150, v150, v146
	v_and_b32_e32 v146, 0xffff0000, v147
	v_max_f32_e32 v147, 0, v170
	v_fmamk_f32 v144, v68, 0xbfb8aa3b, v88
	v_exp_f32_e32 v144, v144
	v_sqrt_f32_e32 v147, v147
	v_add_f32_e32 v144, 1.0, v144
	v_mul_f32_e32 v147, v165, v147
	v_mul_f32_e32 v165, v147, v146
	v_cvt_pk_bf16_f32 v146, v148, v149
	v_cvt_pk_bf16_f32 v147, v151, v168
	global_store_dwordx2 v[224:225], v[146:147], off
	v_cvt_pk_bf16_f32 v146, v150, v166
	v_cvt_pk_bf16_f32 v147, v164, v165
	global_store_dwordx2 v[226:227], v[146:147], off
	v_rcp_f32_e32 v144, v144
	s_nop 0
	v_mul_f32_e32 v144, v84, v144
	v_add_f32_e32 v145, v144, v144
	v_mul_f32_e32 v247, 0x3fb8aa3b, v145
	v_exp_f32_e32 v247, v247
	v_fma_f32 v146, v145, s14, 0.5
	v_fma_f32 v146, v145, v146, 1.0
	v_cmp_nlt_f32_e32 vcc, s51, v145
	v_mul_f32_e64 v146, v146, -v145
	v_sub_f32_e32 v247, 1.0, v247
	v_cndmask_b32_e32 v146, v146, v247, vcc
	v_fmamk_f32 v145, v69, 0xbfb8aa3b, v89
	v_exp_f32_e32 v145, v145
	s_nop 0
	v_add_f32_e32 v145, 1.0, v145
	v_rcp_f32_e32 v145, v145
	s_nop 0
	v_mul_f32_e32 v145, v85, v145
	v_add_f32_e32 v147, v145, v145
	v_mul_f32_e32 v247, 0x3fb8aa3b, v147
	v_exp_f32_e32 v247, v247
	v_fma_f32 v150, v147, s14, 0.5
	v_fma_f32 v150, v147, v150, 1.0
	v_cmp_nlt_f32_e32 vcc, s51, v147
	v_mul_f32_e64 v150, v150, -v147
	v_sub_f32_e32 v247, 1.0, v247
	v_cndmask_b32_e32 v150, v150, v247, vcc
	v_fmamk_f32 v147, v70, 0xbfb8aa3b, v90
	v_exp_f32_e32 v147, v147
	s_nop 0
	v_add_f32_e32 v147, 1.0, v147
	v_rcp_f32_e32 v147, v147
	s_nop 0
	v_mul_f32_e32 v147, v86, v147
	v_add_f32_e32 v148, v147, v147
	v_mul_f32_e32 v247, 0x3fb8aa3b, v148
	v_exp_f32_e32 v247, v247
	v_fma_f32 v151, v148, s14, 0.5
	v_fma_f32 v151, v148, v151, 1.0
	v_cmp_nlt_f32_e32 vcc, s51, v148
	v_mul_f32_e64 v151, v151, -v148
	v_sub_f32_e32 v247, 1.0, v247
	v_cndmask_b32_e32 v151, v151, v247, vcc
	v_fmamk_f32 v148, v71, 0xbfb8aa3b, v91
	v_exp_f32_e32 v148, v148
	s_nop 0
	v_add_f32_e32 v148, 1.0, v148
	v_rcp_f32_e32 v148, v148
	s_nop 0
	v_mul_f32_e32 v148, v87, v148
	v_add_f32_e32 v168, v148, v148
	v_mul_f32_e32 v247, 0x3fb8aa3b, v168
	v_exp_f32_e32 v247, v247
	v_fma_f32 v149, v168, s14, 0.5
	v_fma_f32 v149, v168, v149, 1.0
	v_cmp_nlt_f32_e32 vcc, s51, v168
	v_mul_f32_e64 v149, v149, -v168
	v_sub_f32_e32 v247, 1.0, v247
	v_cndmask_b32_e32 v149, v149, v247, vcc
	v_fmamk_f32 v164, v66, 0xbfb8aa3b, v78
	v_exp_f32_e32 v164, v164
	v_max_f32_e32 v151, 0, v151
	v_add_f32_e32 v164, 1.0, v164
	v_max_f32_e32 v150, 0, v150
	v_max_f32_e32 v146, 0, v146
	v_rcp_f32_e32 v164, v164
	v_lshlrev_b32_e32 v165, 16, v141
	v_sqrt_f32_e32 v151, v151
	v_lshlrev_b64 v[142:143], 10, v[142:143]
	v_lshl_add_u64 v[234:235], s[28:29], 0, v[178:179]
	v_mul_f32_e32 v151, v164, v151
	v_fmamk_f32 v164, v67, 0xbfb8aa3b, v79
	v_exp_f32_e32 v164, v164
	v_mul_f32_e32 v151, v151, v165
	v_add_f32_e32 v164, 1.0, v164
	v_rcp_f32_e32 v164, v164
	v_fmamk_f32 v165, v65, 0xbfb8aa3b, v77
	v_exp_f32_e32 v165, v165
	s_nop 0
	v_add_f32_e32 v165, 1.0, v165
	v_rcp_f32_e32 v165, v165
	v_and_b32_e32 v166, 0xffff0000, v140
	v_sqrt_f32_e32 v150, v150
	v_lshlrev_b32_e32 v140, 16, v140
	v_mul_f32_e32 v150, v165, v150
	v_fmamk_f32 v165, v64, 0xbfb8aa3b, v76
	v_exp_f32_e32 v165, v165
	v_mul_f32_e32 v150, v150, v166
	v_add_f32_e32 v165, 1.0, v165
	v_rcp_f32_e32 v165, v165
	v_or_b32_e32 v170, 64, v180
	v_sqrt_f32_e32 v146, v146
	v_ashrrev_i32_e32 v171, 31, v170
	v_lshlrev_b64 v[232:233], 1, v[170:171]
	v_mul_f32_e32 v146, v165, v146
	v_mul_f32_e32 v146, v146, v140
	v_and_b32_e32 v140, 0xffff0000, v141
	v_max_f32_e32 v141, 0, v149
	v_lshl_add_u64 v[170:171], v[234:235], 0, v[232:233]
	v_sqrt_f32_e32 v141, v141
	s_nop 0
	v_mul_f32_e32 v141, v164, v141
	v_mul_f32_e32 v149, v141, v140
	v_lshl_add_u64 v[140:141], v[142:143], 0, v[180:181]
	v_lshlrev_b64 v[140:141], 1, v[140:141]
	v_cvt_pk_bf16_f32 v142, v144, v145
	v_cvt_pk_bf16_f32 v143, v147, v148
	v_lshl_add_u64 v[228:229], s[58:59], 0, v[140:141]
	v_lshl_add_u64 v[230:231], s[0:1], 0, v[140:141]
	global_store_dwordx2 v[228:229], v[142:143], off
	v_cvt_pk_bf16_f32 v142, v146, v150
	v_cvt_pk_bf16_f32 v143, v151, v149
	global_store_dwordx2 v[230:231], v[142:143], off
	global_load_dwordx4 v[148:151], v[172:173], off offset:256
	s_nop 0
	global_load_dwordx4 v[140:143], v[158:159], off offset:256
	global_load_dwordx4 v[144:147], v[174:175], off offset:256
	global_load_dwordx2 v[236:237], v[170:171], off
	v_lshl_add_u64 v[170:171], s[28:29], 0, v[176:177]
	v_lshl_add_u64 v[170:171], v[170:171], 0, v[232:233]
	global_load_dwordx2 v[234:235], v[170:171], off
	s_waitcnt vmcnt(0)
	v_mul_f32_e32 v148, 0xbfb8aa3b, v148
	v_mul_f32_e32 v149, 0xbfb8aa3b, v149
	v_mul_f32_e32 v150, 0xbfb8aa3b, v150
	v_mul_f32_e32 v151, 0xbfb8aa3b, v151
	v_mul_f32_e32 v140, 0xbfb8aa3b, v140
	v_mul_f32_e32 v141, 0xbfb8aa3b, v141
	v_mul_f32_e32 v142, 0xbfb8aa3b, v142
	v_mul_f32_e32 v143, 0xbfb8aa3b, v143
	v_mul_f32_e32 v144, 0xc1000000, v144
	v_mul_f32_e32 v145, 0xc1000000, v145
	v_mul_f32_e32 v146, 0xc1000000, v146
	v_mul_f32_e32 v147, 0xc1000000, v147
	v_fmamk_f32 v164, v60, 0xbfb8aa3b, v148
	v_exp_f32_e32 v164, v164
	s_nop 0
	v_add_f32_e32 v164, 1.0, v164
	v_rcp_f32_e32 v164, v164
	s_nop 0
	v_mul_f32_e32 v168, v144, v164
	v_add_f32_e32 v170, v168, v168
	v_mul_f32_e32 v247, 0x3fb8aa3b, v170
	v_exp_f32_e32 v247, v247
	v_fma_f32 v171, v170, s14, 0.5
	v_fma_f32 v171, v170, v171, 1.0
	v_cmp_nlt_f32_e32 vcc, s51, v170
	v_mul_f32_e64 v171, v171, -v170
	v_sub_f32_e32 v247, 1.0, v247
	v_cndmask_b32_e32 v171, v171, v247, vcc
	v_fmamk_f32 v164, v61, 0xbfb8aa3b, v149
	v_exp_f32_e32 v164, v164
	s_nop 0
	v_add_f32_e32 v164, 1.0, v164
	v_rcp_f32_e32 v164, v164
	s_nop 0
	v_mul_f32_e32 v170, v145, v164
	v_add_f32_e32 v241, v170, v170
	v_mul_f32_e32 v247, 0x3fb8aa3b, v241
	v_exp_f32_e32 v247, v247
	v_fma_f32 v244, v241, s14, 0.5
	v_fma_f32 v244, v241, v244, 1.0
	v_cmp_nlt_f32_e32 vcc, s51, v241
	v_mul_f32_e64 v244, v244, -v241
	v_sub_f32_e32 v247, 1.0, v247
	v_cndmask_b32_e32 v244, v244, v247, vcc
	v_fmamk_f32 v164, v62, 0xbfb8aa3b, v150
	v_exp_f32_e32 v164, v164
	s_nop 0
	v_add_f32_e32 v164, 1.0, v164
	v_rcp_f32_e32 v164, v164
	s_nop 0
	v_mul_f32_e32 v241, v146, v164
	v_add_f32_e32 v242, v241, v241
	v_mul_f32_e32 v247, 0x3fb8aa3b, v242
	v_exp_f32_e32 v247, v247
	v_fma_f32 v245, v242, s14, 0.5
	v_fma_f32 v245, v242, v245, 1.0
	v_cmp_nlt_f32_e32 vcc, s51, v242
	v_mul_f32_e64 v245, v245, -v242
	v_sub_f32_e32 v247, 1.0, v247
	v_cndmask_b32_e32 v245, v245, v247, vcc
	v_fmamk_f32 v164, v63, 0xbfb8aa3b, v151
	v_exp_f32_e32 v164, v164
	s_nop 0
	v_add_f32_e32 v164, 1.0, v164
	v_rcp_f32_e32 v164, v164
	s_nop 0
	v_mul_f32_e32 v242, v147, v164
	v_add_f32_e32 v246, v242, v242
	v_mul_f32_e32 v247, 0x3fb8aa3b, v246
	v_exp_f32_e32 v247, v247
	v_fma_f32 v243, v246, s14, 0.5
	v_fma_f32 v243, v246, v243, 1.0
	v_cmp_nlt_f32_e32 vcc, s51, v246
	v_mul_f32_e64 v243, v243, -v246
	v_sub_f32_e32 v247, 1.0, v247
	v_cndmask_b32_e32 v243, v243, v247, vcc
	v_fmamk_f32 v164, v58, 0xbfb8aa3b, v142
	v_exp_f32_e32 v164, v164
	v_max_f32_e32 v171, 0, v171
	v_cvt_pk_bf16_f32 v170, v168, v170
	v_add_f32_e32 v164, 1.0, v164
	v_max_f32_e32 v166, 0, v245
	v_rcp_f32_e32 v164, v164
	v_lshlrev_b32_e32 v165, 16, v237
	v_sqrt_f32_e32 v166, v166
	s_nop 0
	v_mul_f32_e32 v164, v164, v166
	v_mul_f32_e32 v164, v164, v165
	v_fmamk_f32 v165, v59, 0xbfb8aa3b, v143
	v_exp_f32_e32 v165, v165
	s_nop 0
	v_add_f32_e32 v165, 1.0, v165
	v_rcp_f32_e32 v165, v165
	v_fmamk_f32 v166, v57, 0xbfb8aa3b, v141
	v_exp_f32_e32 v166, v166
	s_nop 0
	v_add_f32_e32 v166, 1.0, v166
	v_max_f32_e32 v169, 0, v244
	v_rcp_f32_e32 v166, v166
	v_and_b32_e32 v167, 0xffff0000, v236
	v_sqrt_f32_e32 v169, v169
	s_nop 0
	v_mul_f32_e32 v166, v166, v169
	v_fmamk_f32 v169, v56, 0xbfb8aa3b, v140
	v_exp_f32_e32 v169, v169
	v_mul_f32_e32 v166, v166, v167
	v_lshlrev_b32_e32 v167, 16, v236
	v_add_f32_e32 v169, 1.0, v169
	v_rcp_f32_e32 v169, v169
	v_sqrt_f32_e32 v171, v171
	s_nop 0
	v_mul_f32_e32 v169, v169, v171
	v_max_f32_e32 v171, 0, v243
	v_mul_f32_e32 v167, v169, v167
	v_and_b32_e32 v169, 0xffff0000, v237
	v_sqrt_f32_e32 v171, v171
	s_nop 0
	v_mul_f32_e32 v165, v165, v171
	v_cvt_pk_bf16_f32 v171, v241, v242
	v_mul_f32_e32 v165, v165, v169
	global_store_dwordx2 v[190:191], v[170:171], off offset:128
	v_cvt_pk_bf16_f32 v170, v167, v166
	v_cvt_pk_bf16_f32 v171, v164, v165
	v_fmamk_f32 v164, v52, 0xbfb8aa3b, v148
	v_exp_f32_e32 v164, v164
	global_store_dwordx2 v[194:195], v[170:171], off offset:128
	v_add_f32_e32 v164, 1.0, v164
	v_rcp_f32_e32 v164, v164
	s_nop 0
	v_mul_f32_e32 v168, v144, v164
	v_add_f32_e32 v170, v168, v168
	v_mul_f32_e32 v247, 0x3fb8aa3b, v170
	v_exp_f32_e32 v247, v247
	v_fma_f32 v171, v170, s14, 0.5
	v_fma_f32 v171, v170, v171, 1.0
	v_cmp_nlt_f32_e32 vcc, s51, v170
	v_mul_f32_e64 v171, v171, -v170
	v_sub_f32_e32 v247, 1.0, v247
	v_cndmask_b32_e32 v171, v171, v247, vcc
	v_fmamk_f32 v164, v53, 0xbfb8aa3b, v149
	v_exp_f32_e32 v164, v164
	s_nop 0
	v_add_f32_e32 v164, 1.0, v164
	v_rcp_f32_e32 v164, v164
	s_nop 0
	v_mul_f32_e32 v170, v145, v164
	v_add_f32_e32 v190, v170, v170
	v_mul_f32_e32 v247, 0x3fb8aa3b, v190
	v_exp_f32_e32 v247, v247
	v_fma_f32 v195, v190, s14, 0.5
	v_fma_f32 v195, v190, v195, 1.0
	v_cmp_nlt_f32_e32 vcc, s51, v190
	v_mul_f32_e64 v195, v195, -v190
	v_sub_f32_e32 v247, 1.0, v247
	v_cndmask_b32_e32 v195, v195, v247, vcc
	v_fmamk_f32 v164, v54, 0xbfb8aa3b, v150
	v_exp_f32_e32 v164, v164
	s_nop 0
	v_add_f32_e32 v164, 1.0, v164
	v_rcp_f32_e32 v164, v164
	s_nop 0
	v_mul_f32_e32 v190, v146, v164
	v_add_f32_e32 v191, v190, v190
	v_mul_f32_e32 v247, 0x3fb8aa3b, v191
	v_exp_f32_e32 v247, v247
	v_fma_f32 v236, v191, s14, 0.5
	v_fma_f32 v236, v191, v236, 1.0
	v_cmp_nlt_f32_e32 vcc, s51, v191
	v_mul_f32_e64 v236, v236, -v191
	v_sub_f32_e32 v247, 1.0, v247
	v_cndmask_b32_e32 v236, v236, v247, vcc
	v_fmamk_f32 v164, v55, 0xbfb8aa3b, v151
	v_exp_f32_e32 v164, v164
	s_nop 0
	v_add_f32_e32 v164, 1.0, v164
	v_rcp_f32_e32 v164, v164
	s_nop 0
	v_mul_f32_e32 v191, v147, v164
	v_add_f32_e32 v237, v191, v191
	v_mul_f32_e32 v247, 0x3fb8aa3b, v237
	v_exp_f32_e32 v247, v247
	v_fma_f32 v194, v237, s14, 0.5
	v_fma_f32 v194, v237, v194, 1.0
	v_cmp_nlt_f32_e32 vcc, s51, v237
	v_mul_f32_e64 v194, v194, -v237
	v_sub_f32_e32 v247, 1.0, v247
	v_cndmask_b32_e32 v194, v194, v247, vcc
	v_fmamk_f32 v164, v50, 0xbfb8aa3b, v142
	v_exp_f32_e32 v164, v164
	v_max_f32_e32 v171, 0, v171
	v_cvt_pk_bf16_f32 v170, v168, v170
	v_add_f32_e32 v164, 1.0, v164
	v_max_f32_e32 v166, 0, v236
	v_rcp_f32_e32 v164, v164
	v_lshlrev_b32_e32 v165, 16, v235
	v_sqrt_f32_e32 v166, v166
	s_nop 0
	v_mul_f32_e32 v164, v164, v166
	v_mul_f32_e32 v164, v164, v165
	v_fmamk_f32 v165, v51, 0xbfb8aa3b, v143
	v_exp_f32_e32 v165, v165
	s_nop 0
	v_add_f32_e32 v165, 1.0, v165
	v_rcp_f32_e32 v165, v165
	v_fmamk_f32 v166, v49, 0xbfb8aa3b, v141
	v_exp_f32_e32 v166, v166
	s_nop 0
	v_add_f32_e32 v166, 1.0, v166
	v_max_f32_e32 v169, 0, v195
	v_rcp_f32_e32 v166, v166
	v_and_b32_e32 v167, 0xffff0000, v234
	v_sqrt_f32_e32 v169, v169
	s_nop 0
	v_mul_f32_e32 v166, v166, v169
	v_fmamk_f32 v169, v48, 0xbfb8aa3b, v140
	v_exp_f32_e32 v169, v169
	v_mul_f32_e32 v166, v166, v167
	v_lshlrev_b32_e32 v167, 16, v234
	v_add_f32_e32 v169, 1.0, v169
	v_rcp_f32_e32 v169, v169
	v_sqrt_f32_e32 v171, v171
	s_nop 0
	v_mul_f32_e32 v169, v169, v171
	v_max_f32_e32 v171, 0, v194
	v_mul_f32_e32 v167, v169, v167
	v_and_b32_e32 v169, 0xffff0000, v235
	v_sqrt_f32_e32 v171, v171
	s_nop 0
	v_mul_f32_e32 v165, v165, v171
	v_cvt_pk_bf16_f32 v171, v190, v191
	v_mul_f32_e32 v165, v165, v169
	global_store_dwordx2 v[188:189], v[170:171], off offset:128
	v_cvt_pk_bf16_f32 v170, v167, v166
	v_cvt_pk_bf16_f32 v171, v164, v165
	global_store_dwordx2 v[192:193], v[170:171], off offset:128
	v_lshl_add_u64 v[170:171], s[28:29], 0, v[196:197]
	v_lshl_add_u64 v[170:171], v[170:171], 0, v[232:233]
	global_load_dwordx2 v[190:191], v[170:171], off
	v_lshl_add_u64 v[170:171], s[28:29], 0, v[198:199]
	v_lshl_add_u64 v[170:171], v[170:171], 0, v[232:233]
	global_load_dwordx2 v[188:189], v[170:171], off
	v_fmamk_f32 v164, v44, 0xbfb8aa3b, v148
	v_exp_f32_e32 v164, v164
	s_nop 0
	v_add_f32_e32 v164, 1.0, v164
	v_rcp_f32_e32 v164, v164
	s_nop 0
	v_mul_f32_e32 v168, v144, v164
	v_add_f32_e32 v170, v168, v168
	v_mul_f32_e32 v247, 0x3fb8aa3b, v170
	v_exp_f32_e32 v247, v247
	v_fma_f32 v171, v170, s14, 0.5
	v_fma_f32 v171, v170, v171, 1.0
	v_cmp_nlt_f32_e32 vcc, s51, v170
	v_mul_f32_e64 v171, v171, -v170
	v_sub_f32_e32 v247, 1.0, v247
	v_cndmask_b32_e32 v171, v171, v247, vcc
	v_fmamk_f32 v164, v45, 0xbfb8aa3b, v149
	v_exp_f32_e32 v164, v164
	s_nop 0
	v_add_f32_e32 v164, 1.0, v164
	v_rcp_f32_e32 v164, v164
	s_nop 0
	v_mul_f32_e32 v170, v145, v164
	v_add_f32_e32 v192, v170, v170
	v_mul_f32_e32 v247, 0x3fb8aa3b, v192
	v_exp_f32_e32 v247, v247
	v_fma_f32 v195, v192, s14, 0.5
	v_fma_f32 v195, v192, v195, 1.0
	v_cmp_nlt_f32_e32 vcc, s51, v192
	v_mul_f32_e64 v195, v195, -v192
	v_sub_f32_e32 v247, 1.0, v247
	v_cndmask_b32_e32 v195, v195, v247, vcc
	v_fmamk_f32 v164, v46, 0xbfb8aa3b, v150
	v_exp_f32_e32 v164, v164
	s_nop 0
	v_add_f32_e32 v164, 1.0, v164
	v_rcp_f32_e32 v164, v164
	s_nop 0
	v_mul_f32_e32 v192, v146, v164
	v_add_f32_e32 v193, v192, v192
	v_mul_f32_e32 v247, 0x3fb8aa3b, v193
	v_exp_f32_e32 v247, v247
	v_fma_f32 v196, v193, s14, 0.5
	v_fma_f32 v196, v193, v196, 1.0
	v_cmp_nlt_f32_e32 vcc, s51, v193
	v_mul_f32_e64 v196, v196, -v193
	v_sub_f32_e32 v247, 1.0, v247
	v_cndmask_b32_e32 v196, v196, v247, vcc
	v_fmamk_f32 v164, v47, 0xbfb8aa3b, v151
	v_exp_f32_e32 v164, v164
	s_nop 0
	v_add_f32_e32 v164, 1.0, v164
	v_rcp_f32_e32 v164, v164
	s_nop 0
	v_mul_f32_e32 v193, v147, v164
	v_add_f32_e32 v197, v193, v193
	v_mul_f32_e32 v247, 0x3fb8aa3b, v197
	v_exp_f32_e32 v247, v247
	v_fma_f32 v194, v197, s14, 0.5
	v_fma_f32 v194, v197, v194, 1.0
	v_cmp_nlt_f32_e32 vcc, s51, v197
	v_mul_f32_e64 v194, v194, -v197
	v_sub_f32_e32 v247, 1.0, v247
	v_cndmask_b32_e32 v194, v194, v247, vcc
	v_fmamk_f32 v164, v42, 0xbfb8aa3b, v142
	v_exp_f32_e32 v164, v164
	v_max_f32_e32 v171, 0, v171
	v_cvt_pk_bf16_f32 v170, v168, v170
	v_add_f32_e32 v164, 1.0, v164
	v_max_f32_e32 v166, 0, v196
	v_rcp_f32_e32 v164, v164
	s_waitcnt vmcnt(0)
	v_lshlrev_b32_e32 v165, 16, v191
	v_sqrt_f32_e32 v166, v166
	s_nop 0
	v_mul_f32_e32 v164, v164, v166
	v_mul_f32_e32 v164, v164, v165
	v_fmamk_f32 v165, v43, 0xbfb8aa3b, v143
	v_exp_f32_e32 v165, v165
	s_nop 0
	v_add_f32_e32 v165, 1.0, v165
	v_rcp_f32_e32 v165, v165
	v_fmamk_f32 v166, v41, 0xbfb8aa3b, v141
	v_exp_f32_e32 v166, v166
	s_nop 0
	v_add_f32_e32 v166, 1.0, v166
	v_max_f32_e32 v169, 0, v195
	v_rcp_f32_e32 v166, v166
	v_and_b32_e32 v167, 0xffff0000, v190
	v_sqrt_f32_e32 v169, v169
	s_nop 0
	v_mul_f32_e32 v166, v166, v169
	v_fmamk_f32 v169, v40, 0xbfb8aa3b, v140
	v_exp_f32_e32 v169, v169
	v_mul_f32_e32 v166, v166, v167
	v_lshlrev_b32_e32 v167, 16, v190
	v_add_f32_e32 v169, 1.0, v169
	v_rcp_f32_e32 v169, v169
	v_sqrt_f32_e32 v171, v171
	s_nop 0
	v_mul_f32_e32 v169, v169, v171
	v_max_f32_e32 v171, 0, v194
	v_mul_f32_e32 v167, v169, v167
	v_and_b32_e32 v169, 0xffff0000, v191
	v_sqrt_f32_e32 v171, v171
	s_nop 0
	v_mul_f32_e32 v165, v165, v171
	v_cvt_pk_bf16_f32 v171, v192, v193
	v_mul_f32_e32 v165, v165, v169
	global_store_dwordx2 v[202:203], v[170:171], off offset:128
	v_cvt_pk_bf16_f32 v170, v167, v166
	v_cvt_pk_bf16_f32 v171, v164, v165
	v_fmamk_f32 v164, v36, 0xbfb8aa3b, v148
	v_exp_f32_e32 v164, v164
	global_store_dwordx2 v[206:207], v[170:171], off offset:128
	v_add_f32_e32 v164, 1.0, v164
	v_rcp_f32_e32 v164, v164
	s_nop 0
	v_mul_f32_e32 v168, v144, v164
	v_add_f32_e32 v170, v168, v168
	v_mul_f32_e32 v247, 0x3fb8aa3b, v170
	v_exp_f32_e32 v247, v247
	v_fma_f32 v171, v170, s14, 0.5
	v_fma_f32 v171, v170, v171, 1.0
	v_cmp_nlt_f32_e32 vcc, s51, v170
	v_mul_f32_e64 v171, v171, -v170
	v_sub_f32_e32 v247, 1.0, v247
	v_cndmask_b32_e32 v171, v171, v247, vcc
	v_fmamk_f32 v164, v37, 0xbfb8aa3b, v149
	v_exp_f32_e32 v164, v164
	s_nop 0
	v_add_f32_e32 v164, 1.0, v164
	v_rcp_f32_e32 v164, v164
	s_nop 0
	v_mul_f32_e32 v170, v145, v164
	v_add_f32_e32 v190, v170, v170
	v_mul_f32_e32 v247, 0x3fb8aa3b, v190
	v_exp_f32_e32 v247, v247
	v_fma_f32 v193, v190, s14, 0.5
	v_fma_f32 v193, v190, v193, 1.0
	v_cmp_nlt_f32_e32 vcc, s51, v190
	v_mul_f32_e64 v193, v193, -v190
	v_sub_f32_e32 v247, 1.0, v247
	v_cndmask_b32_e32 v193, v193, v247, vcc
	v_fmamk_f32 v164, v38, 0xbfb8aa3b, v150
	v_exp_f32_e32 v164, v164
	s_nop 0
	v_add_f32_e32 v164, 1.0, v164
	v_rcp_f32_e32 v164, v164
	s_nop 0
	v_mul_f32_e32 v190, v146, v164
	v_add_f32_e32 v191, v190, v190
	v_mul_f32_e32 v247, 0x3fb8aa3b, v191
	v_exp_f32_e32 v247, v247
	v_fma_f32 v194, v191, s14, 0.5
	v_fma_f32 v194, v191, v194, 1.0
	v_cmp_nlt_f32_e32 vcc, s51, v191
	v_mul_f32_e64 v194, v194, -v191
	v_sub_f32_e32 v247, 1.0, v247
	v_cndmask_b32_e32 v194, v194, v247, vcc
	v_fmamk_f32 v164, v39, 0xbfb8aa3b, v151
	v_exp_f32_e32 v164, v164
	s_nop 0
	v_add_f32_e32 v164, 1.0, v164
	v_rcp_f32_e32 v164, v164
	s_nop 0
	v_mul_f32_e32 v191, v147, v164
	v_add_f32_e32 v195, v191, v191
	v_mul_f32_e32 v247, 0x3fb8aa3b, v195
	v_exp_f32_e32 v247, v247
	v_fma_f32 v192, v195, s14, 0.5
	v_fma_f32 v192, v195, v192, 1.0
	v_cmp_nlt_f32_e32 vcc, s51, v195
	v_mul_f32_e64 v192, v192, -v195
	v_sub_f32_e32 v247, 1.0, v247
	v_cndmask_b32_e32 v192, v192, v247, vcc
	v_fmamk_f32 v164, v34, 0xbfb8aa3b, v142
	v_exp_f32_e32 v164, v164
	v_max_f32_e32 v171, 0, v171
	v_cvt_pk_bf16_f32 v170, v168, v170
	v_add_f32_e32 v164, 1.0, v164
	v_max_f32_e32 v166, 0, v194
	v_rcp_f32_e32 v164, v164
	v_lshlrev_b32_e32 v165, 16, v189
	v_sqrt_f32_e32 v166, v166
	s_nop 0
	v_mul_f32_e32 v164, v164, v166
	v_mul_f32_e32 v164, v164, v165
	v_fmamk_f32 v165, v35, 0xbfb8aa3b, v143
	v_exp_f32_e32 v165, v165
	s_nop 0
	v_add_f32_e32 v165, 1.0, v165
	v_rcp_f32_e32 v165, v165
	v_fmamk_f32 v166, v33, 0xbfb8aa3b, v141
	v_exp_f32_e32 v166, v166
	s_nop 0
	v_add_f32_e32 v166, 1.0, v166
	v_max_f32_e32 v169, 0, v193
	v_rcp_f32_e32 v166, v166
	v_and_b32_e32 v167, 0xffff0000, v188
	v_sqrt_f32_e32 v169, v169
	s_nop 0
	v_mul_f32_e32 v166, v166, v169
	v_fmamk_f32 v169, v32, 0xbfb8aa3b, v140
	v_exp_f32_e32 v169, v169
	v_mul_f32_e32 v166, v166, v167
	v_lshlrev_b32_e32 v167, 16, v188
	v_add_f32_e32 v169, 1.0, v169
	v_rcp_f32_e32 v169, v169
	v_sqrt_f32_e32 v171, v171
	s_nop 0
	v_mul_f32_e32 v169, v169, v171
	v_max_f32_e32 v171, 0, v192
	v_mul_f32_e32 v167, v169, v167
	v_and_b32_e32 v169, 0xffff0000, v189
	v_sqrt_f32_e32 v171, v171
	s_nop 0
	v_mul_f32_e32 v165, v165, v171
	v_cvt_pk_bf16_f32 v171, v190, v191
	v_mul_f32_e32 v165, v165, v169
	global_store_dwordx2 v[200:201], v[170:171], off offset:128
	v_cvt_pk_bf16_f32 v170, v167, v166
	v_cvt_pk_bf16_f32 v171, v164, v165
	global_store_dwordx2 v[204:205], v[170:171], off offset:128
	v_lshl_add_u64 v[170:171], s[28:29], 0, v[208:209]
	v_lshl_add_u64 v[170:171], v[170:171], 0, v[232:233]
	global_load_dwordx2 v[190:191], v[170:171], off
	v_lshl_add_u64 v[170:171], s[28:29], 0, v[210:211]
	v_lshl_add_u64 v[170:171], v[170:171], 0, v[232:233]
	global_load_dwordx2 v[188:189], v[170:171], off
	v_fmamk_f32 v164, v28, 0xbfb8aa3b, v148
	v_exp_f32_e32 v164, v164
	s_nop 0
	v_add_f32_e32 v164, 1.0, v164
	v_rcp_f32_e32 v164, v164
	s_nop 0
	v_mul_f32_e32 v168, v144, v164
	v_add_f32_e32 v170, v168, v168
	v_mul_f32_e32 v247, 0x3fb8aa3b, v170
	v_exp_f32_e32 v247, v247
	v_fma_f32 v171, v170, s14, 0.5
	v_fma_f32 v171, v170, v171, 1.0
	v_cmp_nlt_f32_e32 vcc, s51, v170
	v_mul_f32_e64 v171, v171, -v170
	v_sub_f32_e32 v247, 1.0, v247
	v_cndmask_b32_e32 v171, v171, v247, vcc
	v_fmamk_f32 v164, v29, 0xbfb8aa3b, v149
	v_exp_f32_e32 v164, v164
	s_nop 0
	v_add_f32_e32 v164, 1.0, v164
	v_rcp_f32_e32 v164, v164
	s_nop 0
	v_mul_f32_e32 v170, v145, v164
	v_add_f32_e32 v192, v170, v170
	v_mul_f32_e32 v247, 0x3fb8aa3b, v192
	v_exp_f32_e32 v247, v247
	v_fma_f32 v195, v192, s14, 0.5
	v_fma_f32 v195, v192, v195, 1.0
	v_cmp_nlt_f32_e32 vcc, s51, v192
	v_mul_f32_e64 v195, v195, -v192
	v_sub_f32_e32 v247, 1.0, v247
	v_cndmask_b32_e32 v195, v195, v247, vcc
	v_fmamk_f32 v164, v30, 0xbfb8aa3b, v150
	v_exp_f32_e32 v164, v164
	s_nop 0
	v_add_f32_e32 v164, 1.0, v164
	v_rcp_f32_e32 v164, v164
	s_nop 0
	v_mul_f32_e32 v192, v146, v164
	v_add_f32_e32 v193, v192, v192
	v_mul_f32_e32 v247, 0x3fb8aa3b, v193
	v_exp_f32_e32 v247, v247
	v_fma_f32 v196, v193, s14, 0.5
	v_fma_f32 v196, v193, v196, 1.0
	v_cmp_nlt_f32_e32 vcc, s51, v193
	v_mul_f32_e64 v196, v196, -v193
	v_sub_f32_e32 v247, 1.0, v247
	v_cndmask_b32_e32 v196, v196, v247, vcc
	v_fmamk_f32 v164, v31, 0xbfb8aa3b, v151
	v_exp_f32_e32 v164, v164
	s_nop 0
	v_add_f32_e32 v164, 1.0, v164
	v_rcp_f32_e32 v164, v164
	s_nop 0
	v_mul_f32_e32 v193, v147, v164
	v_add_f32_e32 v197, v193, v193
	v_mul_f32_e32 v247, 0x3fb8aa3b, v197
	v_exp_f32_e32 v247, v247
	v_fma_f32 v194, v197, s14, 0.5
	v_fma_f32 v194, v197, v194, 1.0
	v_cmp_nlt_f32_e32 vcc, s51, v197
	v_mul_f32_e64 v194, v194, -v197
	v_sub_f32_e32 v247, 1.0, v247
	v_cndmask_b32_e32 v194, v194, v247, vcc
	v_fmamk_f32 v164, v26, 0xbfb8aa3b, v142
	v_exp_f32_e32 v164, v164
	v_max_f32_e32 v171, 0, v171
	v_cvt_pk_bf16_f32 v170, v168, v170
	v_add_f32_e32 v164, 1.0, v164
	v_max_f32_e32 v166, 0, v196
	v_rcp_f32_e32 v164, v164
	s_waitcnt vmcnt(0)
	v_lshlrev_b32_e32 v165, 16, v191
	v_sqrt_f32_e32 v166, v166
	s_nop 0
	v_mul_f32_e32 v164, v164, v166
	v_mul_f32_e32 v164, v164, v165
	v_fmamk_f32 v165, v27, 0xbfb8aa3b, v143
	v_exp_f32_e32 v165, v165
	s_nop 0
	v_add_f32_e32 v165, 1.0, v165
	v_rcp_f32_e32 v165, v165
	v_fmamk_f32 v166, v25, 0xbfb8aa3b, v141
	v_exp_f32_e32 v166, v166
	s_nop 0
	v_add_f32_e32 v166, 1.0, v166
	v_max_f32_e32 v169, 0, v195
	v_rcp_f32_e32 v166, v166
	v_and_b32_e32 v167, 0xffff0000, v190
	v_sqrt_f32_e32 v169, v169
	s_nop 0
	v_mul_f32_e32 v166, v166, v169
	v_fmamk_f32 v169, v24, 0xbfb8aa3b, v140
	v_exp_f32_e32 v169, v169
	v_mul_f32_e32 v166, v166, v167
	v_lshlrev_b32_e32 v167, 16, v190
	v_add_f32_e32 v169, 1.0, v169
	v_rcp_f32_e32 v169, v169
	v_sqrt_f32_e32 v171, v171
	s_nop 0
	v_mul_f32_e32 v169, v169, v171
	v_max_f32_e32 v171, 0, v194
	v_mul_f32_e32 v167, v169, v167
	v_and_b32_e32 v169, 0xffff0000, v191
	v_sqrt_f32_e32 v171, v171
	s_nop 0
	v_mul_f32_e32 v165, v165, v171
	v_cvt_pk_bf16_f32 v171, v192, v193
	v_mul_f32_e32 v165, v165, v169
	global_store_dwordx2 v[214:215], v[170:171], off offset:128
	v_cvt_pk_bf16_f32 v170, v167, v166
	v_cvt_pk_bf16_f32 v171, v164, v165
	v_fmamk_f32 v164, v20, 0xbfb8aa3b, v148
	v_exp_f32_e32 v164, v164
	global_store_dwordx2 v[218:219], v[170:171], off offset:128
	v_add_f32_e32 v164, 1.0, v164
	v_rcp_f32_e32 v164, v164
	s_nop 0
	v_mul_f32_e32 v168, v144, v164
	v_add_f32_e32 v170, v168, v168
	v_mul_f32_e32 v247, 0x3fb8aa3b, v170
	v_exp_f32_e32 v247, v247
	v_fma_f32 v171, v170, s14, 0.5
	v_fma_f32 v171, v170, v171, 1.0
	v_cmp_nlt_f32_e32 vcc, s51, v170
	v_mul_f32_e64 v171, v171, -v170
	v_sub_f32_e32 v247, 1.0, v247
	v_cndmask_b32_e32 v171, v171, v247, vcc
	v_fmamk_f32 v164, v21, 0xbfb8aa3b, v149
	v_exp_f32_e32 v164, v164
	s_nop 0
	v_add_f32_e32 v164, 1.0, v164
	v_rcp_f32_e32 v164, v164
	s_nop 0
	v_mul_f32_e32 v170, v145, v164
	v_add_f32_e32 v190, v170, v170
	v_mul_f32_e32 v247, 0x3fb8aa3b, v190
	v_exp_f32_e32 v247, v247
	v_fma_f32 v193, v190, s14, 0.5
	v_fma_f32 v193, v190, v193, 1.0
	v_cmp_nlt_f32_e32 vcc, s51, v190
	v_mul_f32_e64 v193, v193, -v190
	v_sub_f32_e32 v247, 1.0, v247
	v_cndmask_b32_e32 v193, v193, v247, vcc
	v_fmamk_f32 v164, v22, 0xbfb8aa3b, v150
	v_exp_f32_e32 v164, v164
	s_nop 0
	v_add_f32_e32 v164, 1.0, v164
	v_rcp_f32_e32 v164, v164
	s_nop 0
	v_mul_f32_e32 v190, v146, v164
	v_add_f32_e32 v191, v190, v190
	v_mul_f32_e32 v247, 0x3fb8aa3b, v191
	v_exp_f32_e32 v247, v247
	v_fma_f32 v194, v191, s14, 0.5
	v_fma_f32 v194, v191, v194, 1.0
	v_cmp_nlt_f32_e32 vcc, s51, v191
	v_mul_f32_e64 v194, v194, -v191
	v_sub_f32_e32 v247, 1.0, v247
	v_cndmask_b32_e32 v194, v194, v247, vcc
	v_fmamk_f32 v164, v23, 0xbfb8aa3b, v151
	v_exp_f32_e32 v164, v164
	s_nop 0
	v_add_f32_e32 v164, 1.0, v164
	v_rcp_f32_e32 v164, v164
	s_nop 0
	v_mul_f32_e32 v191, v147, v164
	v_add_f32_e32 v195, v191, v191
	v_mul_f32_e32 v247, 0x3fb8aa3b, v195
	v_exp_f32_e32 v247, v247
	v_fma_f32 v192, v195, s14, 0.5
	v_fma_f32 v192, v195, v192, 1.0
	v_cmp_nlt_f32_e32 vcc, s51, v195
	v_mul_f32_e64 v192, v192, -v195
	v_sub_f32_e32 v247, 1.0, v247
	v_cndmask_b32_e32 v192, v192, v247, vcc
	v_fmamk_f32 v164, v18, 0xbfb8aa3b, v142
	v_exp_f32_e32 v164, v164
	v_max_f32_e32 v171, 0, v171
	v_cvt_pk_bf16_f32 v170, v168, v170
	v_add_f32_e32 v164, 1.0, v164
	v_max_f32_e32 v166, 0, v194
	v_rcp_f32_e32 v164, v164
	v_lshlrev_b32_e32 v165, 16, v189
	v_sqrt_f32_e32 v166, v166
	s_nop 0
	v_mul_f32_e32 v164, v164, v166
	v_mul_f32_e32 v164, v164, v165
	v_fmamk_f32 v165, v19, 0xbfb8aa3b, v143
	v_exp_f32_e32 v165, v165
	s_nop 0
	v_add_f32_e32 v165, 1.0, v165
	v_rcp_f32_e32 v165, v165
	v_fmamk_f32 v166, v17, 0xbfb8aa3b, v141
	v_exp_f32_e32 v166, v166
	s_nop 0
	v_add_f32_e32 v166, 1.0, v166
	v_max_f32_e32 v169, 0, v193
	v_rcp_f32_e32 v166, v166
	v_and_b32_e32 v167, 0xffff0000, v188
	v_sqrt_f32_e32 v169, v169
	s_nop 0
	v_mul_f32_e32 v166, v166, v169
	v_fmamk_f32 v169, v16, 0xbfb8aa3b, v140
	v_exp_f32_e32 v169, v169
	v_mul_f32_e32 v166, v166, v167
	v_lshlrev_b32_e32 v167, 16, v188
	v_add_f32_e32 v169, 1.0, v169
	v_rcp_f32_e32 v169, v169
	v_sqrt_f32_e32 v171, v171
	s_nop 0
	v_mul_f32_e32 v169, v169, v171
	v_max_f32_e32 v171, 0, v192
	v_mul_f32_e32 v167, v169, v167
	v_and_b32_e32 v169, 0xffff0000, v189
	v_sqrt_f32_e32 v171, v171
	s_nop 0
	v_mul_f32_e32 v165, v165, v171
	v_cvt_pk_bf16_f32 v171, v190, v191
	v_mul_f32_e32 v165, v165, v169
	global_store_dwordx2 v[212:213], v[170:171], off offset:128
	v_cvt_pk_bf16_f32 v170, v167, v166
	v_cvt_pk_bf16_f32 v171, v164, v165
	global_store_dwordx2 v[216:217], v[170:171], off offset:128
	v_lshl_add_u64 v[170:171], s[28:29], 0, v[220:221]
	v_lshl_add_u64 v[170:171], v[170:171], 0, v[232:233]
	global_load_dwordx2 v[190:191], v[170:171], off
	v_lshl_add_u64 v[170:171], s[28:29], 0, v[222:223]
	v_lshl_add_u64 v[170:171], v[170:171], 0, v[232:233]
	global_load_dwordx2 v[188:189], v[170:171], off
	v_fmamk_f32 v164, v12, 0xbfb8aa3b, v148
	v_exp_f32_e32 v164, v164
	s_nop 0
	v_add_f32_e32 v164, 1.0, v164
	v_rcp_f32_e32 v164, v164
	s_nop 0
	v_mul_f32_e32 v168, v144, v164
	v_add_f32_e32 v170, v168, v168
	v_mul_f32_e32 v247, 0x3fb8aa3b, v170
	v_exp_f32_e32 v247, v247
	v_fma_f32 v171, v170, s14, 0.5
	v_fma_f32 v171, v170, v171, 1.0
	v_cmp_nlt_f32_e32 vcc, s51, v170
	v_mul_f32_e64 v171, v171, -v170
	v_sub_f32_e32 v247, 1.0, v247
	v_cndmask_b32_e32 v171, v171, v247, vcc
	v_fmamk_f32 v164, v13, 0xbfb8aa3b, v149
	v_exp_f32_e32 v164, v164
	s_nop 0
	v_add_f32_e32 v164, 1.0, v164
	v_rcp_f32_e32 v164, v164
	s_nop 0
	v_mul_f32_e32 v170, v145, v164
	v_add_f32_e32 v192, v170, v170
	v_mul_f32_e32 v247, 0x3fb8aa3b, v192
	v_exp_f32_e32 v247, v247
	v_fma_f32 v195, v192, s14, 0.5
	v_fma_f32 v195, v192, v195, 1.0
	v_cmp_nlt_f32_e32 vcc, s51, v192
	v_mul_f32_e64 v195, v195, -v192
	v_sub_f32_e32 v247, 1.0, v247
	v_cndmask_b32_e32 v195, v195, v247, vcc
	v_fmamk_f32 v164, v14, 0xbfb8aa3b, v150
	v_exp_f32_e32 v164, v164
	s_nop 0
	v_add_f32_e32 v164, 1.0, v164
	v_rcp_f32_e32 v164, v164
	s_nop 0
	v_mul_f32_e32 v192, v146, v164
	v_add_f32_e32 v193, v192, v192
	v_mul_f32_e32 v247, 0x3fb8aa3b, v193
	v_exp_f32_e32 v247, v247
	v_fma_f32 v196, v193, s14, 0.5
	v_fma_f32 v196, v193, v196, 1.0
	v_cmp_nlt_f32_e32 vcc, s51, v193
	v_mul_f32_e64 v196, v196, -v193
	v_sub_f32_e32 v247, 1.0, v247
	v_cndmask_b32_e32 v196, v196, v247, vcc
	v_fmamk_f32 v164, v15, 0xbfb8aa3b, v151
	v_exp_f32_e32 v164, v164
	s_nop 0
	v_add_f32_e32 v164, 1.0, v164
	v_rcp_f32_e32 v164, v164
	s_nop 0
	v_mul_f32_e32 v193, v147, v164
	v_add_f32_e32 v197, v193, v193
	v_mul_f32_e32 v247, 0x3fb8aa3b, v197
	v_exp_f32_e32 v247, v247
	v_fma_f32 v194, v197, s14, 0.5
	v_fma_f32 v194, v197, v194, 1.0
	v_cmp_nlt_f32_e32 vcc, s51, v197
	v_mul_f32_e64 v194, v194, -v197
	v_sub_f32_e32 v247, 1.0, v247
	v_cndmask_b32_e32 v194, v194, v247, vcc
	v_fmamk_f32 v164, v10, 0xbfb8aa3b, v142
	v_exp_f32_e32 v164, v164
	v_max_f32_e32 v171, 0, v171
	v_add_f32_e32 v164, 1.0, v164
	v_fmamk_f32 v148, v4, 0xbfb8aa3b, v148
	v_exp_f32_e32 v148, v148
	v_cvt_pk_bf16_f32 v170, v168, v170
	v_max_f32_e32 v166, 0, v196
	v_rcp_f32_e32 v164, v164
	s_waitcnt vmcnt(0)
	v_lshlrev_b32_e32 v165, 16, v191
	v_sqrt_f32_e32 v166, v166
	v_add_f32_e32 v148, 1.0, v148
	v_mul_f32_e32 v164, v164, v166
	v_mul_f32_e32 v164, v164, v165
	v_fmamk_f32 v165, v11, 0xbfb8aa3b, v143
	v_exp_f32_e32 v165, v165
	s_nop 0
	v_add_f32_e32 v165, 1.0, v165
	v_rcp_f32_e32 v165, v165
	v_fmamk_f32 v166, v9, 0xbfb8aa3b, v141
	v_exp_f32_e32 v166, v166
	s_nop 0
	v_add_f32_e32 v166, 1.0, v166
	v_max_f32_e32 v169, 0, v195
	v_rcp_f32_e32 v166, v166
	v_and_b32_e32 v167, 0xffff0000, v190
	v_sqrt_f32_e32 v169, v169
	s_nop 0
	v_mul_f32_e32 v166, v166, v169
	v_fmamk_f32 v169, v8, 0xbfb8aa3b, v140
	v_exp_f32_e32 v169, v169
	v_mul_f32_e32 v166, v166, v167
	v_lshlrev_b32_e32 v167, 16, v190
	v_add_f32_e32 v169, 1.0, v169
	v_rcp_f32_e32 v169, v169
	v_sqrt_f32_e32 v171, v171
	s_nop 0
	v_mul_f32_e32 v169, v169, v171
	v_max_f32_e32 v171, 0, v194
	v_mul_f32_e32 v167, v169, v167
	v_and_b32_e32 v169, 0xffff0000, v191
	v_sqrt_f32_e32 v171, v171
	s_nop 0
	v_mul_f32_e32 v165, v165, v171
	v_cvt_pk_bf16_f32 v171, v192, v193
	v_mul_f32_e32 v165, v165, v169
	global_store_dwordx2 v[224:225], v[170:171], off offset:128
	v_cvt_pk_bf16_f32 v170, v167, v166
	v_cvt_pk_bf16_f32 v171, v164, v165
	global_store_dwordx2 v[226:227], v[170:171], off offset:128
	v_rcp_f32_e32 v148, v148
	s_nop 0
	v_mul_f32_e32 v144, v144, v148
	v_add_f32_e32 v168, v144, v144
	v_mul_f32_e32 v247, 0x3fb8aa3b, v168
	v_exp_f32_e32 v247, v247
	v_fma_f32 v148, v168, s14, 0.5
	v_fma_f32 v148, v168, v148, 1.0
	v_cmp_nlt_f32_e32 vcc, s51, v168
	v_mul_f32_e64 v148, v148, -v168
	v_sub_f32_e32 v247, 1.0, v247
	v_cndmask_b32_e32 v148, v148, v247, vcc
	v_fmamk_f32 v149, v5, 0xbfb8aa3b, v149
	v_exp_f32_e32 v149, v149
	s_nop 0
	v_add_f32_e32 v149, 1.0, v149
	v_rcp_f32_e32 v149, v149
	s_nop 0
	v_mul_f32_e32 v145, v145, v149
	v_add_f32_e32 v149, v145, v145
	v_mul_f32_e32 v247, 0x3fb8aa3b, v149
	v_exp_f32_e32 v247, v247
	v_fma_f32 v168, v149, s14, 0.5
	v_fma_f32 v168, v149, v168, 1.0
	v_cmp_nlt_f32_e32 vcc, s51, v149
	v_mul_f32_e64 v168, v168, -v149
	v_sub_f32_e32 v247, 1.0, v247
	v_cndmask_b32_e32 v168, v168, v247, vcc
	v_fmamk_f32 v149, v6, 0xbfb8aa3b, v150
	v_exp_f32_e32 v149, v149
	s_nop 0
	v_add_f32_e32 v149, 1.0, v149
	v_rcp_f32_e32 v149, v149
	s_nop 0
	v_mul_f32_e32 v146, v146, v149
	v_add_f32_e32 v149, v146, v146
	v_mul_f32_e32 v247, 0x3fb8aa3b, v149
	v_exp_f32_e32 v247, v247
	v_fma_f32 v150, v149, s14, 0.5
	v_fma_f32 v150, v149, v150, 1.0
	v_cmp_nlt_f32_e32 vcc, s51, v149
	v_mul_f32_e64 v150, v150, -v149
	v_sub_f32_e32 v247, 1.0, v247
	v_cndmask_b32_e32 v150, v150, v247, vcc
	v_fmamk_f32 v149, v7, 0xbfb8aa3b, v151
	v_exp_f32_e32 v149, v149
	s_nop 0
	v_add_f32_e32 v149, 1.0, v149
	v_rcp_f32_e32 v149, v149
	s_nop 0
	v_mul_f32_e32 v147, v147, v149
	v_add_f32_e32 v151, v147, v147
	v_mul_f32_e32 v247, 0x3fb8aa3b, v151
	v_exp_f32_e32 v247, v247
	v_fma_f32 v149, v151, s14, 0.5
	v_fma_f32 v149, v151, v149, 1.0
	v_cmp_nlt_f32_e32 vcc, s51, v151
	v_mul_f32_e64 v149, v149, -v151
	v_sub_f32_e32 v247, 1.0, v247
	v_cndmask_b32_e32 v149, v149, v247, vcc
	v_fmamk_f32 v143, v3, 0xbfb8aa3b, v143
	v_exp_f32_e32 v143, v143
	v_fmamk_f32 v142, v2, 0xbfb8aa3b, v142
	v_exp_f32_e32 v142, v142
	v_add_f32_e32 v143, 1.0, v143
	v_add_f32_e32 v142, 1.0, v142
	v_fmamk_f32 v141, v1, 0xbfb8aa3b, v141
	v_exp_f32_e32 v141, v141
	v_max_f32_e32 v150, 0, v150
	v_add_f32_e32 v141, 1.0, v141
	v_cmp_gt_f32_e32 vcc, s53, v150
	v_rcp_f32_e32 v142, v142
	s_nop 0
	v_cndmask_b32_e64 v164, 0, 32, vcc
	v_ldexp_f32 v150, v150, v164
	v_cndmask_b32_e64 v164, 0, -16, vcc
	v_rcp_f32_e32 v141, v141
	v_max_f32_e32 v165, 0, v168
	v_sqrt_f32_e32 v150, v150
	v_fmamk_f32 v140, v0, 0xbfb8aa3b, v140
	v_sqrt_f32_e32 v165, v165
	v_exp_f32_e32 v140, v140
	v_ldexp_f32 v150, v150, v164
	v_rcp_f32_e32 v143, v143
	v_lshlrev_b32_e32 v151, 16, v189
	v_mul_f32_e32 v142, v142, v150
	v_mul_f32_e32 v142, v142, v151
	v_and_b32_e32 v151, 0xffff0000, v188
	v_mul_f32_e32 v141, v141, v165
	v_add_f32_e32 v140, 1.0, v140
	v_mul_f32_e32 v151, v141, v151
	v_lshlrev_b32_e32 v150, 16, v188
	v_and_b32_e32 v164, 0xffff0000, v189
	s_mov_b64 s[0:1], 0
	v_rcp_f32_e32 v140, v140
	v_max_f32_e32 v141, 0, v148
	v_sqrt_f32_e32 v141, v141
	s_nop 0
	v_mul_f32_e32 v140, v140, v141
	v_mul_f32_e32 v148, v140, v150
	v_max_f32_e32 v140, 0, v149
	v_sqrt_f32_e32 v140, v140
	s_nop 0
	v_mul_f32_e32 v140, v143, v140
	v_mul_f32_e32 v143, v140, v164
	v_cvt_pk_bf16_f32 v140, v144, v145
	v_cvt_pk_bf16_f32 v141, v146, v147
	global_store_dwordx2 v[228:229], v[140:141], off offset:128
	v_cvt_pk_bf16_f32 v140, v148, v151
	v_cvt_pk_bf16_f32 v141, v142, v143
	global_store_dwordx2 v[230:231], v[140:141], off offset:128
.LBB0_712:
	s_and_b64 vcc, exec, s[0:1]
	s_cbranch_vccz .LBB0_447
	v_readlane_b32 s0, v253, 45
	v_readlane_b32 s1, v253, 46
	s_nop 1
	v_lshl_add_u64 v[140:141], v[180:181], 1, s[0:1]
	v_lshl_add_u64 v[142:143], v[140:141], 0, v[178:179]
	v_lshl_add_u64 v[146:147], v[140:141], 0, v[176:177]
	global_load_dwordx2 v[144:145], v[142:143], off
	s_nop 0
	global_load_dwordx2 v[142:143], v[146:147], off
	s_and_saveexec_b64 s[0:1], s[4:5]
	s_xor_b64 s[0:1], exec, s[0:1]
	v_mul_f32_e32 v146, 0x3fb8aa3b, v183
	v_exp_f32_e32 v146, v146
	s_nop 0
	v_sub_f32_e32 v146, 1.0, v146
	s_andn2_saveexec_b64 s[0:1], s[0:1]
	v_fma_f32 v146, v183, s14, 0.5
	v_fma_f32 v146, v183, v146, 1.0
	v_mul_f32_e64 v146, v146, -v183
	s_or_b64 exec, exec, s[0:1]
	v_fmamk_f32 v137, v137, 0xbfb8aa3b, v89
	v_exp_f32_e32 v137, v137
	s_nop 0
	v_add_f32_e32 v137, 1.0, v137
	v_rcp_f32_e32 v137, v137
	s_nop 0
	v_mul_f32_e32 v137, v85, v137
	v_add_f32_e32 v148, v137, v137
	v_mul_f32_e32 v247, 0x3fb8aa3b, v148
	v_exp_f32_e32 v247, v247
	v_fma_f32 v147, v148, s14, 0.5
	v_fma_f32 v147, v148, v147, 1.0
	v_cmp_nlt_f32_e32 vcc, s51, v148
	v_mul_f32_e64 v147, v147, -v148
	v_sub_f32_e32 v247, 1.0, v247
	v_cndmask_b32_e32 v147, v147, v247, vcc
	v_fmamk_f32 v138, v138, 0xbfb8aa3b, v90
	v_exp_f32_e32 v138, v138
	s_nop 0
	v_add_f32_e32 v138, 1.0, v138
	v_rcp_f32_e32 v138, v138
	s_nop 0
	v_mul_f32_e32 v138, v86, v138
	v_add_f32_e32 v148, v138, v138
	v_mul_f32_e32 v247, 0x3fb8aa3b, v148
	v_exp_f32_e32 v247, v247
	v_fma_f32 v149, v148, s14, 0.5
	v_fma_f32 v149, v148, v149, 1.0
	v_cmp_nlt_f32_e32 vcc, s51, v148
	v_mul_f32_e64 v149, v149, -v148
	v_sub_f32_e32 v247, 1.0, v247
	v_cndmask_b32_e32 v149, v149, v247, vcc
	v_fmamk_f32 v139, v139, 0xbfb8aa3b, v91
	v_exp_f32_e32 v139, v139
	s_nop 0
	v_add_f32_e32 v139, 1.0, v139
	v_rcp_f32_e32 v139, v139
	s_nop 0
	v_mul_f32_e32 v139, v87, v139
	v_add_f32_e32 v150, v139, v139
	v_mul_f32_e32 v247, 0x3fb8aa3b, v150
	v_exp_f32_e32 v247, v247
	v_fma_f32 v148, v150, s14, 0.5
	v_fma_f32 v148, v150, v148, 1.0
	v_cmp_nlt_f32_e32 vcc, s51, v150
	v_mul_f32_e64 v148, v148, -v150
	v_sub_f32_e32 v247, 1.0, v247
	v_cndmask_b32_e32 v148, v148, v247, vcc
	v_fmamk_f32 v134, v134, 0xbfb8aa3b, v78
	v_exp_f32_e32 v134, v134
	v_max_f32_e32 v149, 0, v149
	v_add_f32_e32 v134, 1.0, v134
	v_fmamk_f32 v133, v133, 0xbfb8aa3b, v77
	v_exp_f32_e32 v133, v133
	v_rcp_f32_e32 v134, v134
	s_waitcnt vmcnt(0)
	v_lshlrev_b32_e32 v150, 16, v145
	v_sqrt_f32_e32 v149, v149
	v_add_f32_e32 v133, 1.0, v133
	v_max_f32_e32 v147, 0, v147
	v_mul_f32_e32 v134, v134, v149
	v_mul_f32_e32 v149, v134, v150
	v_fmamk_f32 v134, v135, 0xbfb8aa3b, v79
	v_exp_f32_e32 v134, v134
	v_fmamk_f32 v128, v128, 0xbfb8aa3b, v88
	v_exp_f32_e32 v128, v128
	v_add_f32_e32 v134, 1.0, v134
	v_add_f32_e32 v128, 1.0, v128
	v_rcp_f32_e32 v134, v134
	s_lshl_b32 s0, s7, 21
	v_readlane_b32 s1, v251, 24
	s_add_u32 s4, s1, s0
	v_rcp_f32_e32 v133, v133
	v_and_b32_e32 v135, 0xffff0000, v144
	v_sqrt_f32_e32 v147, v147
	v_readlane_b32 s1, v251, 25
	s_addc_u32 s5, s1, 0
	v_mul_f32_e32 v133, v133, v147
	v_mul_f32_e32 v147, v133, v135
	v_max_f32_e32 v135, 0, v146
	v_lshlrev_b32_e32 v133, 16, v144
	v_readlane_b32 s1, v251, 26
	v_sqrt_f32_e32 v135, v135
	s_add_u32 s0, s1, s0
	v_readlane_b32 s1, v251, 27
	v_mul_f32_e32 v135, v136, v135
	v_mul_f32_e32 v144, v135, v133
	v_max_f32_e32 v135, 0, v148
	v_and_b32_e32 v133, 0xffff0000, v145
	s_addc_u32 s1, s1, 0
	v_sqrt_f32_e32 v135, v135
	s_nop 0
	v_mul_f32_e32 v134, v134, v135
	v_mul_f32_e32 v145, v134, v133
	v_lshl_add_u64 v[134:135], v[186:187], 0, v[180:181]
	v_lshlrev_b64 v[134:135], 1, v[134:135]
	v_cvt_pk_bf16_f32 v136, v132, v137
	v_lshl_add_u64 v[132:133], s[4:5], 0, v[134:135]
	v_cvt_pk_bf16_f32 v137, v138, v139
	global_store_dwordx2 v[132:133], v[136:137], off
	v_cvt_pk_bf16_f32 v136, v144, v147
	v_lshl_add_u64 v[134:135], s[0:1], 0, v[134:135]
	v_cvt_pk_bf16_f32 v137, v149, v145
	global_store_dwordx2 v[134:135], v[136:137], off
	v_rcp_f32_e32 v128, v128
	s_nop 0
	v_mul_f32_e32 v128, v84, v128
	v_add_f32_e32 v137, v128, v128
	v_mul_f32_e32 v247, 0x3fb8aa3b, v137
	v_exp_f32_e32 v247, v247
	v_fma_f32 v136, v137, s14, 0.5
	v_fma_f32 v136, v137, v136, 1.0
	v_cmp_nlt_f32_e32 vcc, s51, v137
	v_mul_f32_e64 v136, v136, -v137
	v_sub_f32_e32 v247, 1.0, v247
	v_cndmask_b32_e32 v136, v136, v247, vcc
	v_fmamk_f32 v129, v129, 0xbfb8aa3b, v89
	v_exp_f32_e32 v129, v129
	s_nop 0
	v_add_f32_e32 v129, 1.0, v129
	v_rcp_f32_e32 v129, v129
	s_nop 0
	v_mul_f32_e32 v129, v85, v129
	v_add_f32_e32 v137, v129, v129
	v_mul_f32_e32 v247, 0x3fb8aa3b, v137
	v_exp_f32_e32 v247, v247
	v_fma_f32 v138, v137, s14, 0.5
	v_fma_f32 v138, v137, v138, 1.0
	v_cmp_nlt_f32_e32 vcc, s51, v137
	v_mul_f32_e64 v138, v138, -v137
	v_sub_f32_e32 v247, 1.0, v247
	v_cndmask_b32_e32 v138, v138, v247, vcc
	v_fmamk_f32 v130, v130, 0xbfb8aa3b, v90
	v_exp_f32_e32 v130, v130
	s_nop 0
	v_add_f32_e32 v130, 1.0, v130
	v_rcp_f32_e32 v130, v130
	s_nop 0
	v_mul_f32_e32 v130, v86, v130
	v_add_f32_e32 v137, v130, v130
	v_mul_f32_e32 v247, 0x3fb8aa3b, v137
	v_exp_f32_e32 v247, v247
	v_fma_f32 v139, v137, s14, 0.5
	v_fma_f32 v139, v137, v139, 1.0
	v_cmp_nlt_f32_e32 vcc, s51, v137
	v_mul_f32_e64 v139, v139, -v137
	v_sub_f32_e32 v247, 1.0, v247
	v_cndmask_b32_e32 v139, v139, v247, vcc
	v_fmamk_f32 v131, v131, 0xbfb8aa3b, v91
	v_exp_f32_e32 v131, v131
	s_nop 0
	v_add_f32_e32 v131, 1.0, v131
	v_rcp_f32_e32 v131, v131
	s_nop 0
	v_mul_f32_e32 v131, v87, v131
	v_add_f32_e32 v144, v131, v131
	v_mul_f32_e32 v247, 0x3fb8aa3b, v144
	v_exp_f32_e32 v247, v247
	v_fma_f32 v137, v144, s14, 0.5
	v_fma_f32 v137, v144, v137, 1.0
	v_cmp_nlt_f32_e32 vcc, s51, v144
	v_mul_f32_e64 v137, v137, -v144
	v_sub_f32_e32 v247, 1.0, v247
	v_cndmask_b32_e32 v137, v137, v247, vcc
	v_fmamk_f32 v126, v126, 0xbfb8aa3b, v78
	v_exp_f32_e32 v126, v126
	v_max_f32_e32 v139, 0, v139
	v_add_f32_e32 v126, 1.0, v126
	v_fmamk_f32 v125, v125, 0xbfb8aa3b, v77
	v_exp_f32_e32 v125, v125
	v_rcp_f32_e32 v126, v126
	v_lshlrev_b32_e32 v144, 16, v143
	v_sqrt_f32_e32 v139, v139
	v_add_f32_e32 v125, 1.0, v125
	v_max_f32_e32 v138, 0, v138
	v_mul_f32_e32 v126, v126, v139
	v_mul_f32_e32 v139, v126, v144
	v_fmamk_f32 v126, v127, 0xbfb8aa3b, v79
	v_exp_f32_e32 v126, v126
	v_fmamk_f32 v124, v124, 0xbfb8aa3b, v76
	v_exp_f32_e32 v124, v124
	v_add_f32_e32 v126, 1.0, v126
	v_add_f32_e32 v124, 1.0, v124
	v_max_f32_e32 v137, 0, v137
	v_rcp_f32_e32 v126, v126
	v_fmamk_f32 v120, v120, 0xbfb8aa3b, v88
	v_exp_f32_e32 v120, v120
	v_rcp_f32_e32 v125, v125
	v_and_b32_e32 v127, 0xffff0000, v142
	v_sqrt_f32_e32 v138, v138
	v_add_f32_e32 v120, 1.0, v120
	v_mul_f32_e32 v125, v125, v138
	v_mul_f32_e32 v138, v125, v127
	v_lshlrev_b32_e32 v125, 16, v142
	v_rcp_f32_e32 v124, v124
	v_max_f32_e32 v127, 0, v136
	v_cmp_gt_f32_e32 vcc, s53, v127
	s_nop 0
	s_nop 0
	v_cndmask_b32_e64 v136, 0, 32, vcc
	v_ldexp_f32 v127, v127, v136
	v_cndmask_b32_e64 v136, 0, -16, vcc
	v_sqrt_f32_e32 v127, v127
	v_sqrt_f32_e32 v137, v137
	v_ldexp_f32 v127, v127, v136
	v_mul_f32_e32 v124, v124, v127
	v_mul_f32_e32 v136, v124, v125
	v_lshlrev_b64 v[124:125], 10, v[184:185]
	v_and_b32_e32 v127, 0xffff0000, v143
	v_mul_f32_e32 v126, v126, v137
	v_lshl_add_u64 v[124:125], v[124:125], 0, v[180:181]
	v_mul_f32_e32 v137, v126, v127
	v_cvt_pk_bf16_f32 v126, v128, v129
	v_lshlrev_b64 v[128:129], 1, v[124:125]
	v_or_b32_e32 v142, 32, v182
	v_cvt_pk_bf16_f32 v127, v130, v131
	v_lshl_add_u64 v[124:125], s[4:5], 0, v[128:129]
	v_ashrrev_i32_e32 v143, 31, v142
	global_store_dwordx2 v[124:125], v[126:127], off
	v_cvt_pk_bf16_f32 v130, v136, v138
	v_cvt_pk_bf16_f32 v131, v139, v137
	v_lshl_add_u64 v[126:127], s[0:1], 0, v[128:129]
	v_lshlrev_b64 v[128:129], 11, v[142:143]
	v_or_b32_e32 v136, 48, v182
	global_store_dwordx2 v[126:127], v[130:131], off
	v_lshl_add_u64 v[130:131], v[140:141], 0, v[128:129]
	v_ashrrev_i32_e32 v137, 31, v136
	global_load_dwordx2 v[144:145], v[130:131], off
	v_lshlrev_b64 v[130:131], 11, v[136:137]
	v_lshl_add_u64 v[138:139], v[140:141], 0, v[130:131]
	global_load_dwordx2 v[138:139], v[138:139], off
	v_rcp_f32_e32 v120, v120
	s_nop 0
	v_mul_f32_e32 v120, v84, v120
	v_add_f32_e32 v147, v120, v120
	v_mul_f32_e32 v247, 0x3fb8aa3b, v147
	v_exp_f32_e32 v247, v247
	v_fma_f32 v146, v147, s14, 0.5
	v_fma_f32 v146, v147, v146, 1.0
	v_cmp_nlt_f32_e32 vcc, s51, v147
	v_mul_f32_e64 v146, v146, -v147
	v_sub_f32_e32 v247, 1.0, v247
	v_cndmask_b32_e32 v146, v146, v247, vcc
	v_fmamk_f32 v121, v121, 0xbfb8aa3b, v89
	v_exp_f32_e32 v121, v121
	s_nop 0
	v_add_f32_e32 v121, 1.0, v121
	v_rcp_f32_e32 v121, v121
	s_nop 0
	v_mul_f32_e32 v121, v85, v121
	v_add_f32_e32 v147, v121, v121
	v_mul_f32_e32 v247, 0x3fb8aa3b, v147
	v_exp_f32_e32 v247, v247
	v_fma_f32 v148, v147, s14, 0.5
	v_fma_f32 v148, v147, v148, 1.0
	v_cmp_nlt_f32_e32 vcc, s51, v147
	v_mul_f32_e64 v148, v148, -v147
	v_sub_f32_e32 v247, 1.0, v247
	v_cndmask_b32_e32 v148, v148, v247, vcc
	v_fmamk_f32 v122, v122, 0xbfb8aa3b, v90
	v_exp_f32_e32 v122, v122
	s_nop 0
	v_add_f32_e32 v122, 1.0, v122
	v_rcp_f32_e32 v122, v122
	s_nop 0
	v_mul_f32_e32 v122, v86, v122
	v_add_f32_e32 v147, v122, v122
	v_mul_f32_e32 v247, 0x3fb8aa3b, v147
	v_exp_f32_e32 v247, v247
	v_fma_f32 v149, v147, s14, 0.5
	v_fma_f32 v149, v147, v149, 1.0
	v_cmp_nlt_f32_e32 vcc, s51, v147
	v_mul_f32_e64 v149, v149, -v147
	v_sub_f32_e32 v247, 1.0, v247
	v_cndmask_b32_e32 v149, v149, v247, vcc
	v_fmamk_f32 v123, v123, 0xbfb8aa3b, v91
	v_exp_f32_e32 v123, v123
	s_nop 0
	v_add_f32_e32 v123, 1.0, v123
	v_rcp_f32_e32 v123, v123
	s_nop 0
	v_mul_f32_e32 v123, v87, v123
	v_add_f32_e32 v150, v123, v123
	v_mul_f32_e32 v247, 0x3fb8aa3b, v150
	v_exp_f32_e32 v247, v247
	v_fma_f32 v147, v150, s14, 0.5
	v_fma_f32 v147, v150, v147, 1.0
	v_cmp_nlt_f32_e32 vcc, s51, v150
	v_mul_f32_e64 v147, v147, -v150
	v_sub_f32_e32 v247, 1.0, v247
	v_cndmask_b32_e32 v147, v147, v247, vcc
	v_fmamk_f32 v118, v118, 0xbfb8aa3b, v78
	v_exp_f32_e32 v118, v118
	v_max_f32_e32 v149, 0, v149
	v_add_f32_e32 v118, 1.0, v118
	v_fmamk_f32 v117, v117, 0xbfb8aa3b, v77
	v_exp_f32_e32 v117, v117
	v_rcp_f32_e32 v118, v118
	s_waitcnt vmcnt(0)
	v_lshlrev_b32_e32 v150, 16, v145
	v_sqrt_f32_e32 v149, v149
	v_add_f32_e32 v117, 1.0, v117
	v_max_f32_e32 v148, 0, v148
	v_mul_f32_e32 v118, v118, v149
	v_mul_f32_e32 v149, v118, v150
	v_fmamk_f32 v118, v119, 0xbfb8aa3b, v79
	v_exp_f32_e32 v118, v118
	v_fmamk_f32 v116, v116, 0xbfb8aa3b, v76
	v_exp_f32_e32 v116, v116
	v_add_f32_e32 v118, 1.0, v118
	v_add_f32_e32 v116, 1.0, v116
	v_fmamk_f32 v112, v112, 0xbfb8aa3b, v88
	v_rcp_f32_e32 v118, v118
	v_exp_f32_e32 v112, v112
	v_rcp_f32_e32 v117, v117
	v_and_b32_e32 v119, 0xffff0000, v144
	v_sqrt_f32_e32 v148, v148
	v_add_f32_e32 v112, 1.0, v112
	v_mul_f32_e32 v117, v117, v148
	v_mul_f32_e32 v148, v117, v119
	v_lshlrev_b32_e32 v117, 16, v144
	v_rcp_f32_e32 v116, v116
	v_max_f32_e32 v119, 0, v146
	v_sqrt_f32_e32 v119, v119
	s_nop 0
	v_mul_f32_e32 v116, v116, v119
	v_mul_f32_e32 v144, v116, v117
	v_lshlrev_b64 v[116:117], 10, v[142:143]
	v_max_f32_e32 v142, 0, v147
	v_and_b32_e32 v119, 0xffff0000, v145
	v_lshl_add_u64 v[116:117], v[116:117], 0, v[180:181]
	v_sqrt_f32_e32 v142, v142
	s_nop 0
	v_mul_f32_e32 v118, v118, v142
	v_mul_f32_e32 v142, v118, v119
	v_cvt_pk_bf16_f32 v118, v120, v121
	v_lshlrev_b64 v[120:121], 1, v[116:117]
	v_cvt_pk_bf16_f32 v119, v122, v123
	v_lshl_add_u64 v[116:117], s[4:5], 0, v[120:121]
	global_store_dwordx2 v[116:117], v[118:119], off
	v_lshl_add_u64 v[118:119], s[0:1], 0, v[120:121]
	v_cvt_pk_bf16_f32 v122, v144, v148
	v_cvt_pk_bf16_f32 v123, v149, v142
	global_store_dwordx2 v[118:119], v[122:123], off
	v_rcp_f32_e32 v112, v112
	s_nop 0
	v_mul_f32_e32 v112, v84, v112
	v_add_f32_e32 v121, v112, v112
	v_mul_f32_e32 v247, 0x3fb8aa3b, v121
	v_exp_f32_e32 v247, v247
	v_fma_f32 v120, v121, s14, 0.5
	v_fma_f32 v120, v121, v120, 1.0
	v_cmp_nlt_f32_e32 vcc, s51, v121
	v_mul_f32_e64 v120, v120, -v121
	v_sub_f32_e32 v247, 1.0, v247
	v_cndmask_b32_e32 v120, v120, v247, vcc
	v_fmamk_f32 v113, v113, 0xbfb8aa3b, v89
	v_exp_f32_e32 v113, v113
	s_nop 0
	v_add_f32_e32 v113, 1.0, v113
	v_rcp_f32_e32 v113, v113
	s_nop 0
	v_mul_f32_e32 v113, v85, v113
	v_add_f32_e32 v121, v113, v113
	v_mul_f32_e32 v247, 0x3fb8aa3b, v121
	v_exp_f32_e32 v247, v247
	v_fma_f32 v122, v121, s14, 0.5
	v_fma_f32 v122, v121, v122, 1.0
	v_cmp_nlt_f32_e32 vcc, s51, v121
	v_mul_f32_e64 v122, v122, -v121
	v_sub_f32_e32 v247, 1.0, v247
	v_cndmask_b32_e32 v122, v122, v247, vcc
	v_fmamk_f32 v114, v114, 0xbfb8aa3b, v90
	v_exp_f32_e32 v114, v114
	s_nop 0
	v_add_f32_e32 v114, 1.0, v114
	v_rcp_f32_e32 v114, v114
	s_nop 0
	v_mul_f32_e32 v114, v86, v114
	v_add_f32_e32 v121, v114, v114
	v_mul_f32_e32 v247, 0x3fb8aa3b, v121
	v_exp_f32_e32 v247, v247
	v_fma_f32 v123, v121, s14, 0.5
	v_fma_f32 v123, v121, v123, 1.0
	v_cmp_nlt_f32_e32 vcc, s51, v121
	v_mul_f32_e64 v123, v123, -v121
	v_sub_f32_e32 v247, 1.0, v247
	v_cndmask_b32_e32 v123, v123, v247, vcc
	v_fmamk_f32 v115, v115, 0xbfb8aa3b, v91
	v_exp_f32_e32 v115, v115
	s_nop 0
	v_add_f32_e32 v115, 1.0, v115
	v_rcp_f32_e32 v115, v115
	s_nop 0
	v_mul_f32_e32 v115, v87, v115
	v_add_f32_e32 v142, v115, v115
	v_mul_f32_e32 v247, 0x3fb8aa3b, v142
	v_exp_f32_e32 v247, v247
	v_fma_f32 v121, v142, s14, 0.5
	v_fma_f32 v121, v142, v121, 1.0
	v_cmp_nlt_f32_e32 vcc, s51, v142
	v_mul_f32_e64 v121, v121, -v142
	v_sub_f32_e32 v247, 1.0, v247
	v_cndmask_b32_e32 v121, v121, v247, vcc
	v_fmamk_f32 v110, v110, 0xbfb8aa3b, v78
	v_exp_f32_e32 v110, v110
	v_max_f32_e32 v123, 0, v123
	v_add_f32_e32 v110, 1.0, v110
	v_fmamk_f32 v109, v109, 0xbfb8aa3b, v77
	v_exp_f32_e32 v109, v109
	v_rcp_f32_e32 v110, v110
	v_lshlrev_b32_e32 v142, 16, v139
	v_sqrt_f32_e32 v123, v123
	v_add_f32_e32 v109, 1.0, v109
	v_max_f32_e32 v122, 0, v122
	v_mul_f32_e32 v110, v110, v123
	v_mul_f32_e32 v123, v110, v142
	v_fmamk_f32 v110, v111, 0xbfb8aa3b, v79
	v_exp_f32_e32 v110, v110
	v_fmamk_f32 v108, v108, 0xbfb8aa3b, v76
	v_exp_f32_e32 v108, v108
	v_add_f32_e32 v110, 1.0, v110
	v_add_f32_e32 v108, 1.0, v108
	v_max_f32_e32 v121, 0, v121
	v_rcp_f32_e32 v110, v110
	v_fmamk_f32 v104, v104, 0xbfb8aa3b, v88
	v_exp_f32_e32 v104, v104
	v_rcp_f32_e32 v109, v109
	v_and_b32_e32 v111, 0xffff0000, v138
	v_sqrt_f32_e32 v122, v122
	v_add_f32_e32 v104, 1.0, v104
	v_mul_f32_e32 v109, v109, v122
	v_mul_f32_e32 v122, v109, v111
	v_lshlrev_b32_e32 v109, 16, v138
	v_rcp_f32_e32 v108, v108
	v_max_f32_e32 v111, 0, v120
	v_sqrt_f32_e32 v111, v111
	s_nop 0
	v_mul_f32_e32 v108, v108, v111
	v_mul_f32_e32 v120, v108, v109
	v_lshlrev_b64 v[108:109], 10, v[136:137]
	v_sqrt_f32_e32 v121, v121
	v_and_b32_e32 v111, 0xffff0000, v139
	v_lshl_add_u64 v[108:109], v[108:109], 0, v[180:181]
	v_mul_f32_e32 v110, v110, v121
	v_mul_f32_e32 v121, v110, v111
	v_cvt_pk_bf16_f32 v110, v112, v113
	v_lshlrev_b64 v[112:113], 1, v[108:109]
	v_add_u32_e32 v136, 0x80, v182
	v_cvt_pk_bf16_f32 v111, v114, v115
	v_lshl_add_u64 v[108:109], s[4:5], 0, v[112:113]
	v_ashrrev_i32_e32 v137, 31, v136
	global_store_dwordx2 v[108:109], v[110:111], off
	v_cvt_pk_bf16_f32 v114, v120, v122
	v_cvt_pk_bf16_f32 v115, v123, v121
	v_lshl_add_u64 v[110:111], s[0:1], 0, v[112:113]
	v_lshlrev_b64 v[112:113], 11, v[136:137]
	v_add_u32_e32 v120, 0x90, v182
	global_store_dwordx2 v[110:111], v[114:115], off
	v_lshl_add_u64 v[114:115], v[140:141], 0, v[112:113]
	v_ashrrev_i32_e32 v121, 31, v120
	global_load_dwordx2 v[138:139], v[114:115], off
	v_lshlrev_b64 v[114:115], 11, v[120:121]
	v_lshl_add_u64 v[122:123], v[140:141], 0, v[114:115]
	global_load_dwordx2 v[122:123], v[122:123], off
	v_rcp_f32_e32 v104, v104
	s_nop 0
	v_mul_f32_e32 v104, v84, v104
	v_add_f32_e32 v143, v104, v104
	v_mul_f32_e32 v247, 0x3fb8aa3b, v143
	v_exp_f32_e32 v247, v247
	v_fma_f32 v142, v143, s14, 0.5
	v_fma_f32 v142, v143, v142, 1.0
	v_cmp_nlt_f32_e32 vcc, s51, v143
	v_mul_f32_e64 v142, v142, -v143
	v_sub_f32_e32 v247, 1.0, v247
	v_cndmask_b32_e32 v142, v142, v247, vcc
	v_fmamk_f32 v105, v105, 0xbfb8aa3b, v89
	v_exp_f32_e32 v105, v105
	s_nop 0
	v_add_f32_e32 v105, 1.0, v105
	v_rcp_f32_e32 v105, v105
	s_nop 0
	v_mul_f32_e32 v105, v85, v105
	v_add_f32_e32 v143, v105, v105
	v_mul_f32_e32 v247, 0x3fb8aa3b, v143
	v_exp_f32_e32 v247, v247
	v_fma_f32 v144, v143, s14, 0.5
	v_fma_f32 v144, v143, v144, 1.0
	v_cmp_nlt_f32_e32 vcc, s51, v143
	v_mul_f32_e64 v144, v144, -v143
	v_sub_f32_e32 v247, 1.0, v247
	v_cndmask_b32_e32 v144, v144, v247, vcc
	v_fmamk_f32 v106, v106, 0xbfb8aa3b, v90
	v_exp_f32_e32 v106, v106
	s_nop 0
	v_add_f32_e32 v106, 1.0, v106
	v_rcp_f32_e32 v106, v106
	s_nop 0
	v_mul_f32_e32 v106, v86, v106
	v_add_f32_e32 v143, v106, v106
	v_mul_f32_e32 v247, 0x3fb8aa3b, v143
	v_exp_f32_e32 v247, v247
	v_fma_f32 v145, v143, s14, 0.5
	v_fma_f32 v145, v143, v145, 1.0
	v_cmp_nlt_f32_e32 vcc, s51, v143
	v_mul_f32_e64 v145, v145, -v143
	v_sub_f32_e32 v247, 1.0, v247
	v_cndmask_b32_e32 v145, v145, v247, vcc
	v_fmamk_f32 v107, v107, 0xbfb8aa3b, v91
	v_exp_f32_e32 v107, v107
	s_nop 0
	v_add_f32_e32 v107, 1.0, v107
	v_rcp_f32_e32 v107, v107
	s_nop 0
	v_mul_f32_e32 v107, v87, v107
	v_add_f32_e32 v146, v107, v107
	v_mul_f32_e32 v247, 0x3fb8aa3b, v146
	v_exp_f32_e32 v247, v247
	v_fma_f32 v143, v146, s14, 0.5
	v_fma_f32 v143, v146, v143, 1.0
	v_cmp_nlt_f32_e32 vcc, s51, v146
	v_mul_f32_e64 v143, v143, -v146
	v_sub_f32_e32 v247, 1.0, v247
	v_cndmask_b32_e32 v143, v143, v247, vcc
	v_fmamk_f32 v102, v102, 0xbfb8aa3b, v78
	v_exp_f32_e32 v102, v102
	v_max_f32_e32 v145, 0, v145
	v_add_f32_e32 v102, 1.0, v102
	v_fmamk_f32 v101, v101, 0xbfb8aa3b, v77
	v_exp_f32_e32 v101, v101
	v_rcp_f32_e32 v102, v102
	s_waitcnt vmcnt(0)
	v_lshlrev_b32_e32 v146, 16, v139
	v_sqrt_f32_e32 v145, v145
	v_add_f32_e32 v101, 1.0, v101
	v_max_f32_e32 v144, 0, v144
	v_mul_f32_e32 v102, v102, v145
	v_mul_f32_e32 v145, v102, v146
	v_fmamk_f32 v102, v103, 0xbfb8aa3b, v79
	v_exp_f32_e32 v102, v102
	v_fmamk_f32 v100, v100, 0xbfb8aa3b, v76
	v_exp_f32_e32 v100, v100
	v_add_f32_e32 v102, 1.0, v102
	v_add_f32_e32 v100, 1.0, v100
	v_fmamk_f32 v96, v96, 0xbfb8aa3b, v88
	v_rcp_f32_e32 v102, v102
	v_exp_f32_e32 v96, v96
	v_rcp_f32_e32 v101, v101
	v_and_b32_e32 v103, 0xffff0000, v138
	v_sqrt_f32_e32 v144, v144
	v_add_f32_e32 v96, 1.0, v96
	v_mul_f32_e32 v101, v101, v144
	v_mul_f32_e32 v144, v101, v103
	v_lshlrev_b32_e32 v101, 16, v138
	v_rcp_f32_e32 v100, v100
	v_max_f32_e32 v103, 0, v142
	v_sqrt_f32_e32 v103, v103
	s_nop 0
	v_mul_f32_e32 v100, v100, v103
	v_mul_f32_e32 v138, v100, v101
	v_lshlrev_b64 v[100:101], 10, v[136:137]
	v_max_f32_e32 v136, 0, v143
	v_and_b32_e32 v103, 0xffff0000, v139
	v_lshl_add_u64 v[100:101], v[100:101], 0, v[180:181]
	v_sqrt_f32_e32 v136, v136
	s_nop 0
	v_mul_f32_e32 v102, v102, v136
	v_mul_f32_e32 v136, v102, v103
	v_cvt_pk_bf16_f32 v102, v104, v105
	v_lshlrev_b64 v[104:105], 1, v[100:101]
	v_cvt_pk_bf16_f32 v103, v106, v107
	v_lshl_add_u64 v[100:101], s[4:5], 0, v[104:105]
	global_store_dwordx2 v[100:101], v[102:103], off
	v_lshl_add_u64 v[102:103], s[0:1], 0, v[104:105]
	v_cvt_pk_bf16_f32 v106, v138, v144
	v_cvt_pk_bf16_f32 v107, v145, v136
	global_store_dwordx2 v[102:103], v[106:107], off
	v_rcp_f32_e32 v96, v96
	s_nop 0
	v_mul_f32_e32 v96, v84, v96
	v_add_f32_e32 v105, v96, v96
	v_mul_f32_e32 v247, 0x3fb8aa3b, v105
	v_exp_f32_e32 v247, v247
	v_fma_f32 v104, v105, s14, 0.5
	v_fma_f32 v104, v105, v104, 1.0
	v_cmp_nlt_f32_e32 vcc, s51, v105
	v_mul_f32_e64 v104, v104, -v105
	v_sub_f32_e32 v247, 1.0, v247
	v_cndmask_b32_e32 v104, v104, v247, vcc
	v_fmamk_f32 v97, v97, 0xbfb8aa3b, v89
	v_exp_f32_e32 v97, v97
	s_nop 0
	v_add_f32_e32 v97, 1.0, v97
	v_rcp_f32_e32 v97, v97
	s_nop 0
	v_mul_f32_e32 v97, v85, v97
	v_add_f32_e32 v105, v97, v97
	v_mul_f32_e32 v247, 0x3fb8aa3b, v105
	v_exp_f32_e32 v247, v247
	v_fma_f32 v106, v105, s14, 0.5
	v_fma_f32 v106, v105, v106, 1.0
	v_cmp_nlt_f32_e32 vcc, s51, v105
	v_mul_f32_e64 v106, v106, -v105
	v_sub_f32_e32 v247, 1.0, v247
	v_cndmask_b32_e32 v106, v106, v247, vcc
	v_fmamk_f32 v98, v98, 0xbfb8aa3b, v90
	v_exp_f32_e32 v98, v98
	s_nop 0
	v_add_f32_e32 v98, 1.0, v98
	v_rcp_f32_e32 v98, v98
	s_nop 0
	v_mul_f32_e32 v98, v86, v98
	v_add_f32_e32 v105, v98, v98
	v_mul_f32_e32 v247, 0x3fb8aa3b, v105
	v_exp_f32_e32 v247, v247
	v_fma_f32 v107, v105, s14, 0.5
	v_fma_f32 v107, v105, v107, 1.0
	v_cmp_nlt_f32_e32 vcc, s51, v105
	v_mul_f32_e64 v107, v107, -v105
	v_sub_f32_e32 v247, 1.0, v247
	v_cndmask_b32_e32 v107, v107, v247, vcc
	v_fmamk_f32 v99, v99, 0xbfb8aa3b, v91
	v_exp_f32_e32 v99, v99
	s_nop 0
	v_add_f32_e32 v99, 1.0, v99
	v_rcp_f32_e32 v99, v99
	s_nop 0
	v_mul_f32_e32 v99, v87, v99
	v_add_f32_e32 v136, v99, v99
	v_mul_f32_e32 v247, 0x3fb8aa3b, v136
	v_exp_f32_e32 v247, v247
	v_fma_f32 v105, v136, s14, 0.5
	v_fma_f32 v105, v136, v105, 1.0
	v_cmp_nlt_f32_e32 vcc, s51, v136
	v_mul_f32_e64 v105, v105, -v136
	v_sub_f32_e32 v247, 1.0, v247
	v_cndmask_b32_e32 v105, v105, v247, vcc
	v_fmamk_f32 v94, v94, 0xbfb8aa3b, v78
	v_exp_f32_e32 v94, v94
	v_max_f32_e32 v107, 0, v107
	v_add_f32_e32 v94, 1.0, v94
	v_fmamk_f32 v93, v93, 0xbfb8aa3b, v77
	v_exp_f32_e32 v93, v93
	v_rcp_f32_e32 v94, v94
	v_lshlrev_b32_e32 v136, 16, v123
	v_sqrt_f32_e32 v107, v107
	v_add_f32_e32 v93, 1.0, v93
	v_max_f32_e32 v106, 0, v106
	v_mul_f32_e32 v94, v94, v107
	v_mul_f32_e32 v107, v94, v136
	v_fmamk_f32 v94, v95, 0xbfb8aa3b, v79
	v_exp_f32_e32 v94, v94
	v_fmamk_f32 v92, v92, 0xbfb8aa3b, v76
	v_exp_f32_e32 v92, v92
	v_add_f32_e32 v94, 1.0, v94
	v_add_f32_e32 v92, 1.0, v92
	v_max_f32_e32 v105, 0, v105
	v_rcp_f32_e32 v94, v94
	v_fmamk_f32 v80, v80, 0xbfb8aa3b, v88
	v_exp_f32_e32 v80, v80
	v_rcp_f32_e32 v93, v93
	v_and_b32_e32 v95, 0xffff0000, v122
	v_sqrt_f32_e32 v106, v106
	v_add_f32_e32 v80, 1.0, v80
	v_mul_f32_e32 v93, v93, v106
	v_mul_f32_e32 v106, v93, v95
	v_lshlrev_b32_e32 v93, 16, v122
	v_rcp_f32_e32 v92, v92
	v_max_f32_e32 v95, 0, v104
	v_sqrt_f32_e32 v95, v95
	s_nop 0
	v_mul_f32_e32 v92, v92, v95
	v_mul_f32_e32 v104, v92, v93
	v_lshlrev_b64 v[92:93], 10, v[120:121]
	v_sqrt_f32_e32 v105, v105
	v_and_b32_e32 v95, 0xffff0000, v123
	v_lshl_add_u64 v[92:93], v[92:93], 0, v[180:181]
	v_mul_f32_e32 v94, v94, v105
	v_mul_f32_e32 v105, v94, v95
	v_cvt_pk_bf16_f32 v94, v96, v97
	v_lshlrev_b64 v[96:97], 1, v[92:93]
	v_add_u32_e32 v120, 0xa0, v182
	v_cvt_pk_bf16_f32 v95, v98, v99
	v_lshl_add_u64 v[92:93], s[4:5], 0, v[96:97]
	v_ashrrev_i32_e32 v121, 31, v120
	global_store_dwordx2 v[92:93], v[94:95], off
	v_cvt_pk_bf16_f32 v98, v104, v106
	v_cvt_pk_bf16_f32 v99, v107, v105
	v_lshl_add_u64 v[94:95], s[0:1], 0, v[96:97]
	v_lshlrev_b64 v[96:97], 11, v[120:121]
	v_add_u32_e32 v104, 0xb0, v182
	global_store_dwordx2 v[94:95], v[98:99], off
	v_lshl_add_u64 v[98:99], v[140:141], 0, v[96:97]
	v_ashrrev_i32_e32 v105, 31, v104
	global_load_dwordx2 v[122:123], v[98:99], off
	v_lshlrev_b64 v[98:99], 11, v[104:105]
	v_lshl_add_u64 v[106:107], v[140:141], 0, v[98:99]
	global_load_dwordx2 v[106:107], v[106:107], off
	v_rcp_f32_e32 v80, v80
	s_nop 0
	v_mul_f32_e32 v80, v84, v80
	v_add_f32_e32 v137, v80, v80
	v_mul_f32_e32 v247, 0x3fb8aa3b, v137
	v_exp_f32_e32 v247, v247
	v_fma_f32 v136, v137, s14, 0.5
	v_fma_f32 v136, v137, v136, 1.0
	v_cmp_nlt_f32_e32 vcc, s51, v137
	v_mul_f32_e64 v136, v136, -v137
	v_sub_f32_e32 v247, 1.0, v247
	v_cndmask_b32_e32 v136, v136, v247, vcc
	v_fmamk_f32 v81, v81, 0xbfb8aa3b, v89
	v_exp_f32_e32 v81, v81
	s_nop 0
	v_add_f32_e32 v81, 1.0, v81
	v_rcp_f32_e32 v81, v81
	s_nop 0
	v_mul_f32_e32 v81, v85, v81
	v_add_f32_e32 v137, v81, v81
	v_mul_f32_e32 v247, 0x3fb8aa3b, v137
	v_exp_f32_e32 v247, v247
	v_fma_f32 v138, v137, s14, 0.5
	v_fma_f32 v138, v137, v138, 1.0
	v_cmp_nlt_f32_e32 vcc, s51, v137
	v_mul_f32_e64 v138, v138, -v137
	v_sub_f32_e32 v247, 1.0, v247
	v_cndmask_b32_e32 v138, v138, v247, vcc
	v_fmamk_f32 v82, v82, 0xbfb8aa3b, v90
	v_exp_f32_e32 v82, v82
	s_nop 0
	v_add_f32_e32 v82, 1.0, v82
	v_rcp_f32_e32 v82, v82
	s_nop 0
	v_mul_f32_e32 v82, v86, v82
	v_add_f32_e32 v137, v82, v82
	v_mul_f32_e32 v247, 0x3fb8aa3b, v137
	v_exp_f32_e32 v247, v247
	v_fma_f32 v139, v137, s14, 0.5
	v_fma_f32 v139, v137, v139, 1.0
	v_cmp_nlt_f32_e32 vcc, s51, v137
	v_mul_f32_e64 v139, v139, -v137
	v_sub_f32_e32 v247, 1.0, v247
	v_cndmask_b32_e32 v139, v139, v247, vcc
	v_fmamk_f32 v83, v83, 0xbfb8aa3b, v91
	v_exp_f32_e32 v83, v83
	s_nop 0
	v_add_f32_e32 v83, 1.0, v83
	v_rcp_f32_e32 v83, v83
	s_nop 0
	v_mul_f32_e32 v83, v87, v83
	v_add_f32_e32 v140, v83, v83
	v_mul_f32_e32 v247, 0x3fb8aa3b, v140
	v_exp_f32_e32 v247, v247
	v_fma_f32 v137, v140, s14, 0.5
	v_fma_f32 v137, v140, v137, 1.0
	v_cmp_nlt_f32_e32 vcc, s51, v140
	v_mul_f32_e64 v137, v137, -v140
	v_sub_f32_e32 v247, 1.0, v247
	v_cndmask_b32_e32 v137, v137, v247, vcc
	v_fmamk_f32 v74, v74, 0xbfb8aa3b, v78
	v_exp_f32_e32 v74, v74
	v_max_f32_e32 v139, 0, v139
	v_add_f32_e32 v74, 1.0, v74
	v_fmamk_f32 v73, v73, 0xbfb8aa3b, v77
	v_exp_f32_e32 v73, v73
	v_rcp_f32_e32 v74, v74
	s_waitcnt vmcnt(0)
	v_lshlrev_b32_e32 v140, 16, v123
	v_sqrt_f32_e32 v139, v139
	v_add_f32_e32 v73, 1.0, v73
	v_max_f32_e32 v138, 0, v138
	v_mul_f32_e32 v74, v74, v139
	v_mul_f32_e32 v139, v74, v140
	v_fmamk_f32 v74, v75, 0xbfb8aa3b, v79
	v_exp_f32_e32 v74, v74
	v_fmamk_f32 v72, v72, 0xbfb8aa3b, v76
	v_exp_f32_e32 v72, v72
	v_add_f32_e32 v74, 1.0, v74
	v_add_f32_e32 v72, 1.0, v72
	v_fmamk_f32 v68, v68, 0xbfb8aa3b, v88
	v_rcp_f32_e32 v74, v74
	v_exp_f32_e32 v68, v68
	v_rcp_f32_e32 v73, v73
	v_and_b32_e32 v75, 0xffff0000, v122
	v_sqrt_f32_e32 v138, v138
	v_add_f32_e32 v68, 1.0, v68
	v_mul_f32_e32 v73, v73, v138
	v_mul_f32_e32 v138, v73, v75
	v_lshlrev_b32_e32 v73, 16, v122
	v_rcp_f32_e32 v72, v72
	v_max_f32_e32 v75, 0, v136
	v_sqrt_f32_e32 v75, v75
	s_nop 0
	v_mul_f32_e32 v72, v72, v75
	v_mul_f32_e32 v122, v72, v73
	v_lshlrev_b64 v[72:73], 10, v[120:121]
	v_max_f32_e32 v120, 0, v137
	v_lshl_add_u64 v[72:73], v[72:73], 0, v[180:181]
	v_and_b32_e32 v75, 0xffff0000, v123
	v_sqrt_f32_e32 v120, v120
	v_lshlrev_b64 v[72:73], 1, v[72:73]
	v_mul_f32_e32 v74, v74, v120
	v_mul_f32_e32 v120, v74, v75
	v_cvt_pk_bf16_f32 v74, v80, v81
	v_cvt_pk_bf16_f32 v75, v82, v83
	v_lshl_add_u64 v[80:81], s[4:5], 0, v[72:73]
	v_lshl_add_u64 v[82:83], s[0:1], 0, v[72:73]
	global_store_dwordx2 v[80:81], v[74:75], off
	v_cvt_pk_bf16_f32 v74, v122, v138
	v_cvt_pk_bf16_f32 v75, v139, v120
	global_store_dwordx2 v[82:83], v[74:75], off
	v_rcp_f32_e32 v68, v68
	s_nop 0
	v_mul_f32_e32 v68, v84, v68
	v_add_f32_e32 v73, v68, v68
	v_mul_f32_e32 v247, 0x3fb8aa3b, v73
	v_exp_f32_e32 v247, v247
	v_fma_f32 v72, v73, s14, 0.5
	v_fma_f32 v72, v73, v72, 1.0
	v_cmp_nlt_f32_e32 vcc, s51, v73
	v_mul_f32_e64 v72, v72, -v73
	v_sub_f32_e32 v247, 1.0, v247
	v_cndmask_b32_e32 v72, v72, v247, vcc
	v_fmamk_f32 v69, v69, 0xbfb8aa3b, v89
	v_exp_f32_e32 v69, v69
	s_nop 0
	v_add_f32_e32 v69, 1.0, v69
	v_rcp_f32_e32 v69, v69
	s_nop 0
	v_mul_f32_e32 v69, v85, v69
	v_add_f32_e32 v73, v69, v69
	v_mul_f32_e32 v247, 0x3fb8aa3b, v73
	v_exp_f32_e32 v247, v247
	v_fma_f32 v74, v73, s14, 0.5
	v_fma_f32 v74, v73, v74, 1.0
	v_cmp_nlt_f32_e32 vcc, s51, v73
	v_mul_f32_e64 v74, v74, -v73
	v_sub_f32_e32 v247, 1.0, v247
	v_cndmask_b32_e32 v74, v74, v247, vcc
	v_fmamk_f32 v70, v70, 0xbfb8aa3b, v90
	v_exp_f32_e32 v70, v70
	s_nop 0
	v_add_f32_e32 v70, 1.0, v70
	v_rcp_f32_e32 v70, v70
	s_nop 0
	v_mul_f32_e32 v70, v86, v70
	v_add_f32_e32 v73, v70, v70
	v_mul_f32_e32 v247, 0x3fb8aa3b, v73
	v_exp_f32_e32 v247, v247
	v_fma_f32 v75, v73, s14, 0.5
	v_fma_f32 v75, v73, v75, 1.0
	v_cmp_nlt_f32_e32 vcc, s51, v73
	v_mul_f32_e64 v75, v75, -v73
	v_sub_f32_e32 v247, 1.0, v247
	v_cndmask_b32_e32 v75, v75, v247, vcc
	v_fmamk_f32 v71, v71, 0xbfb8aa3b, v91
	v_exp_f32_e32 v71, v71
	s_nop 0
	v_add_f32_e32 v71, 1.0, v71
	v_rcp_f32_e32 v71, v71
	s_nop 0
	v_mul_f32_e32 v71, v87, v71
	v_add_f32_e32 v84, v71, v71
	v_mul_f32_e32 v247, 0x3fb8aa3b, v84
	v_exp_f32_e32 v247, v247
	v_fma_f32 v73, v84, s14, 0.5
	v_fma_f32 v73, v84, v73, 1.0
	v_cmp_nlt_f32_e32 vcc, s51, v84
	v_mul_f32_e64 v73, v73, -v84
	v_sub_f32_e32 v247, 1.0, v247
	v_cndmask_b32_e32 v73, v73, v247, vcc
	v_fmamk_f32 v66, v66, 0xbfb8aa3b, v78
	v_exp_f32_e32 v66, v66
	v_max_f32_e32 v75, 0, v75
	v_add_f32_e32 v66, 1.0, v66
	v_fmamk_f32 v65, v65, 0xbfb8aa3b, v77
	v_exp_f32_e32 v65, v65
	v_rcp_f32_e32 v66, v66
	v_lshlrev_b32_e32 v78, 16, v107
	v_sqrt_f32_e32 v75, v75
	v_add_f32_e32 v65, 1.0, v65
	v_max_f32_e32 v74, 0, v74
	v_mul_f32_e32 v66, v66, v75
	v_mul_f32_e32 v75, v66, v78
	v_fmamk_f32 v66, v67, 0xbfb8aa3b, v79
	v_exp_f32_e32 v66, v66
	v_fmamk_f32 v64, v64, 0xbfb8aa3b, v76
	v_exp_f32_e32 v64, v64
	v_add_f32_e32 v66, 1.0, v66
	v_add_f32_e32 v64, 1.0, v64
	v_max_f32_e32 v73, 0, v73
	v_rcp_f32_e32 v66, v66
	v_rcp_f32_e32 v65, v65
	v_and_b32_e32 v67, 0xffff0000, v106
	v_sqrt_f32_e32 v74, v74
	v_or_b32_e32 v84, 64, v180
	v_ashrrev_i32_e32 v85, 31, v84
	v_mul_f32_e32 v65, v65, v74
	v_mul_f32_e32 v74, v65, v67
	v_lshlrev_b32_e32 v65, 16, v106
	v_lshlrev_b64 v[84:85], 1, v[84:85]
	v_rcp_f32_e32 v64, v64
	v_max_f32_e32 v67, 0, v72
	v_sqrt_f32_e32 v67, v67
	v_sqrt_f32_e32 v73, v73
	v_mul_f32_e32 v64, v64, v67
	v_mul_f32_e32 v72, v64, v65
	v_lshlrev_b64 v[64:65], 10, v[104:105]
	v_lshl_add_u64 v[64:65], v[64:65], 0, v[180:181]
	v_and_b32_e32 v67, 0xffff0000, v107
	v_mul_f32_e32 v66, v66, v73
	v_lshlrev_b64 v[64:65], 1, v[64:65]
	v_mul_f32_e32 v73, v66, v67
	v_cvt_pk_bf16_f32 v66, v68, v69
	v_cvt_pk_bf16_f32 v67, v70, v71
	v_lshl_add_u64 v[76:77], s[4:5], 0, v[64:65]
	v_lshl_add_u64 v[78:79], s[0:1], 0, v[64:65]
	global_store_dwordx2 v[76:77], v[66:67], off
	v_cvt_pk_bf16_f32 v66, v72, v74
	v_cvt_pk_bf16_f32 v67, v75, v73
	global_store_dwordx2 v[78:79], v[66:67], off
	global_load_dwordx4 v[72:75], v[172:173], off offset:256
	s_nop 0
	global_load_dwordx4 v[64:67], v[158:159], off offset:256
	global_load_dwordx4 v[68:71], v[174:175], off offset:256
	v_readlane_b32 s0, v253, 45
	v_readlane_b32 s1, v253, 46
	s_waitcnt vmcnt(0)
	v_mul_f32_e32 v72, 0xbfb8aa3b, v72
	v_mul_f32_e32 v73, 0xbfb8aa3b, v73
	v_mul_f32_e32 v74, 0xbfb8aa3b, v74
	v_mul_f32_e32 v75, 0xbfb8aa3b, v75
	v_mul_f32_e32 v64, 0xbfb8aa3b, v64
	v_mul_f32_e32 v65, 0xbfb8aa3b, v65
	v_mul_f32_e32 v66, 0xbfb8aa3b, v66
	v_mul_f32_e32 v67, 0xbfb8aa3b, v67
	v_mul_f32_e32 v68, 0xc1000000, v68
	v_mul_f32_e32 v69, 0xc1000000, v69
	v_mul_f32_e32 v70, 0xc1000000, v70
	v_mul_f32_e32 v71, 0xc1000000, v71
	v_lshl_add_u64 v[86:87], s[0:1], 0, v[178:179]
	v_lshl_add_u64 v[86:87], v[86:87], 0, v[84:85]
	global_load_dwordx2 v[88:89], v[86:87], off
	v_lshl_add_u64 v[86:87], s[0:1], 0, v[176:177]
	v_lshl_add_u64 v[86:87], v[86:87], 0, v[84:85]
	global_load_dwordx2 v[86:87], v[86:87], off
	v_fmamk_f32 v60, v60, 0xbfb8aa3b, v72
	v_exp_f32_e32 v60, v60
	s_nop 0
	v_add_f32_e32 v60, 1.0, v60
	v_rcp_f32_e32 v60, v60
	s_nop 0
	v_mul_f32_e32 v60, v68, v60
	v_add_f32_e32 v91, v60, v60
	v_mul_f32_e32 v247, 0x3fb8aa3b, v91
	v_exp_f32_e32 v247, v247
	v_fma_f32 v90, v91, s14, 0.5
	v_fma_f32 v90, v91, v90, 1.0
	v_cmp_nlt_f32_e32 vcc, s51, v91
	v_mul_f32_e64 v90, v90, -v91
	v_sub_f32_e32 v247, 1.0, v247
	v_cndmask_b32_e32 v90, v90, v247, vcc
	v_fmamk_f32 v61, v61, 0xbfb8aa3b, v73
	v_exp_f32_e32 v61, v61
	s_nop 0
	v_add_f32_e32 v61, 1.0, v61
	v_rcp_f32_e32 v61, v61
	s_nop 0
	v_mul_f32_e32 v61, v69, v61
	v_add_f32_e32 v91, v61, v61
	v_mul_f32_e32 v247, 0x3fb8aa3b, v91
	v_exp_f32_e32 v247, v247
	v_fma_f32 v104, v91, s14, 0.5
	v_fma_f32 v104, v91, v104, 1.0
	v_cmp_nlt_f32_e32 vcc, s51, v91
	v_mul_f32_e64 v104, v104, -v91
	v_sub_f32_e32 v247, 1.0, v247
	v_cndmask_b32_e32 v104, v104, v247, vcc
	v_fmamk_f32 v62, v62, 0xbfb8aa3b, v74
	v_exp_f32_e32 v62, v62
	s_nop 0
	v_add_f32_e32 v62, 1.0, v62
	v_rcp_f32_e32 v62, v62
	s_nop 0
	v_mul_f32_e32 v62, v70, v62
	v_add_f32_e32 v91, v62, v62
	v_mul_f32_e32 v247, 0x3fb8aa3b, v91
	v_exp_f32_e32 v247, v247
	v_fma_f32 v105, v91, s14, 0.5
	v_fma_f32 v105, v91, v105, 1.0
	v_cmp_nlt_f32_e32 vcc, s51, v91
	v_mul_f32_e64 v105, v105, -v91
	v_sub_f32_e32 v247, 1.0, v247
	v_cndmask_b32_e32 v105, v105, v247, vcc
	v_fmamk_f32 v63, v63, 0xbfb8aa3b, v75
	v_exp_f32_e32 v63, v63
	s_nop 0
	v_add_f32_e32 v63, 1.0, v63
	v_rcp_f32_e32 v63, v63
	s_nop 0
	v_mul_f32_e32 v63, v71, v63
	v_add_f32_e32 v106, v63, v63
	v_mul_f32_e32 v247, 0x3fb8aa3b, v106
	v_exp_f32_e32 v247, v247
	v_fma_f32 v91, v106, s14, 0.5
	v_fma_f32 v91, v106, v91, 1.0
	v_cmp_nlt_f32_e32 vcc, s51, v106
	v_mul_f32_e64 v91, v91, -v106
	v_sub_f32_e32 v247, 1.0, v247
	v_cndmask_b32_e32 v91, v91, v247, vcc
	v_fmamk_f32 v58, v58, 0xbfb8aa3b, v66
	v_exp_f32_e32 v58, v58
	v_max_f32_e32 v105, 0, v105
	v_add_f32_e32 v58, 1.0, v58
	v_fmamk_f32 v59, v59, 0xbfb8aa3b, v67
	v_exp_f32_e32 v59, v59
	v_rcp_f32_e32 v58, v58
	v_add_f32_e32 v59, 1.0, v59
	v_sqrt_f32_e32 v105, v105
	s_waitcnt vmcnt(0)
	v_lshlrev_b32_e32 v106, 16, v89
	v_fmamk_f32 v57, v57, 0xbfb8aa3b, v65
	v_mul_f32_e32 v58, v58, v105
	v_mul_f32_e32 v58, v58, v106
	v_exp_f32_e32 v57, v57
	v_max_f32_e32 v104, 0, v104
	v_add_f32_e32 v57, 1.0, v57
	v_rcp_f32_e32 v59, v59
	v_fmamk_f32 v56, v56, 0xbfb8aa3b, v64
	v_exp_f32_e32 v56, v56
	v_rcp_f32_e32 v57, v57
	v_and_b32_e32 v105, 0xffff0000, v88
	v_sqrt_f32_e32 v104, v104
	v_add_f32_e32 v56, 1.0, v56
	v_mul_f32_e32 v57, v57, v104
	v_mul_f32_e32 v104, v57, v105
	v_lshlrev_b32_e32 v57, 16, v88
	v_fmamk_f32 v52, v52, 0xbfb8aa3b, v72
	v_exp_f32_e32 v52, v52
	v_rcp_f32_e32 v56, v56
	v_max_f32_e32 v88, 0, v90
	v_add_f32_e32 v52, 1.0, v52
	v_sqrt_f32_e32 v88, v88
	s_nop 0
	v_mul_f32_e32 v56, v56, v88
	v_mul_f32_e32 v88, v56, v57
	v_max_f32_e32 v57, 0, v91
	v_and_b32_e32 v56, 0xffff0000, v89
	v_sqrt_f32_e32 v57, v57
	s_nop 0
	v_mul_f32_e32 v57, v59, v57
	v_mul_f32_e32 v59, v57, v56
	v_cvt_pk_bf16_f32 v56, v60, v61
	v_cvt_pk_bf16_f32 v57, v62, v63
	global_store_dwordx2 v[132:133], v[56:57], off offset:128
	v_cvt_pk_bf16_f32 v56, v88, v104
	v_cvt_pk_bf16_f32 v57, v58, v59
	global_store_dwordx2 v[134:135], v[56:57], off offset:128
	v_rcp_f32_e32 v52, v52
	s_nop 0
	v_mul_f32_e32 v52, v68, v52
	v_add_f32_e32 v57, v52, v52
	v_mul_f32_e32 v247, 0x3fb8aa3b, v57
	v_exp_f32_e32 v247, v247
	v_fma_f32 v56, v57, s14, 0.5
	v_fma_f32 v56, v57, v56, 1.0
	v_cmp_nlt_f32_e32 vcc, s51, v57
	v_mul_f32_e64 v56, v56, -v57
	v_sub_f32_e32 v247, 1.0, v247
	v_cndmask_b32_e32 v56, v56, v247, vcc
	v_fmamk_f32 v53, v53, 0xbfb8aa3b, v73
	v_exp_f32_e32 v53, v53
	s_nop 0
	v_add_f32_e32 v53, 1.0, v53
	v_rcp_f32_e32 v53, v53
	s_nop 0
	v_mul_f32_e32 v53, v69, v53
	v_add_f32_e32 v57, v53, v53
	v_mul_f32_e32 v247, 0x3fb8aa3b, v57
	v_exp_f32_e32 v247, v247
	v_fma_f32 v58, v57, s14, 0.5
	v_fma_f32 v58, v57, v58, 1.0
	v_cmp_nlt_f32_e32 vcc, s51, v57
	v_mul_f32_e64 v58, v58, -v57
	v_sub_f32_e32 v247, 1.0, v247
	v_cndmask_b32_e32 v58, v58, v247, vcc
	v_fmamk_f32 v54, v54, 0xbfb8aa3b, v74
	v_exp_f32_e32 v54, v54
	s_nop 0
	v_add_f32_e32 v54, 1.0, v54
	v_rcp_f32_e32 v54, v54
	s_nop 0
	v_mul_f32_e32 v54, v70, v54
	v_add_f32_e32 v57, v54, v54
	v_mul_f32_e32 v247, 0x3fb8aa3b, v57
	v_exp_f32_e32 v247, v247
	v_fma_f32 v59, v57, s14, 0.5
	v_fma_f32 v59, v57, v59, 1.0
	v_cmp_nlt_f32_e32 vcc, s51, v57
	v_mul_f32_e64 v59, v59, -v57
	v_sub_f32_e32 v247, 1.0, v247
	v_cndmask_b32_e32 v59, v59, v247, vcc
	v_fmamk_f32 v55, v55, 0xbfb8aa3b, v75
	v_exp_f32_e32 v55, v55
	s_nop 0
	v_add_f32_e32 v55, 1.0, v55
	v_rcp_f32_e32 v55, v55
	s_nop 0
	v_mul_f32_e32 v55, v71, v55
	v_add_f32_e32 v60, v55, v55
	v_mul_f32_e32 v247, 0x3fb8aa3b, v60
	v_exp_f32_e32 v247, v247
	v_fma_f32 v57, v60, s14, 0.5
	v_fma_f32 v57, v60, v57, 1.0
	v_cmp_nlt_f32_e32 vcc, s51, v60
	v_mul_f32_e64 v57, v57, -v60
	v_sub_f32_e32 v247, 1.0, v247
	v_cndmask_b32_e32 v57, v57, v247, vcc
	v_fmamk_f32 v50, v50, 0xbfb8aa3b, v66
	v_exp_f32_e32 v50, v50
	v_max_f32_e32 v59, 0, v59
	v_add_f32_e32 v50, 1.0, v50
	v_fmamk_f32 v51, v51, 0xbfb8aa3b, v67
	v_exp_f32_e32 v51, v51
	v_rcp_f32_e32 v50, v50
	v_add_f32_e32 v51, 1.0, v51
	v_sqrt_f32_e32 v59, v59
	v_lshlrev_b32_e32 v60, 16, v87
	v_fmamk_f32 v49, v49, 0xbfb8aa3b, v65
	v_mul_f32_e32 v50, v50, v59
	v_mul_f32_e32 v50, v50, v60
	v_exp_f32_e32 v49, v49
	v_max_f32_e32 v58, 0, v58
	v_add_f32_e32 v49, 1.0, v49
	v_rcp_f32_e32 v51, v51
	v_fmamk_f32 v48, v48, 0xbfb8aa3b, v64
	v_exp_f32_e32 v48, v48
	v_rcp_f32_e32 v49, v49
	v_and_b32_e32 v59, 0xffff0000, v86
	v_sqrt_f32_e32 v58, v58
	v_add_f32_e32 v48, 1.0, v48
	v_mul_f32_e32 v49, v49, v58
	v_mul_f32_e32 v58, v49, v59
	v_max_f32_e32 v56, 0, v56
	v_lshlrev_b32_e32 v49, 16, v86
	v_readlane_b32 s0, v253, 45
	v_rcp_f32_e32 v48, v48
	v_readlane_b32 s1, v253, 46
	v_sqrt_f32_e32 v56, v56
	v_fmamk_f32 v44, v44, 0xbfb8aa3b, v72
	v_mul_f32_e32 v48, v48, v56
	v_mul_f32_e32 v56, v48, v49
	v_max_f32_e32 v49, 0, v57
	v_and_b32_e32 v48, 0xffff0000, v87
	v_exp_f32_e32 v44, v44
	v_sqrt_f32_e32 v49, v49
	v_add_f32_e32 v44, 1.0, v44
	v_mul_f32_e32 v49, v51, v49
	v_mul_f32_e32 v51, v49, v48
	v_cvt_pk_bf16_f32 v48, v52, v53
	v_cvt_pk_bf16_f32 v49, v54, v55
	global_store_dwordx2 v[124:125], v[48:49], off offset:128
	v_cvt_pk_bf16_f32 v48, v56, v58
	v_cvt_pk_bf16_f32 v49, v50, v51
	global_store_dwordx2 v[126:127], v[48:49], off offset:128
	v_lshl_add_u64 v[48:49], s[0:1], 0, v[128:129]
	v_lshl_add_u64 v[48:49], v[48:49], 0, v[84:85]
	global_load_dwordx2 v[50:51], v[48:49], off
	v_lshl_add_u64 v[48:49], s[0:1], 0, v[130:131]
	v_lshl_add_u64 v[48:49], v[48:49], 0, v[84:85]
	global_load_dwordx2 v[48:49], v[48:49], off
	v_rcp_f32_e32 v44, v44
	s_nop 0
	v_mul_f32_e32 v44, v68, v44
	v_add_f32_e32 v53, v44, v44
	v_mul_f32_e32 v247, 0x3fb8aa3b, v53
	v_exp_f32_e32 v247, v247
	v_fma_f32 v52, v53, s14, 0.5
	v_fma_f32 v52, v53, v52, 1.0
	v_cmp_nlt_f32_e32 vcc, s51, v53
	v_mul_f32_e64 v52, v52, -v53
	v_sub_f32_e32 v247, 1.0, v247
	v_cndmask_b32_e32 v52, v52, v247, vcc
	v_fmamk_f32 v45, v45, 0xbfb8aa3b, v73
	v_exp_f32_e32 v45, v45
	s_nop 0
	v_add_f32_e32 v45, 1.0, v45
	v_rcp_f32_e32 v45, v45
	s_nop 0
	v_mul_f32_e32 v45, v69, v45
	v_add_f32_e32 v53, v45, v45
	v_mul_f32_e32 v247, 0x3fb8aa3b, v53
	v_exp_f32_e32 v247, v247
	v_fma_f32 v54, v53, s14, 0.5
	v_fma_f32 v54, v53, v54, 1.0
	v_cmp_nlt_f32_e32 vcc, s51, v53
	v_mul_f32_e64 v54, v54, -v53
	v_sub_f32_e32 v247, 1.0, v247
	v_cndmask_b32_e32 v54, v54, v247, vcc
	v_fmamk_f32 v46, v46, 0xbfb8aa3b, v74
	v_exp_f32_e32 v46, v46
	s_nop 0
	v_add_f32_e32 v46, 1.0, v46
	v_rcp_f32_e32 v46, v46
	s_nop 0
	v_mul_f32_e32 v46, v70, v46
	v_add_f32_e32 v53, v46, v46
	v_mul_f32_e32 v247, 0x3fb8aa3b, v53
	v_exp_f32_e32 v247, v247
	v_fma_f32 v55, v53, s14, 0.5
	v_fma_f32 v55, v53, v55, 1.0
	v_cmp_nlt_f32_e32 vcc, s51, v53
	v_mul_f32_e64 v55, v55, -v53
	v_sub_f32_e32 v247, 1.0, v247
	v_cndmask_b32_e32 v55, v55, v247, vcc
	v_fmamk_f32 v47, v47, 0xbfb8aa3b, v75
	v_exp_f32_e32 v47, v47
	s_nop 0
	v_add_f32_e32 v47, 1.0, v47
	v_rcp_f32_e32 v47, v47
	s_nop 0
	v_mul_f32_e32 v47, v71, v47
	v_add_f32_e32 v56, v47, v47
	v_mul_f32_e32 v247, 0x3fb8aa3b, v56
	v_exp_f32_e32 v247, v247
	v_fma_f32 v53, v56, s14, 0.5
	v_fma_f32 v53, v56, v53, 1.0
	v_cmp_nlt_f32_e32 vcc, s51, v56
	v_mul_f32_e64 v53, v53, -v56
	v_sub_f32_e32 v247, 1.0, v247
	v_cndmask_b32_e32 v53, v53, v247, vcc
	v_fmamk_f32 v42, v42, 0xbfb8aa3b, v66
	v_exp_f32_e32 v42, v42
	v_max_f32_e32 v55, 0, v55
	v_add_f32_e32 v42, 1.0, v42
	v_fmamk_f32 v43, v43, 0xbfb8aa3b, v67
	v_exp_f32_e32 v43, v43
	v_rcp_f32_e32 v42, v42
	v_add_f32_e32 v43, 1.0, v43
	v_sqrt_f32_e32 v55, v55
	s_waitcnt vmcnt(0)
	v_lshlrev_b32_e32 v56, 16, v51
	v_fmamk_f32 v41, v41, 0xbfb8aa3b, v65
	v_mul_f32_e32 v42, v42, v55
	v_mul_f32_e32 v42, v42, v56
	v_exp_f32_e32 v41, v41
	v_max_f32_e32 v54, 0, v54
	v_add_f32_e32 v41, 1.0, v41
	v_rcp_f32_e32 v43, v43
	v_fmamk_f32 v40, v40, 0xbfb8aa3b, v64
	v_exp_f32_e32 v40, v40
	v_rcp_f32_e32 v41, v41
	v_and_b32_e32 v55, 0xffff0000, v50
	v_sqrt_f32_e32 v54, v54
	v_add_f32_e32 v40, 1.0, v40
	v_mul_f32_e32 v41, v41, v54
	v_mul_f32_e32 v54, v41, v55
	v_lshlrev_b32_e32 v41, 16, v50
	v_fmamk_f32 v36, v36, 0xbfb8aa3b, v72
	v_exp_f32_e32 v36, v36
	v_rcp_f32_e32 v40, v40
	v_max_f32_e32 v50, 0, v52
	v_add_f32_e32 v36, 1.0, v36
	v_sqrt_f32_e32 v50, v50
	s_nop 0
	v_mul_f32_e32 v40, v40, v50
	v_mul_f32_e32 v50, v40, v41
	v_max_f32_e32 v41, 0, v53
	v_and_b32_e32 v40, 0xffff0000, v51
	v_sqrt_f32_e32 v41, v41
	s_nop 0
	v_mul_f32_e32 v41, v43, v41
	v_mul_f32_e32 v43, v41, v40
	v_cvt_pk_bf16_f32 v40, v44, v45
	v_cvt_pk_bf16_f32 v41, v46, v47
	global_store_dwordx2 v[116:117], v[40:41], off offset:128
	v_cvt_pk_bf16_f32 v40, v50, v54
	v_cvt_pk_bf16_f32 v41, v42, v43
	global_store_dwordx2 v[118:119], v[40:41], off offset:128
	v_rcp_f32_e32 v36, v36
	s_nop 0
	v_mul_f32_e32 v36, v68, v36
	v_add_f32_e32 v41, v36, v36
	v_mul_f32_e32 v247, 0x3fb8aa3b, v41
	v_exp_f32_e32 v247, v247
	v_fma_f32 v40, v41, s14, 0.5
	v_fma_f32 v40, v41, v40, 1.0
	v_cmp_nlt_f32_e32 vcc, s51, v41
	v_mul_f32_e64 v40, v40, -v41
	v_sub_f32_e32 v247, 1.0, v247
	v_cndmask_b32_e32 v40, v40, v247, vcc
	v_fmamk_f32 v37, v37, 0xbfb8aa3b, v73
	v_exp_f32_e32 v37, v37
	s_nop 0
	v_add_f32_e32 v37, 1.0, v37
	v_rcp_f32_e32 v37, v37
	s_nop 0
	v_mul_f32_e32 v37, v69, v37
	v_add_f32_e32 v41, v37, v37
	v_mul_f32_e32 v247, 0x3fb8aa3b, v41
	v_exp_f32_e32 v247, v247
	v_fma_f32 v42, v41, s14, 0.5
	v_fma_f32 v42, v41, v42, 1.0
	v_cmp_nlt_f32_e32 vcc, s51, v41
	v_mul_f32_e64 v42, v42, -v41
	v_sub_f32_e32 v247, 1.0, v247
	v_cndmask_b32_e32 v42, v42, v247, vcc
	v_fmamk_f32 v38, v38, 0xbfb8aa3b, v74
	v_exp_f32_e32 v38, v38
	s_nop 0
	v_add_f32_e32 v38, 1.0, v38
	v_rcp_f32_e32 v38, v38
	s_nop 0
	v_mul_f32_e32 v38, v70, v38
	v_add_f32_e32 v41, v38, v38
	v_mul_f32_e32 v247, 0x3fb8aa3b, v41
	v_exp_f32_e32 v247, v247
	v_fma_f32 v43, v41, s14, 0.5
	v_fma_f32 v43, v41, v43, 1.0
	v_cmp_nlt_f32_e32 vcc, s51, v41
	v_mul_f32_e64 v43, v43, -v41
	v_sub_f32_e32 v247, 1.0, v247
	v_cndmask_b32_e32 v43, v43, v247, vcc
	v_fmamk_f32 v39, v39, 0xbfb8aa3b, v75
	v_exp_f32_e32 v39, v39
	s_nop 0
	v_add_f32_e32 v39, 1.0, v39
	v_rcp_f32_e32 v39, v39
	s_nop 0
	v_mul_f32_e32 v39, v71, v39
	v_add_f32_e32 v44, v39, v39
	v_mul_f32_e32 v247, 0x3fb8aa3b, v44
	v_exp_f32_e32 v247, v247
	v_fma_f32 v41, v44, s14, 0.5
	v_fma_f32 v41, v44, v41, 1.0
	v_cmp_nlt_f32_e32 vcc, s51, v44
	v_mul_f32_e64 v41, v41, -v44
	v_sub_f32_e32 v247, 1.0, v247
	v_cndmask_b32_e32 v41, v41, v247, vcc
	v_fmamk_f32 v34, v34, 0xbfb8aa3b, v66
	v_exp_f32_e32 v34, v34
	v_max_f32_e32 v43, 0, v43
	v_add_f32_e32 v34, 1.0, v34
	v_fmamk_f32 v35, v35, 0xbfb8aa3b, v67
	v_exp_f32_e32 v35, v35
	v_rcp_f32_e32 v34, v34
	v_add_f32_e32 v35, 1.0, v35
	v_sqrt_f32_e32 v43, v43
	v_lshlrev_b32_e32 v44, 16, v49
	v_fmamk_f32 v33, v33, 0xbfb8aa3b, v65
	v_mul_f32_e32 v34, v34, v43
	v_mul_f32_e32 v34, v34, v44
	v_exp_f32_e32 v33, v33
	v_max_f32_e32 v42, 0, v42
	v_add_f32_e32 v33, 1.0, v33
	v_rcp_f32_e32 v35, v35
	v_fmamk_f32 v32, v32, 0xbfb8aa3b, v64
	v_exp_f32_e32 v32, v32
	v_rcp_f32_e32 v33, v33
	v_and_b32_e32 v43, 0xffff0000, v48
	v_sqrt_f32_e32 v42, v42
	v_add_f32_e32 v32, 1.0, v32
	v_mul_f32_e32 v33, v33, v42
	v_mul_f32_e32 v42, v33, v43
	v_max_f32_e32 v40, 0, v40
	v_lshlrev_b32_e32 v33, 16, v48
	v_readlane_b32 s0, v253, 45
	v_rcp_f32_e32 v32, v32
	v_readlane_b32 s1, v253, 46
	v_sqrt_f32_e32 v40, v40
	v_fmamk_f32 v28, v28, 0xbfb8aa3b, v72
	v_mul_f32_e32 v32, v32, v40
	v_mul_f32_e32 v40, v32, v33
	v_max_f32_e32 v33, 0, v41
	v_and_b32_e32 v32, 0xffff0000, v49
	v_exp_f32_e32 v28, v28
	v_sqrt_f32_e32 v33, v33
	v_add_f32_e32 v28, 1.0, v28
	v_mul_f32_e32 v33, v35, v33
	v_mul_f32_e32 v35, v33, v32
	v_cvt_pk_bf16_f32 v32, v36, v37
	v_cvt_pk_bf16_f32 v33, v38, v39
	global_store_dwordx2 v[108:109], v[32:33], off offset:128
	v_cvt_pk_bf16_f32 v32, v40, v42
	v_cvt_pk_bf16_f32 v33, v34, v35
	global_store_dwordx2 v[110:111], v[32:33], off offset:128
	v_lshl_add_u64 v[32:33], s[0:1], 0, v[112:113]
	v_lshl_add_u64 v[32:33], v[32:33], 0, v[84:85]
	global_load_dwordx2 v[34:35], v[32:33], off
	v_lshl_add_u64 v[32:33], s[0:1], 0, v[114:115]
	v_lshl_add_u64 v[32:33], v[32:33], 0, v[84:85]
	global_load_dwordx2 v[32:33], v[32:33], off
	v_rcp_f32_e32 v28, v28
	s_nop 0
	v_mul_f32_e32 v28, v68, v28
	v_add_f32_e32 v37, v28, v28
	v_mul_f32_e32 v247, 0x3fb8aa3b, v37
	v_exp_f32_e32 v247, v247
	v_fma_f32 v36, v37, s14, 0.5
	v_fma_f32 v36, v37, v36, 1.0
	v_cmp_nlt_f32_e32 vcc, s51, v37
	v_mul_f32_e64 v36, v36, -v37
	v_sub_f32_e32 v247, 1.0, v247
	v_cndmask_b32_e32 v36, v36, v247, vcc
	v_fmamk_f32 v29, v29, 0xbfb8aa3b, v73
	v_exp_f32_e32 v29, v29
	s_nop 0
	v_add_f32_e32 v29, 1.0, v29
	v_rcp_f32_e32 v29, v29
	s_nop 0
	v_mul_f32_e32 v29, v69, v29
	v_add_f32_e32 v37, v29, v29
	v_mul_f32_e32 v247, 0x3fb8aa3b, v37
	v_exp_f32_e32 v247, v247
	v_fma_f32 v38, v37, s14, 0.5
	v_fma_f32 v38, v37, v38, 1.0
	v_cmp_nlt_f32_e32 vcc, s51, v37
	v_mul_f32_e64 v38, v38, -v37
	v_sub_f32_e32 v247, 1.0, v247
	v_cndmask_b32_e32 v38, v38, v247, vcc
	v_fmamk_f32 v30, v30, 0xbfb8aa3b, v74
	v_exp_f32_e32 v30, v30
	s_nop 0
	v_add_f32_e32 v30, 1.0, v30
	v_rcp_f32_e32 v30, v30
	s_nop 0
	v_mul_f32_e32 v30, v70, v30
	v_add_f32_e32 v37, v30, v30
	v_mul_f32_e32 v247, 0x3fb8aa3b, v37
	v_exp_f32_e32 v247, v247
	v_fma_f32 v39, v37, s14, 0.5
	v_fma_f32 v39, v37, v39, 1.0
	v_cmp_nlt_f32_e32 vcc, s51, v37
	v_mul_f32_e64 v39, v39, -v37
	v_sub_f32_e32 v247, 1.0, v247
	v_cndmask_b32_e32 v39, v39, v247, vcc
	v_fmamk_f32 v31, v31, 0xbfb8aa3b, v75
	v_exp_f32_e32 v31, v31
	s_nop 0
	v_add_f32_e32 v31, 1.0, v31
	v_rcp_f32_e32 v31, v31
	s_nop 0
	v_mul_f32_e32 v31, v71, v31
	v_add_f32_e32 v40, v31, v31
	v_mul_f32_e32 v247, 0x3fb8aa3b, v40
	v_exp_f32_e32 v247, v247
	v_fma_f32 v37, v40, s14, 0.5
	v_fma_f32 v37, v40, v37, 1.0
	v_cmp_nlt_f32_e32 vcc, s51, v40
	v_mul_f32_e64 v37, v37, -v40
	v_sub_f32_e32 v247, 1.0, v247
	v_cndmask_b32_e32 v37, v37, v247, vcc
	v_fmamk_f32 v26, v26, 0xbfb8aa3b, v66
	v_exp_f32_e32 v26, v26
	v_max_f32_e32 v39, 0, v39
	v_add_f32_e32 v26, 1.0, v26
	v_fmamk_f32 v27, v27, 0xbfb8aa3b, v67
	v_exp_f32_e32 v27, v27
	v_rcp_f32_e32 v26, v26
	v_add_f32_e32 v27, 1.0, v27
	v_sqrt_f32_e32 v39, v39
	s_waitcnt vmcnt(0)
	v_lshlrev_b32_e32 v40, 16, v35
	v_fmamk_f32 v25, v25, 0xbfb8aa3b, v65
	v_mul_f32_e32 v26, v26, v39
	v_mul_f32_e32 v26, v26, v40
	v_exp_f32_e32 v25, v25
	v_max_f32_e32 v38, 0, v38
	v_add_f32_e32 v25, 1.0, v25
	v_rcp_f32_e32 v27, v27
	v_fmamk_f32 v24, v24, 0xbfb8aa3b, v64
	v_exp_f32_e32 v24, v24
	v_rcp_f32_e32 v25, v25
	v_and_b32_e32 v39, 0xffff0000, v34
	v_sqrt_f32_e32 v38, v38
	v_add_f32_e32 v24, 1.0, v24
	v_mul_f32_e32 v25, v25, v38
	v_mul_f32_e32 v38, v25, v39
	v_lshlrev_b32_e32 v25, 16, v34
	v_fmamk_f32 v20, v20, 0xbfb8aa3b, v72
	v_exp_f32_e32 v20, v20
	v_rcp_f32_e32 v24, v24
	v_max_f32_e32 v34, 0, v36
	v_add_f32_e32 v20, 1.0, v20
	v_sqrt_f32_e32 v34, v34
	s_nop 0
	v_mul_f32_e32 v24, v24, v34
	v_mul_f32_e32 v34, v24, v25
	v_max_f32_e32 v25, 0, v37
	v_and_b32_e32 v24, 0xffff0000, v35
	v_sqrt_f32_e32 v25, v25
	s_nop 0
	v_mul_f32_e32 v25, v27, v25
	v_mul_f32_e32 v27, v25, v24
	v_cvt_pk_bf16_f32 v24, v28, v29
	v_cvt_pk_bf16_f32 v25, v30, v31
	global_store_dwordx2 v[100:101], v[24:25], off offset:128
	v_cvt_pk_bf16_f32 v24, v34, v38
	v_cvt_pk_bf16_f32 v25, v26, v27
	global_store_dwordx2 v[102:103], v[24:25], off offset:128
	v_rcp_f32_e32 v20, v20
	s_nop 0
	v_mul_f32_e32 v20, v68, v20
	v_add_f32_e32 v25, v20, v20
	v_mul_f32_e32 v247, 0x3fb8aa3b, v25
	v_exp_f32_e32 v247, v247
	v_fma_f32 v24, v25, s14, 0.5
	v_fma_f32 v24, v25, v24, 1.0
	v_cmp_nlt_f32_e32 vcc, s51, v25
	v_mul_f32_e64 v24, v24, -v25
	v_sub_f32_e32 v247, 1.0, v247
	v_cndmask_b32_e32 v24, v24, v247, vcc
	v_fmamk_f32 v21, v21, 0xbfb8aa3b, v73
	v_exp_f32_e32 v21, v21
	s_nop 0
	v_add_f32_e32 v21, 1.0, v21
	v_rcp_f32_e32 v21, v21
	s_nop 0
	v_mul_f32_e32 v21, v69, v21
	v_add_f32_e32 v25, v21, v21
	v_mul_f32_e32 v247, 0x3fb8aa3b, v25
	v_exp_f32_e32 v247, v247
	v_fma_f32 v26, v25, s14, 0.5
	v_fma_f32 v26, v25, v26, 1.0
	v_cmp_nlt_f32_e32 vcc, s51, v25
	v_mul_f32_e64 v26, v26, -v25
	v_sub_f32_e32 v247, 1.0, v247
	v_cndmask_b32_e32 v26, v26, v247, vcc
	v_fmamk_f32 v22, v22, 0xbfb8aa3b, v74
	v_exp_f32_e32 v22, v22
	s_nop 0
	v_add_f32_e32 v22, 1.0, v22
	v_rcp_f32_e32 v22, v22
	s_nop 0
	v_mul_f32_e32 v22, v70, v22
	v_add_f32_e32 v25, v22, v22
	v_mul_f32_e32 v247, 0x3fb8aa3b, v25
	v_exp_f32_e32 v247, v247
	v_fma_f32 v27, v25, s14, 0.5
	v_fma_f32 v27, v25, v27, 1.0
	v_cmp_nlt_f32_e32 vcc, s51, v25
	v_mul_f32_e64 v27, v27, -v25
	v_sub_f32_e32 v247, 1.0, v247
	v_cndmask_b32_e32 v27, v27, v247, vcc
	v_fmamk_f32 v23, v23, 0xbfb8aa3b, v75
	v_exp_f32_e32 v23, v23
	s_nop 0
	v_add_f32_e32 v23, 1.0, v23
	v_rcp_f32_e32 v23, v23
	s_nop 0
	v_mul_f32_e32 v23, v71, v23
	v_add_f32_e32 v28, v23, v23
	v_mul_f32_e32 v247, 0x3fb8aa3b, v28
	v_exp_f32_e32 v247, v247
	v_fma_f32 v25, v28, s14, 0.5
	v_fma_f32 v25, v28, v25, 1.0
	v_cmp_nlt_f32_e32 vcc, s51, v28
	v_mul_f32_e64 v25, v25, -v28
	v_sub_f32_e32 v247, 1.0, v247
	v_cndmask_b32_e32 v25, v25, v247, vcc
	v_fmamk_f32 v18, v18, 0xbfb8aa3b, v66
	v_exp_f32_e32 v18, v18
	v_max_f32_e32 v27, 0, v27
	v_add_f32_e32 v18, 1.0, v18
	v_fmamk_f32 v19, v19, 0xbfb8aa3b, v67
	v_exp_f32_e32 v19, v19
	v_rcp_f32_e32 v18, v18
	v_add_f32_e32 v19, 1.0, v19
	v_sqrt_f32_e32 v27, v27
	v_lshlrev_b32_e32 v28, 16, v33
	v_fmamk_f32 v17, v17, 0xbfb8aa3b, v65
	v_mul_f32_e32 v18, v18, v27
	v_mul_f32_e32 v18, v18, v28
	v_exp_f32_e32 v17, v17
	v_max_f32_e32 v26, 0, v26
	v_add_f32_e32 v17, 1.0, v17
	v_rcp_f32_e32 v19, v19
	v_fmamk_f32 v16, v16, 0xbfb8aa3b, v64
	v_exp_f32_e32 v16, v16
	v_rcp_f32_e32 v17, v17
	v_and_b32_e32 v27, 0xffff0000, v32
	v_sqrt_f32_e32 v26, v26
	v_add_f32_e32 v16, 1.0, v16
	v_mul_f32_e32 v17, v17, v26
	v_mul_f32_e32 v26, v17, v27
	v_max_f32_e32 v24, 0, v24
	v_lshlrev_b32_e32 v17, 16, v32
	v_readlane_b32 s0, v253, 45
	v_rcp_f32_e32 v16, v16
	v_readlane_b32 s1, v253, 46
	v_sqrt_f32_e32 v24, v24
	v_fmamk_f32 v12, v12, 0xbfb8aa3b, v72
	v_mul_f32_e32 v16, v16, v24
	v_mul_f32_e32 v24, v16, v17
	v_max_f32_e32 v17, 0, v25
	v_and_b32_e32 v16, 0xffff0000, v33
	v_exp_f32_e32 v12, v12
	v_sqrt_f32_e32 v17, v17
	v_add_f32_e32 v12, 1.0, v12
	v_mul_f32_e32 v17, v19, v17
	v_mul_f32_e32 v19, v17, v16
	v_cvt_pk_bf16_f32 v16, v20, v21
	v_cvt_pk_bf16_f32 v17, v22, v23
	global_store_dwordx2 v[92:93], v[16:17], off offset:128
	v_cvt_pk_bf16_f32 v16, v24, v26
	v_cvt_pk_bf16_f32 v17, v18, v19
	global_store_dwordx2 v[94:95], v[16:17], off offset:128
	v_lshl_add_u64 v[16:17], s[0:1], 0, v[96:97]
	v_lshl_add_u64 v[16:17], v[16:17], 0, v[84:85]
	global_load_dwordx2 v[18:19], v[16:17], off
	v_lshl_add_u64 v[16:17], s[0:1], 0, v[98:99]
	v_lshl_add_u64 v[16:17], v[16:17], 0, v[84:85]
	global_load_dwordx2 v[16:17], v[16:17], off
	v_rcp_f32_e32 v12, v12
	s_nop 0
	v_mul_f32_e32 v12, v68, v12
	v_add_f32_e32 v21, v12, v12
	v_mul_f32_e32 v247, 0x3fb8aa3b, v21
	v_exp_f32_e32 v247, v247
	v_fma_f32 v20, v21, s14, 0.5
	v_fma_f32 v20, v21, v20, 1.0
	v_cmp_nlt_f32_e32 vcc, s51, v21
	v_mul_f32_e64 v20, v20, -v21
	v_sub_f32_e32 v247, 1.0, v247
	v_cndmask_b32_e32 v20, v20, v247, vcc
	v_fmamk_f32 v13, v13, 0xbfb8aa3b, v73
	v_exp_f32_e32 v13, v13
	s_nop 0
	v_add_f32_e32 v13, 1.0, v13
	v_rcp_f32_e32 v13, v13
	s_nop 0
	v_mul_f32_e32 v13, v69, v13
	v_add_f32_e32 v21, v13, v13
	v_mul_f32_e32 v247, 0x3fb8aa3b, v21
	v_exp_f32_e32 v247, v247
	v_fma_f32 v22, v21, s14, 0.5
	v_fma_f32 v22, v21, v22, 1.0
	v_cmp_nlt_f32_e32 vcc, s51, v21
	v_mul_f32_e64 v22, v22, -v21
	v_sub_f32_e32 v247, 1.0, v247
	v_cndmask_b32_e32 v22, v22, v247, vcc
	v_fmamk_f32 v14, v14, 0xbfb8aa3b, v74
	v_exp_f32_e32 v14, v14
	s_nop 0
	v_add_f32_e32 v14, 1.0, v14
	v_rcp_f32_e32 v14, v14
	s_nop 0
	v_mul_f32_e32 v14, v70, v14
	v_add_f32_e32 v21, v14, v14
	v_mul_f32_e32 v247, 0x3fb8aa3b, v21
	v_exp_f32_e32 v247, v247
	v_fma_f32 v23, v21, s14, 0.5
	v_fma_f32 v23, v21, v23, 1.0
	v_cmp_nlt_f32_e32 vcc, s51, v21
	v_mul_f32_e64 v23, v23, -v21
	v_sub_f32_e32 v247, 1.0, v247
	v_cndmask_b32_e32 v23, v23, v247, vcc
	v_fmamk_f32 v15, v15, 0xbfb8aa3b, v75
	v_exp_f32_e32 v15, v15
	s_nop 0
	v_add_f32_e32 v15, 1.0, v15
	v_rcp_f32_e32 v15, v15
	s_nop 0
	v_mul_f32_e32 v15, v71, v15
	v_add_f32_e32 v24, v15, v15
	v_mul_f32_e32 v247, 0x3fb8aa3b, v24
	v_exp_f32_e32 v247, v247
	v_fma_f32 v21, v24, s14, 0.5
	v_fma_f32 v21, v24, v21, 1.0
	v_cmp_nlt_f32_e32 vcc, s51, v24
	v_mul_f32_e64 v21, v21, -v24
	v_sub_f32_e32 v247, 1.0, v247
	v_cndmask_b32_e32 v21, v21, v247, vcc
	v_fmamk_f32 v10, v10, 0xbfb8aa3b, v66
	v_exp_f32_e32 v10, v10
	v_max_f32_e32 v23, 0, v23
	v_add_f32_e32 v10, 1.0, v10
	v_fmamk_f32 v11, v11, 0xbfb8aa3b, v67
	v_exp_f32_e32 v11, v11
	v_rcp_f32_e32 v10, v10
	v_add_f32_e32 v11, 1.0, v11
	v_sqrt_f32_e32 v23, v23
	s_waitcnt vmcnt(0)
	v_lshlrev_b32_e32 v24, 16, v19
	v_fmamk_f32 v9, v9, 0xbfb8aa3b, v65
	v_mul_f32_e32 v10, v10, v23
	v_mul_f32_e32 v10, v10, v24
	v_exp_f32_e32 v9, v9
	v_max_f32_e32 v22, 0, v22
	v_add_f32_e32 v9, 1.0, v9
	v_rcp_f32_e32 v11, v11
	v_fmamk_f32 v8, v8, 0xbfb8aa3b, v64
	v_exp_f32_e32 v8, v8
	v_rcp_f32_e32 v9, v9
	v_and_b32_e32 v23, 0xffff0000, v18
	v_sqrt_f32_e32 v22, v22
	v_add_f32_e32 v8, 1.0, v8
	v_mul_f32_e32 v9, v9, v22
	v_mul_f32_e32 v22, v9, v23
	v_lshlrev_b32_e32 v9, 16, v18
	v_fmamk_f32 v4, v4, 0xbfb8aa3b, v72
	v_exp_f32_e32 v4, v4
	v_rcp_f32_e32 v8, v8
	v_max_f32_e32 v18, 0, v20
	v_add_f32_e32 v4, 1.0, v4
	v_sqrt_f32_e32 v18, v18
	s_nop 0
	v_mul_f32_e32 v8, v8, v18
	v_mul_f32_e32 v18, v8, v9
	v_max_f32_e32 v9, 0, v21
	v_and_b32_e32 v8, 0xffff0000, v19
	v_sqrt_f32_e32 v9, v9
	s_nop 0
	v_mul_f32_e32 v9, v11, v9
	v_mul_f32_e32 v11, v9, v8
	v_cvt_pk_bf16_f32 v8, v12, v13
	v_cvt_pk_bf16_f32 v9, v14, v15
	global_store_dwordx2 v[80:81], v[8:9], off offset:128
	v_cvt_pk_bf16_f32 v8, v18, v22
	v_cvt_pk_bf16_f32 v9, v10, v11
	global_store_dwordx2 v[82:83], v[8:9], off offset:128
	v_rcp_f32_e32 v4, v4
	s_nop 0
	v_mul_f32_e32 v4, v68, v4
	v_add_f32_e32 v9, v4, v4
	v_mul_f32_e32 v247, 0x3fb8aa3b, v9
	v_exp_f32_e32 v247, v247
	v_fma_f32 v8, v9, s14, 0.5
	v_fma_f32 v8, v9, v8, 1.0
	v_cmp_nlt_f32_e32 vcc, s51, v9
	v_mul_f32_e64 v8, v8, -v9
	v_sub_f32_e32 v247, 1.0, v247
	v_cndmask_b32_e32 v8, v8, v247, vcc
	v_fmamk_f32 v5, v5, 0xbfb8aa3b, v73
	v_exp_f32_e32 v5, v5
	s_nop 0
	v_add_f32_e32 v5, 1.0, v5
	v_rcp_f32_e32 v5, v5
	s_nop 0
	v_mul_f32_e32 v5, v69, v5
	v_add_f32_e32 v9, v5, v5
	v_mul_f32_e32 v247, 0x3fb8aa3b, v9
	v_exp_f32_e32 v247, v247
	v_fma_f32 v10, v9, s14, 0.5
	v_fma_f32 v10, v9, v10, 1.0
	v_cmp_nlt_f32_e32 vcc, s51, v9
	v_mul_f32_e64 v10, v10, -v9
	v_sub_f32_e32 v247, 1.0, v247
	v_cndmask_b32_e32 v10, v10, v247, vcc
	v_fmamk_f32 v6, v6, 0xbfb8aa3b, v74
	v_exp_f32_e32 v6, v6
	s_nop 0
	v_add_f32_e32 v6, 1.0, v6
	v_rcp_f32_e32 v6, v6
	s_nop 0
	v_mul_f32_e32 v6, v70, v6
	v_add_f32_e32 v9, v6, v6
	v_mul_f32_e32 v247, 0x3fb8aa3b, v9
	v_exp_f32_e32 v247, v247
	v_fma_f32 v11, v9, s14, 0.5
	v_fma_f32 v11, v9, v11, 1.0
	v_cmp_nlt_f32_e32 vcc, s51, v9
	v_mul_f32_e64 v11, v11, -v9
	v_sub_f32_e32 v247, 1.0, v247
	v_cndmask_b32_e32 v11, v11, v247, vcc
	v_fmamk_f32 v7, v7, 0xbfb8aa3b, v75
	v_exp_f32_e32 v7, v7
	s_nop 0
	v_add_f32_e32 v7, 1.0, v7
	v_rcp_f32_e32 v7, v7
	s_nop 0
	v_mul_f32_e32 v7, v71, v7
	v_add_f32_e32 v12, v7, v7
	v_cmp_nlt_f32_e32 vcc, s51, v12
	s_and_saveexec_b64 s[0:1], vcc
	s_xor_b64 s[0:1], exec, s[0:1]
	v_mul_f32_e32 v9, 0x3fb8aa3b, v12
	v_exp_f32_e32 v9, v9
	s_nop 0
	v_sub_f32_e32 v9, 1.0, v9
	s_andn2_saveexec_b64 s[0:1], s[0:1]
	s_cbranch_execz .LBB0_446
	v_fma_f32 v9, v12, s14, 0.5
	v_fma_f32 v9, v12, v9, 1.0
	v_mul_f32_e64 v9, v9, -v12
	s_branch .LBB0_446

.LBB0_1039:
	s_ashr_i32 s7, s6, 31
	s_lshl_b64 s[12:13], s[6:7], 19
	v_readlane_b32 s7, v253, 49
	s_add_u32 s58, s7, s12
	v_readlane_b32 s7, v253, 50
	s_addc_u32 s59, s7, s13
	s_and_b64 s[0:1], s[0:1], exec
	s_cselect_b32 s7, s59, s5
	s_cselect_b32 s12, s58, s4
	s_add_u32 s0, s8, 0x40080
	s_addc_u32 s1, s9, 0
	s_add_u32 s13, s4, 0x100
	v_mov_b32_e32 v0, 0
	s_addc_u32 s14, s5, 0
	s_mov_b32 s15, -2
	v_mov_b32_e32 v1, v0
	v_pk_mov_b32 v[2:3], v[0:1], v[0:1]
	v_pk_mov_b32 v[4:5], v[0:1], v[0:1]
	v_pk_mov_b32 v[6:7], v[0:1], v[0:1]
	v_pk_mov_b32 v[8:9], v[0:1], v[0:1]
	v_pk_mov_b32 v[10:11], v[0:1], v[0:1]
	v_pk_mov_b32 v[12:13], v[0:1], v[0:1]
	v_pk_mov_b32 v[14:15], v[0:1], v[0:1]
	v_pk_mov_b32 v[16:17], v[0:1], v[0:1]
	v_pk_mov_b32 v[18:19], v[0:1], v[0:1]
	v_pk_mov_b32 v[20:21], v[0:1], v[0:1]
	v_pk_mov_b32 v[22:23], v[0:1], v[0:1]
	v_pk_mov_b32 v[24:25], v[0:1], v[0:1]
	v_pk_mov_b32 v[26:27], v[0:1], v[0:1]
	v_pk_mov_b32 v[28:29], v[0:1], v[0:1]
	v_pk_mov_b32 v[30:31], v[0:1], v[0:1]
	v_pk_mov_b32 v[60:61], v[0:1], v[0:1]
	v_pk_mov_b32 v[62:63], v[0:1], v[0:1]
	v_pk_mov_b32 v[68:69], v[0:1], v[0:1]
	v_pk_mov_b32 v[70:71], v[0:1], v[0:1]
	v_pk_mov_b32 v[72:73], v[0:1], v[0:1]
	v_pk_mov_b32 v[74:75], v[0:1], v[0:1]
	v_pk_mov_b32 v[76:77], v[0:1], v[0:1]
	v_pk_mov_b32 v[78:79], v[0:1], v[0:1]
	v_pk_mov_b32 v[80:81], v[0:1], v[0:1]
	v_pk_mov_b32 v[82:83], v[0:1], v[0:1]
	v_pk_mov_b32 v[84:85], v[0:1], v[0:1]
	v_pk_mov_b32 v[86:87], v[0:1], v[0:1]
	v_pk_mov_b32 v[88:89], v[0:1], v[0:1]
	v_pk_mov_b32 v[90:91], v[0:1], v[0:1]
	v_pk_mov_b32 v[92:93], v[0:1], v[0:1]
	v_pk_mov_b32 v[94:95], v[0:1], v[0:1]
	v_pk_mov_b32 v[32:33], v[0:1], v[0:1]
	v_pk_mov_b32 v[34:35], v[0:1], v[0:1]
	v_pk_mov_b32 v[36:37], v[0:1], v[0:1]
	v_pk_mov_b32 v[38:39], v[0:1], v[0:1]
	v_pk_mov_b32 v[40:41], v[0:1], v[0:1]
	v_pk_mov_b32 v[42:43], v[0:1], v[0:1]
	v_pk_mov_b32 v[44:45], v[0:1], v[0:1]
	v_pk_mov_b32 v[46:47], v[0:1], v[0:1]
	v_pk_mov_b32 v[48:49], v[0:1], v[0:1]
	v_pk_mov_b32 v[50:51], v[0:1], v[0:1]
	v_pk_mov_b32 v[52:53], v[0:1], v[0:1]
	v_pk_mov_b32 v[54:55], v[0:1], v[0:1]
	v_pk_mov_b32 v[56:57], v[0:1], v[0:1]
	v_pk_mov_b32 v[58:59], v[0:1], v[0:1]
	v_pk_mov_b32 v[64:65], v[0:1], v[0:1]
	v_pk_mov_b32 v[66:67], v[0:1], v[0:1]
	v_pk_mov_b32 v[96:97], v[0:1], v[0:1]
	v_pk_mov_b32 v[98:99], v[0:1], v[0:1]
	v_pk_mov_b32 v[100:101], v[0:1], v[0:1]
	v_pk_mov_b32 v[102:103], v[0:1], v[0:1]
	v_pk_mov_b32 v[104:105], v[0:1], v[0:1]
	v_pk_mov_b32 v[106:107], v[0:1], v[0:1]
	v_pk_mov_b32 v[108:109], v[0:1], v[0:1]
	v_pk_mov_b32 v[110:111], v[0:1], v[0:1]
	v_pk_mov_b32 v[112:113], v[0:1], v[0:1]
	v_pk_mov_b32 v[114:115], v[0:1], v[0:1]
	v_pk_mov_b32 v[116:117], v[0:1], v[0:1]
	v_pk_mov_b32 v[118:119], v[0:1], v[0:1]
	v_pk_mov_b32 v[120:121], v[0:1], v[0:1]
	v_pk_mov_b32 v[122:123], v[0:1], v[0:1]
	v_pk_mov_b32 v[124:125], v[0:1], v[0:1]
	v_pk_mov_b32 v[126:127], v[0:1], v[0:1]
	.p2align 6
